# baseline (speedup 1.0000x reference)
; #define PG8_STAGE(bufoff, gbase, voff) do { _Pragma("unroll") for (int _i = 0; _i < 2; ++_i) \
;         __builtin_amdgcn_global_load_lds((const unsigned*)((const char*)(gbase) + (voff)[_i]), (PG8_LAS unsigned*)(lds + (bufoff) + ldsw + _i * 8192), 16, 0, 0); } while (0)
; #define PG8_LDA(dst, b, h) do { _Pragma("unroll") for (int m = 0; m < 4; ++m) _Pragma("unroll") for (int k = 0; k < 2; ++k) dst[m][k] = *(const PG8_LAS bf16x8*)(lds + PG8_SA(b, h) + aoff + m * 2048 + k * 1024); } while (0)
; #define PG8_LDB(dst, b, h) do { _Pragma("unroll") for (int n = 0; n < 2; ++n) _Pragma("unroll") for (int k = 0; k < 2; ++k) dst[n][k] = *(const PG8_LAS bf16x8*)(lds + PG8_SB(b, h) + boff + n * 2048 + k * 1024); } while (0)
; #define PG8_MMA(ai, bj, At, Bt) do { __builtin_amdgcn_s_setprio(1); _Pragma("unroll") for (int m = 0; m < 4; ++m) _Pragma("unroll") for (int n = 0; n < 2; ++n) _Pragma("unroll") for (int k = 0; k < 2; ++k) \
;         acc[ai][bj][m][n] = __builtin_amdgcn_mfma_f32_16x16x32_bf16(Bt[n][k], At[m][k], acc[ai][bj][m][n], 0, 0, 0); __builtin_amdgcn_s_setprio(0); } while (0)
; template <class Epi, class Sched, bool ALIGN_EPI = false, bool SP2 = false>
; __device__ __forceinline__ void gemm_phase(PG8_LAS unsigned char* lds, const Gemm g, const Sched& S, const Epi& E, int wave_s) {
;     ...
;         for (int t = 0; t < nt; t += 2) {
;             const bool last = (t == nt - 2);
;             const char* a1 = cA + (size_t)(t + 1) * kstep;
;             const char* a2 = last ? nA : cA + (size_t)(t + 2) * kstep; const char* b2 = last ? nB : cB + (size_t)(t + 2) * kstep;
;             const char* a3 = a2 + kstep; const char* b3 = b2 + kstep;
;             if (last && has_next) S.a_ready(nxt);
;             if constexpr (SP2) {
;             PG8_LDB(B0, 0, 0); PG8_LDB(B1, 0, 1); PG8_SCHED; PG8_LDA(At, 0, 0); PG8_STAGE(PG8_SA(1, 1), a1 + hstep, voffA);
;             PG8_WAIT_V(8); PG8_WAIT_L(0); PG8_BAR; PG8_MMA(0, 0, At, B0); PG8_MMA(0, 1, At, B1); PG8_BAR; PG8_SCHED;
;     ...
;         { float zf_ = 0.f; asm volatile("" : "+v"(zf_)); const f32x4 zero4_ = {zf_, zf_, zf_, zf_};
; #pragma unroll
;         for (int a = 0; a < 2; ++a)
; #pragma unroll
;             for (int b = 0; b < 2; ++b)
; #pragma unroll
;                 for (int m = 0; m < 4; ++m)
; #pragma unroll
;                     for (int n = 0; n < 2; ++n) acc[a][b][m][n] = zero4_; }
.LBB0_52:
	s_add_u32 s5, s62, 0x100
	v_mov_b64_e32 v[6:7], v[2:3]
	v_mov_b64_e32 v[18:19], v[2:3]
	v_mov_b64_e32 v[22:23], v[2:3]
	v_mov_b64_e32 v[34:35], v[2:3]
	v_mov_b64_e32 v[38:39], v[2:3]
	v_mov_b64_e32 v[50:51], v[2:3]
	v_mov_b64_e32 v[54:55], v[2:3]
	v_mov_b64_e32 v[10:11], v[2:3]
	v_mov_b64_e32 v[14:15], v[2:3]
	v_mov_b64_e32 v[26:27], v[2:3]
	v_mov_b64_e32 v[30:31], v[2:3]
	v_mov_b64_e32 v[42:43], v[2:3]
	v_mov_b64_e32 v[46:47], v[2:3]
	v_mov_b64_e32 v[58:59], v[2:3]
	v_mov_b64_e32 v[62:63], v[2:3]
	v_mov_b64_e32 v[66:67], v[2:3]
	v_mov_b64_e32 v[70:71], v[2:3]
	v_mov_b64_e32 v[82:83], v[2:3]
	v_mov_b64_e32 v[86:87], v[2:3]
	v_mov_b64_e32 v[98:99], v[2:3]
	v_mov_b64_e32 v[102:103], v[2:3]
	v_mov_b64_e32 v[114:115], v[2:3]
	v_mov_b64_e32 v[118:119], v[2:3]
	v_mov_b64_e32 v[74:75], v[2:3]
	v_mov_b64_e32 v[78:79], v[2:3]
	v_mov_b64_e32 v[90:91], v[2:3]
	v_mov_b64_e32 v[94:95], v[2:3]
	v_mov_b64_e32 v[106:107], v[2:3]
	v_mov_b64_e32 v[110:111], v[2:3]
	v_mov_b64_e32 v[122:123], v[2:3]
	v_mov_b64_e32 v[126:127], v[2:3]
	s_addc_u32 s22, s63, 0
	s_mov_b32 s23, -2
	v_mov_b64_e32 v[4:5], v[0:1]
	v_mov_b64_e32 v[16:17], v[0:1]
	v_mov_b64_e32 v[20:21], v[0:1]
	v_mov_b64_e32 v[32:33], v[0:1]
	v_mov_b64_e32 v[36:37], v[0:1]
	v_mov_b64_e32 v[48:49], v[0:1]
	v_mov_b64_e32 v[52:53], v[0:1]
	v_mov_b64_e32 v[8:9], v[0:1]
	v_mov_b64_e32 v[12:13], v[0:1]
	v_mov_b64_e32 v[24:25], v[0:1]
	v_mov_b64_e32 v[28:29], v[0:1]
	v_mov_b64_e32 v[40:41], v[0:1]
	v_mov_b64_e32 v[44:45], v[0:1]
	v_mov_b64_e32 v[56:57], v[0:1]
	v_mov_b64_e32 v[60:61], v[0:1]
	v_mov_b64_e32 v[64:65], v[0:1]
	v_mov_b64_e32 v[68:69], v[0:1]
	v_mov_b64_e32 v[80:81], v[0:1]
	v_mov_b64_e32 v[84:85], v[0:1]
	v_mov_b64_e32 v[96:97], v[0:1]
	v_mov_b64_e32 v[100:101], v[0:1]
	v_mov_b64_e32 v[112:113], v[0:1]
	v_mov_b64_e32 v[116:117], v[0:1]
	v_mov_b64_e32 v[72:73], v[0:1]
	v_mov_b64_e32 v[76:77], v[0:1]
	v_mov_b64_e32 v[88:89], v[0:1]
	v_mov_b64_e32 v[92:93], v[0:1]
	v_mov_b64_e32 v[104:105], v[0:1]
	v_mov_b64_e32 v[108:109], v[0:1]
	v_mov_b64_e32 v[120:121], v[0:1]
	v_mov_b64_e32 v[124:125], v[0:1]
	v_readlane_b32 vcc_lo, v253, 14
	s_nop 3
	s_cmp_eq_u32 vcc_lo, 0
	s_cbranch_scc1 .Lgprio_0
	s_setprio 1
.Lgprio_0:
.LBB0_53:
	s_add_u32 s62, s60, 0x100
	s_addc_u32 s63, s61, 0
	s_add_i32 s3, 0, 0x10000
	s_cmpk_eq_i32 s23, 0x54
	s_cselect_b32 s67, s45, s63
	s_cselect_b32 s66, s44, s62
	v_add_u32_e32 v146, s3, v143
	s_cselect_b32 s65, s59, s22
	s_cselect_b32 s64, s58, s5
	s_add_i32 s26, 0, 0x14000
	ds_read_b128 v[134:137], v146
	ds_read_b128 v[138:141], v146 offset:1024
	ds_read_b128 v[150:153], v146 offset:2048
	ds_read_b128 v[156:159], v146 offset:3072
	v_add_u32_e32 v146, s26, v143
	ds_read_b128 v[160:163], v146
	ds_read_b128 v[164:167], v146 offset:1024
	ds_read_b128 v[168:171], v146 offset:2048
	ds_read_b128 v[172:175], v146 offset:3072
	v_lshl_add_u64 v[146:147], s[60:61], 0, v[130:131]
	s_add_i32 m0, s25, 0xc000
	ds_read_b128 v[176:179], v145
	ds_read_b128 v[180:183], v145 offset:1024
	ds_read_b128 v[184:187], v145 offset:2048
	ds_read_b128 v[188:191], v145 offset:3072
	ds_read_b128 v[206:209], v145 offset:4096
	ds_read_b128 v[210:213], v145 offset:5120
	ds_read_b128 v[214:217], v145 offset:6144
	ds_read_b128 v[218:221], v145 offset:7168
	global_load_lds_dwordx4 v[146:147], off
	v_lshl_add_u64 v[146:147], s[60:61], 0, v[132:133]
	s_add_i32 m0, s25, 0xe000
	s_nop 0
	global_load_lds_dwordx4 v[146:147], off
	s_waitcnt vmcnt(8)
	s_waitcnt lgkmcnt(0)
	s_barrier
	s_waitcnt lgkmcnt(0)
	v_mfma_f32_16x16x32_bf16 v[124:127], v[134:137], v[176:179], v[124:127]
	v_mfma_f32_16x16x32_bf16 v[120:123], v[150:153], v[176:179], v[120:123]
	v_mfma_f32_16x16x32_bf16 v[108:111], v[134:137], v[184:187], v[108:111]
	v_mfma_f32_16x16x32_bf16 v[104:107], v[150:153], v[184:187], v[104:107]
	v_mfma_f32_16x16x32_bf16 v[92:95], v[134:137], v[206:209], v[92:95]
	v_mfma_f32_16x16x32_bf16 v[88:91], v[150:153], v[206:209], v[88:91]
	v_mfma_f32_16x16x32_bf16 v[76:79], v[134:137], v[214:217], v[76:79]
	v_mfma_f32_16x16x32_bf16 v[72:75], v[150:153], v[214:217], v[72:75]
	v_mfma_f32_16x16x32_bf16 v[124:127], v[138:141], v[180:183], v[124:127]
	v_mfma_f32_16x16x32_bf16 v[120:123], v[156:159], v[180:183], v[120:123]
	v_mfma_f32_16x16x32_bf16 v[108:111], v[138:141], v[188:191], v[108:111]
	v_mfma_f32_16x16x32_bf16 v[104:107], v[156:159], v[188:191], v[104:107]
	v_mfma_f32_16x16x32_bf16 v[92:95], v[138:141], v[210:213], v[92:95]
	v_mfma_f32_16x16x32_bf16 v[88:91], v[156:159], v[210:213], v[88:91]
	v_mfma_f32_16x16x32_bf16 v[76:79], v[138:141], v[218:221], v[76:79]
	v_mfma_f32_16x16x32_bf16 v[72:75], v[156:159], v[218:221], v[72:75]
	v_mfma_f32_16x16x32_bf16 v[116:119], v[160:163], v[176:179], v[116:119]
	v_mfma_f32_16x16x32_bf16 v[112:115], v[168:171], v[176:179], v[112:115]
	v_mfma_f32_16x16x32_bf16 v[100:103], v[160:163], v[184:187], v[100:103]
	v_mfma_f32_16x16x32_bf16 v[96:99], v[168:171], v[184:187], v[96:99]
	v_mfma_f32_16x16x32_bf16 v[84:87], v[160:163], v[206:209], v[84:87]
	v_mfma_f32_16x16x32_bf16 v[80:83], v[168:171], v[206:209], v[80:83]
	v_mfma_f32_16x16x32_bf16 v[68:71], v[160:163], v[214:217], v[68:71]
	v_mfma_f32_16x16x32_bf16 v[64:67], v[168:171], v[214:217], v[64:67]
	v_mfma_f32_16x16x32_bf16 v[116:119], v[164:167], v[180:183], v[116:119]
	v_mfma_f32_16x16x32_bf16 v[112:115], v[172:175], v[180:183], v[112:115]
	v_mfma_f32_16x16x32_bf16 v[100:103], v[164:167], v[188:191], v[100:103]
	v_mfma_f32_16x16x32_bf16 v[96:99], v[172:175], v[188:191], v[96:99]
	v_mfma_f32_16x16x32_bf16 v[84:87], v[164:167], v[210:213], v[84:87]
	v_mfma_f32_16x16x32_bf16 v[80:83], v[172:175], v[210:213], v[80:83]
	v_mfma_f32_16x16x32_bf16 v[68:71], v[164:167], v[218:221], v[68:71]
	v_mfma_f32_16x16x32_bf16 v[64:67], v[172:175], v[218:221], v[64:67]
	s_barrier
; #define PG8_STAGE(bufoff, gbase, voff) do { _Pragma("unroll") for (int _i = 0; _i < 2; ++_i) \
;         __builtin_amdgcn_global_load_lds((const unsigned*)((const char*)(gbase) + (voff)[_i]), (PG8_LAS unsigned*)(lds + (bufoff) + ldsw + _i * 8192), 16, 0, 0); } while (0)
; #define PG8_LDA(dst, b, h) do { _Pragma("unroll") for (int m = 0; m < 4; ++m) _Pragma("unroll") for (int k = 0; k < 2; ++k) dst[m][k] = *(const PG8_LAS bf16x8*)(lds + PG8_SA(b, h) + aoff + m * 2048 + k * 1024); } while (0)
; #define PG8_LDB(dst, b, h) do { _Pragma("unroll") for (int n = 0; n < 2; ++n) _Pragma("unroll") for (int k = 0; k < 2; ++k) dst[n][k] = *(const PG8_LAS bf16x8*)(lds + PG8_SB(b, h) + boff + n * 2048 + k * 1024); } while (0)
; #define PG8_MMA(ai, bj, At, Bt) do { __builtin_amdgcn_s_setprio(1); _Pragma("unroll") for (int m = 0; m < 4; ++m) _Pragma("unroll") for (int n = 0; n < 2; ++n) _Pragma("unroll") for (int k = 0; k < 2; ++k) \
;         acc[ai][bj][m][n] = __builtin_amdgcn_mfma_f32_16x16x32_bf16(Bt[n][k], At[m][k], acc[ai][bj][m][n], 0, 0, 0); __builtin_amdgcn_s_setprio(0); } while (0)
; #define PG8_WAIT_V(n) asm volatile("s_waitcnt vmcnt(" #n ")" ::: "memory")
; #define PG8_WAIT_L(n) asm volatile("s_waitcnt lgkmcnt(" #n ")" ::: "memory")
; #define PG8_BAR __builtin_amdgcn_s_barrier()
; #define PG8_SCHED __builtin_amdgcn_sched_barrier(0)
; template <class Epi, class Sched, bool ALIGN_EPI = false, bool SP2 = false>
; __device__ __forceinline__ void gemm_phase(PG8_LAS unsigned char* lds, const Gemm g, const Sched& S, const Epi& E, int wave_s) {
;     ...
;             PG8_LDA(At, 0, 1); PG8_STAGE(PG8_SB(0, 0), b2, voffB); PG8_STAGE(PG8_SB(0, 1), b2 + hstep, voffB); PG8_STAGE(PG8_SA(0, 0), a2, voffA);
;             PG8_WAIT_V(8); PG8_WAIT_L(0); PG8_BAR; PG8_MMA(1, 0, At, B0); PG8_MMA(1, 1, At, B1); PG8_BAR; PG8_SCHED;
;             PG8_LDB(B0, 1, 0); PG8_LDB(B1, 1, 1); PG8_SCHED; PG8_LDA(At, 1, 0); PG8_STAGE(PG8_SA(0, 1), a2 + hstep, voffA);
;             PG8_WAIT_V(8); PG8_WAIT_L(0); PG8_BAR; PG8_MMA(0, 0, At, B0); PG8_MMA(0, 1, At, B1); PG8_BAR; PG8_SCHED;
	s_add_i32 s3, s3, s9
	v_lshl_add_u64 v[146:147], s[64:65], 0, v[148:149]
	s_mov_b32 m0, s3
	ds_read_b128 v[176:179], v145 offset:16384
	ds_read_b128 v[180:183], v145 offset:17408
	ds_read_b128 v[184:187], v145 offset:18432
	ds_read_b128 v[188:191], v145 offset:19456
	ds_read_b128 v[206:209], v145 offset:20480
	ds_read_b128 v[210:213], v145 offset:21504
	ds_read_b128 v[214:217], v145 offset:22528
	ds_read_b128 v[218:221], v145 offset:23552
	global_load_lds_dwordx4 v[146:147], off
	s_add_i32 m0, s3, 0x2000
	s_add_u32 s28, s64, 0x160000
	v_lshl_add_u64 v[222:223], s[64:65], 0, v[128:129]
	s_addc_u32 s29, s65, 0
	s_add_i32 s3, s26, s9
	global_load_lds_dwordx4 v[222:223], off
	v_lshl_add_u64 v[224:225], s[28:29], 0, v[148:149]
	s_mov_b32 m0, s3
	v_lshl_add_u64 v[226:227], s[66:67], 0, v[128:129]
	global_load_lds_dwordx4 v[224:225], off
	v_lshl_add_u64 v[224:225], s[28:29], 0, v[128:129]
	s_add_i32 m0, s3, 0x2000
	s_nop 0
	global_load_lds_dwordx4 v[224:225], off
	v_lshl_add_u64 v[224:225], s[66:67], 0, v[148:149]
	s_mov_b32 m0, s25
	s_nop 0
	global_load_lds_dwordx4 v[224:225], off
	s_mov_b32 m0, s73
	s_nop 0
	global_load_lds_dwordx4 v[226:227], off
	s_waitcnt vmcnt(8)
	s_waitcnt lgkmcnt(0)
	s_barrier
	s_waitcnt lgkmcnt(0)
	v_mfma_f32_16x16x32_bf16 v[60:63], v[134:137], v[176:179], v[60:63]
	v_mfma_f32_16x16x32_bf16 v[56:59], v[150:153], v[176:179], v[56:59]
	v_mfma_f32_16x16x32_bf16 v[44:47], v[134:137], v[184:187], v[44:47]
	v_mfma_f32_16x16x32_bf16 v[40:43], v[150:153], v[184:187], v[40:43]
	v_mfma_f32_16x16x32_bf16 v[28:31], v[134:137], v[206:209], v[28:31]
	v_mfma_f32_16x16x32_bf16 v[24:27], v[150:153], v[206:209], v[24:27]
	v_mfma_f32_16x16x32_bf16 v[12:15], v[134:137], v[214:217], v[12:15]
	v_mfma_f32_16x16x32_bf16 v[8:11], v[150:153], v[214:217], v[8:11]
	v_mfma_f32_16x16x32_bf16 v[60:63], v[138:141], v[180:183], v[60:63]
	v_mfma_f32_16x16x32_bf16 v[56:59], v[156:159], v[180:183], v[56:59]
	v_mfma_f32_16x16x32_bf16 v[44:47], v[138:141], v[188:191], v[44:47]
	v_mfma_f32_16x16x32_bf16 v[40:43], v[156:159], v[188:191], v[40:43]
	v_mfma_f32_16x16x32_bf16 v[28:31], v[138:141], v[210:213], v[28:31]
	v_mfma_f32_16x16x32_bf16 v[24:27], v[156:159], v[210:213], v[24:27]
	v_mfma_f32_16x16x32_bf16 v[12:15], v[138:141], v[218:221], v[12:15]
	v_mfma_f32_16x16x32_bf16 v[8:11], v[156:159], v[218:221], v[8:11]
	v_mfma_f32_16x16x32_bf16 v[52:55], v[160:163], v[176:179], v[52:55]
	v_mfma_f32_16x16x32_bf16 v[48:51], v[168:171], v[176:179], v[48:51]
	v_mfma_f32_16x16x32_bf16 v[36:39], v[160:163], v[184:187], v[36:39]
	v_mfma_f32_16x16x32_bf16 v[32:35], v[168:171], v[184:187], v[32:35]
	v_mfma_f32_16x16x32_bf16 v[20:23], v[160:163], v[206:209], v[20:23]
	v_mfma_f32_16x16x32_bf16 v[16:19], v[168:171], v[206:209], v[16:19]
	v_mfma_f32_16x16x32_bf16 v[4:7], v[160:163], v[214:217], v[4:7]
	v_mfma_f32_16x16x32_bf16 v[0:3], v[168:171], v[214:217], v[0:3]
	v_mfma_f32_16x16x32_bf16 v[52:55], v[164:167], v[180:183], v[52:55]
	v_mfma_f32_16x16x32_bf16 v[48:51], v[172:175], v[180:183], v[48:51]
	v_mfma_f32_16x16x32_bf16 v[36:39], v[164:167], v[188:191], v[36:39]
	v_mfma_f32_16x16x32_bf16 v[32:35], v[172:175], v[188:191], v[32:35]
	v_mfma_f32_16x16x32_bf16 v[20:23], v[164:167], v[210:213], v[20:23]
	v_mfma_f32_16x16x32_bf16 v[16:19], v[172:175], v[210:213], v[16:19]
	v_mfma_f32_16x16x32_bf16 v[4:7], v[164:167], v[218:221], v[4:7]
	v_mfma_f32_16x16x32_bf16 v[0:3], v[172:175], v[218:221], v[0:3]
	s_barrier
	s_add_i32 s3, 0, 0x18000
	s_add_i32 s26, 0, 0x1c000
	v_add_u32_e32 v156, s3, v143
	v_add_u32_e32 v172, s26, v143
	ds_read_b128 v[134:137], v156
	ds_read_b128 v[138:141], v156 offset:1024
	ds_read_b128 v[150:153], v156 offset:2048
	ds_read_b128 v[156:159], v156 offset:3072
	ds_read_b128 v[160:163], v172
	ds_read_b128 v[164:167], v172 offset:1024
	ds_read_b128 v[168:171], v172 offset:2048
	ds_read_b128 v[172:175], v172 offset:3072
	s_add_u32 s28, s66, 0x160000
	s_addc_u32 s29, s67, 0
	s_mov_b32 m0, s74
	v_lshl_add_u64 v[228:229], s[28:29], 0, v[148:149]
	ds_read_b128 v[176:179], v145 offset:32768
	ds_read_b128 v[180:183], v145 offset:33792
	ds_read_b128 v[184:187], v145 offset:34816
	ds_read_b128 v[188:191], v145 offset:35840
	ds_read_b128 v[206:209], v145 offset:36864
	ds_read_b128 v[210:213], v145 offset:37888
	ds_read_b128 v[214:217], v145 offset:38912
	ds_read_b128 v[218:221], v145 offset:39936
	global_load_lds_dwordx4 v[228:229], off
	v_lshl_add_u64 v[228:229], s[28:29], 0, v[128:129]
	s_mov_b32 m0, s75
	s_nop 0
	global_load_lds_dwordx4 v[228:229], off
	s_waitcnt vmcnt(8)
	s_waitcnt lgkmcnt(0)
	s_barrier
; #define PG8_STAGE(bufoff, gbase, voff) do { _Pragma("unroll") for (int _i = 0; _i < 2; ++_i) \
;         __builtin_amdgcn_global_load_lds((const unsigned*)((const char*)(gbase) + (voff)[_i]), (PG8_LAS unsigned*)(lds + (bufoff) + ldsw + _i * 8192), 16, 0, 0); } while (0)
; #define PG8_LDA(dst, b, h) do { _Pragma("unroll") for (int m = 0; m < 4; ++m) _Pragma("unroll") for (int k = 0; k < 2; ++k) dst[m][k] = *(const PG8_LAS bf16x8*)(lds + PG8_SA(b, h) + aoff + m * 2048 + k * 1024); } while (0)
; #define PG8_MMA(ai, bj, At, Bt) do { __builtin_amdgcn_s_setprio(1); _Pragma("unroll") for (int m = 0; m < 4; ++m) _Pragma("unroll") for (int n = 0; n < 2; ++n) _Pragma("unroll") for (int k = 0; k < 2; ++k) \
;         acc[ai][bj][m][n] = __builtin_amdgcn_mfma_f32_16x16x32_bf16(Bt[n][k], At[m][k], acc[ai][bj][m][n], 0, 0, 0); __builtin_amdgcn_s_setprio(0); } while (0)
; #define PG8_WAIT_V(n) asm volatile("s_waitcnt vmcnt(" #n ")" ::: "memory")
; #define PG8_WAIT_L(n) asm volatile("s_waitcnt lgkmcnt(" #n ")" ::: "memory")
; #define PG8_BAR __builtin_amdgcn_s_barrier()
; #define PG8_SCHED __builtin_amdgcn_sched_barrier(0)
; template <class Epi, class Sched, bool ALIGN_EPI = false, bool SP2 = false>
; __device__ __forceinline__ void gemm_phase(PG8_LAS unsigned char* lds, const Gemm g, const Sched& S, const Epi& E, int wave_s) {
;     ...
;         for (int t = 0; t < nt; t += 2) {
;             const bool last = (t == nt - 2);
;     ...
;             PG8_WAIT_V(8); PG8_WAIT_L(0); PG8_BAR; PG8_MMA(0, 0, At, B0); PG8_MMA(0, 1, At, B1); PG8_BAR; PG8_SCHED;
;             PG8_LDA(At, 1, 1); PG8_STAGE(PG8_SB(1, 0), b3, voffB); PG8_STAGE(PG8_SB(1, 1), b3 + hstep, voffB); PG8_STAGE(PG8_SA(1, 0), a3, voffA);
;             PG8_WAIT_V(8); PG8_WAIT_L(0); PG8_BAR; PG8_MMA(1, 0, At, B0); PG8_MMA(1, 1, At, B1); PG8_BAR; PG8_SCHED;
	s_waitcnt lgkmcnt(0)
	v_mfma_f32_16x16x32_bf16 v[124:127], v[134:137], v[176:179], v[124:127]
	v_mfma_f32_16x16x32_bf16 v[120:123], v[150:153], v[176:179], v[120:123]
	v_mfma_f32_16x16x32_bf16 v[108:111], v[134:137], v[184:187], v[108:111]
	v_mfma_f32_16x16x32_bf16 v[104:107], v[150:153], v[184:187], v[104:107]
	v_mfma_f32_16x16x32_bf16 v[92:95], v[134:137], v[206:209], v[92:95]
	v_mfma_f32_16x16x32_bf16 v[88:91], v[150:153], v[206:209], v[88:91]
	v_mfma_f32_16x16x32_bf16 v[76:79], v[134:137], v[214:217], v[76:79]
	v_mfma_f32_16x16x32_bf16 v[72:75], v[150:153], v[214:217], v[72:75]
	v_mfma_f32_16x16x32_bf16 v[124:127], v[138:141], v[180:183], v[124:127]
	v_mfma_f32_16x16x32_bf16 v[120:123], v[156:159], v[180:183], v[120:123]
	v_mfma_f32_16x16x32_bf16 v[108:111], v[138:141], v[188:191], v[108:111]
	v_mfma_f32_16x16x32_bf16 v[104:107], v[156:159], v[188:191], v[104:107]
	v_mfma_f32_16x16x32_bf16 v[92:95], v[138:141], v[210:213], v[92:95]
	v_mfma_f32_16x16x32_bf16 v[88:91], v[156:159], v[210:213], v[88:91]
	v_mfma_f32_16x16x32_bf16 v[76:79], v[138:141], v[218:221], v[76:79]
	v_mfma_f32_16x16x32_bf16 v[72:75], v[156:159], v[218:221], v[72:75]
	v_mfma_f32_16x16x32_bf16 v[116:119], v[160:163], v[176:179], v[116:119]
	v_mfma_f32_16x16x32_bf16 v[112:115], v[168:171], v[176:179], v[112:115]
	v_mfma_f32_16x16x32_bf16 v[100:103], v[160:163], v[184:187], v[100:103]
	v_mfma_f32_16x16x32_bf16 v[96:99], v[168:171], v[184:187], v[96:99]
	v_mfma_f32_16x16x32_bf16 v[84:87], v[160:163], v[206:209], v[84:87]
	v_mfma_f32_16x16x32_bf16 v[80:83], v[168:171], v[206:209], v[80:83]
	v_mfma_f32_16x16x32_bf16 v[68:71], v[160:163], v[214:217], v[68:71]
	v_mfma_f32_16x16x32_bf16 v[64:67], v[168:171], v[214:217], v[64:67]
	v_mfma_f32_16x16x32_bf16 v[116:119], v[164:167], v[180:183], v[116:119]
	v_mfma_f32_16x16x32_bf16 v[112:115], v[172:175], v[180:183], v[112:115]
	v_mfma_f32_16x16x32_bf16 v[100:103], v[164:167], v[188:191], v[100:103]
	v_mfma_f32_16x16x32_bf16 v[96:99], v[172:175], v[188:191], v[96:99]
	v_mfma_f32_16x16x32_bf16 v[84:87], v[164:167], v[210:213], v[84:87]
	v_mfma_f32_16x16x32_bf16 v[80:83], v[172:175], v[210:213], v[80:83]
	v_mfma_f32_16x16x32_bf16 v[68:71], v[164:167], v[218:221], v[68:71]
	v_mfma_f32_16x16x32_bf16 v[64:67], v[172:175], v[218:221], v[64:67]
	s_barrier
	s_add_i32 s3, s3, s9
	v_lshl_add_u64 v[146:147], v[146:147], 0, s[34:35]
	s_mov_b32 m0, s3
	ds_read_b128 v[176:179], v145 offset:49152
	ds_read_b128 v[180:183], v145 offset:50176
	ds_read_b128 v[184:187], v145 offset:51200
	ds_read_b128 v[188:191], v145 offset:52224
	ds_read_b128 v[206:209], v145 offset:53248
	ds_read_b128 v[210:213], v145 offset:54272
	ds_read_b128 v[214:217], v145 offset:55296
	ds_read_b128 v[218:221], v145 offset:56320
	global_load_lds_dwordx4 v[146:147], off
	s_add_i32 m0, s3, 0x2000
	s_add_u32 s28, s64, 0x160080
	v_lshl_add_u64 v[146:147], v[222:223], 0, s[34:35]
	s_addc_u32 s29, s65, 0
	s_add_i32 s3, s26, s9
	global_load_lds_dwordx4 v[146:147], off
	v_lshl_add_u64 v[146:147], s[28:29], 0, v[148:149]
	s_mov_b32 m0, s3
	s_nop 0
	global_load_lds_dwordx4 v[146:147], off
	v_lshl_add_u64 v[146:147], s[28:29], 0, v[128:129]
	s_add_i32 m0, s3, 0x2000
	s_nop 0
	global_load_lds_dwordx4 v[146:147], off
	v_lshl_add_u64 v[146:147], v[224:225], 0, s[34:35]
	s_mov_b32 m0, s79
	s_nop 0
	global_load_lds_dwordx4 v[146:147], off
	v_lshl_add_u64 v[146:147], v[226:227], 0, s[34:35]
	s_mov_b32 m0, s20
	s_nop 0
	global_load_lds_dwordx4 v[146:147], off
	s_waitcnt vmcnt(8)
	s_waitcnt lgkmcnt(0)
	s_barrier
	s_waitcnt lgkmcnt(0)
	v_mfma_f32_16x16x32_bf16 v[60:63], v[134:137], v[176:179], v[60:63]
	v_mfma_f32_16x16x32_bf16 v[56:59], v[150:153], v[176:179], v[56:59]
	v_mfma_f32_16x16x32_bf16 v[44:47], v[134:137], v[184:187], v[44:47]
	v_mfma_f32_16x16x32_bf16 v[40:43], v[150:153], v[184:187], v[40:43]
	v_mfma_f32_16x16x32_bf16 v[28:31], v[134:137], v[206:209], v[28:31]
	v_mfma_f32_16x16x32_bf16 v[24:27], v[150:153], v[206:209], v[24:27]
	v_mfma_f32_16x16x32_bf16 v[12:15], v[134:137], v[214:217], v[12:15]
	v_mfma_f32_16x16x32_bf16 v[8:11], v[150:153], v[214:217], v[8:11]
	v_mfma_f32_16x16x32_bf16 v[60:63], v[138:141], v[180:183], v[60:63]
	v_mfma_f32_16x16x32_bf16 v[56:59], v[156:159], v[180:183], v[56:59]
	v_mfma_f32_16x16x32_bf16 v[44:47], v[138:141], v[188:191], v[44:47]
	v_mfma_f32_16x16x32_bf16 v[40:43], v[156:159], v[188:191], v[40:43]
	v_mfma_f32_16x16x32_bf16 v[28:31], v[138:141], v[210:213], v[28:31]
	v_mfma_f32_16x16x32_bf16 v[24:27], v[156:159], v[210:213], v[24:27]
	v_mfma_f32_16x16x32_bf16 v[12:15], v[138:141], v[218:221], v[12:15]
	v_mfma_f32_16x16x32_bf16 v[8:11], v[156:159], v[218:221], v[8:11]
	v_mfma_f32_16x16x32_bf16 v[52:55], v[160:163], v[176:179], v[52:55]
	v_mfma_f32_16x16x32_bf16 v[48:51], v[168:171], v[176:179], v[48:51]
	v_mfma_f32_16x16x32_bf16 v[36:39], v[160:163], v[184:187], v[36:39]
	v_mfma_f32_16x16x32_bf16 v[32:35], v[168:171], v[184:187], v[32:35]
	v_mfma_f32_16x16x32_bf16 v[20:23], v[160:163], v[206:209], v[20:23]
	v_mfma_f32_16x16x32_bf16 v[16:19], v[168:171], v[206:209], v[16:19]
	v_mfma_f32_16x16x32_bf16 v[4:7], v[160:163], v[214:217], v[4:7]
	v_mfma_f32_16x16x32_bf16 v[0:3], v[168:171], v[214:217], v[0:3]
	v_mfma_f32_16x16x32_bf16 v[52:55], v[164:167], v[180:183], v[52:55]
	v_mfma_f32_16x16x32_bf16 v[48:51], v[172:175], v[180:183], v[48:51]
	v_mfma_f32_16x16x32_bf16 v[36:39], v[164:167], v[188:191], v[36:39]
	v_mfma_f32_16x16x32_bf16 v[32:35], v[172:175], v[188:191], v[32:35]
	v_mfma_f32_16x16x32_bf16 v[20:23], v[164:167], v[210:213], v[20:23]
	v_mfma_f32_16x16x32_bf16 v[16:19], v[172:175], v[210:213], v[16:19]
	v_mfma_f32_16x16x32_bf16 v[4:7], v[164:167], v[218:221], v[4:7]
	v_mfma_f32_16x16x32_bf16 v[0:3], v[172:175], v[218:221], v[0:3]
	s_barrier
	s_add_i32 s23, s23, 2
	s_add_u32 s5, s5, 0x100
	s_addc_u32 s22, s22, 0
	s_cmpk_gt_u32 s23, 0x55
	s_mov_b64 s[60:61], s[62:63]
	s_cbranch_scc0 .LBB0_53
	s_setprio 0
	s_and_b64 vcc, exec, s[56:57]
	s_cbranch_vccz .LBB0_56
	s_barrier

; #define PG8_STAGE(bufoff, gbase, voff) do { _Pragma("unroll") for (int _i = 0; _i < 2; ++_i) \
;         __builtin_amdgcn_global_load_lds((const unsigned*)((const char*)(gbase) + (voff)[_i]), (PG8_LAS unsigned*)(lds + (bufoff) + ldsw + _i * 8192), 16, 0, 0); } while (0)
; #define PG8_LDA(dst, b, h) do { _Pragma("unroll") for (int m = 0; m < 4; ++m) _Pragma("unroll") for (int k = 0; k < 2; ++k) dst[m][k] = *(const PG8_LAS bf16x8*)(lds + PG8_SA(b, h) + aoff + m * 2048 + k * 1024); } while (0)
; #define PG8_LDB(dst, b, h) do { _Pragma("unroll") for (int n = 0; n < 2; ++n) _Pragma("unroll") for (int k = 0; k < 2; ++k) dst[n][k] = *(const PG8_LAS bf16x8*)(lds + PG8_SB(b, h) + boff + n * 2048 + k * 1024); } while (0)
; #define PG8_WAIT_V(n) asm volatile("s_waitcnt vmcnt(" #n ")" ::: "memory")
; #define PG8_WAIT_L(n) asm volatile("s_waitcnt lgkmcnt(" #n ")" ::: "memory")
; template <class Epi, class Sched, bool ALIGN_EPI = false, bool SP2 = false>
; __device__ __forceinline__ void gemm_phase(PG8_LAS unsigned char* lds, const Gemm g, const Sched& S, const Epi& E, int wave_s) {
;     ...
;         const bool has_next = S.next(ui + 1, nxt);
;         const char* nA = has_next ? (const char*)g.A + (size_t)nxt.pm * tstep : cA; const char* nB = has_next ? (const char*)g.Bt + (size_t)nxt.pn * tstep : cB;
;     ...
;             const bool last = (t == nt - 2);
;             const char* a1 = cA + (size_t)(t + 1) * kstep;
;             const char* a2 = last ? nA : cA + (size_t)(t + 2) * kstep; const char* b2 = last ? nB : cB + (size_t)(t + 2) * kstep;
;             const char* a3 = a2 + kstep; const char* b3 = b2 + kstep;
;             if (last && has_next) S.a_ready(nxt);
;             if constexpr (SP2) {
;             PG8_LDB(B0, 0, 0); PG8_LDB(B1, 0, 1); PG8_SCHED; PG8_LDA(At, 0, 0); PG8_STAGE(PG8_SA(1, 1), a1 + hstep, voffA);
;             PG8_WAIT_V(8); PG8_WAIT_L(0); PG8_BAR; PG8_MMA(0, 0, At, B0); PG8_MMA(0, 1, At, B1); PG8_BAR; PG8_SCHED;
;     ...
;         { float zf_ = 0.f; asm volatile("" : "+v"(zf_)); const f32x4 zero4_ = {zf_, zf_, zf_, zf_};
; #pragma unroll
;         for (int a = 0; a < 2; ++a)
; #pragma unroll
;             for (int b = 0; b < 2; ++b)
; #pragma unroll
;                 for (int m = 0; m < 4; ++m)
; #pragma unroll
;                     for (int n = 0; n < 2; ++n) acc[a][b][m][n] = zero4_; }
;         cur = nxt; cA = nA; cB = nB; ++ui;
.LBB0_81:
	s_ashr_i32 s55, s54, 31
	s_lshl_b64 s[22:23], s[54:55], 20
	s_add_u32 s56, s9, s22
	s_addc_u32 s57, s11, s23
	s_and_b64 s[22:23], s[40:41], exec
	s_cselect_b32 s19, s57, s63
	s_cselect_b32 s22, s56, s62
	s_ashr_i32 s53, s52, 31
	s_lshl_b64 s[28:29], s[52:53], 20
	s_add_u32 s58, s20, s28
	s_addc_u32 s59, s21, s29
	s_and_b64 s[28:29], s[40:41], exec
	s_cselect_b32 s5, s59, s65
	s_cselect_b32 s23, s58, s64
	s_add_u32 s62, s62, 0x80080
	s_addc_u32 s63, s63, 0
	s_add_u32 s28, s64, 0x100
	v_mov_b64_e32 v[10:11], v[2:3]
	v_mov_b64_e32 v[18:19], v[2:3]
	v_mov_b64_e32 v[26:27], v[2:3]
	v_mov_b64_e32 v[34:35], v[2:3]
	v_mov_b64_e32 v[42:43], v[2:3]
	v_mov_b64_e32 v[50:51], v[2:3]
	v_mov_b64_e32 v[58:59], v[2:3]
	v_mov_b64_e32 v[6:7], v[2:3]
	v_mov_b64_e32 v[14:15], v[2:3]
	v_mov_b64_e32 v[22:23], v[2:3]
	v_mov_b64_e32 v[30:31], v[2:3]
	v_mov_b64_e32 v[38:39], v[2:3]
	v_mov_b64_e32 v[46:47], v[2:3]
	v_mov_b64_e32 v[54:55], v[2:3]
	v_mov_b64_e32 v[62:63], v[2:3]
	v_mov_b64_e32 v[66:67], v[2:3]
	v_mov_b64_e32 v[74:75], v[2:3]
	v_mov_b64_e32 v[82:83], v[2:3]
	v_mov_b64_e32 v[90:91], v[2:3]
	v_mov_b64_e32 v[98:99], v[2:3]
	v_mov_b64_e32 v[106:107], v[2:3]
	v_mov_b64_e32 v[114:115], v[2:3]
	v_mov_b64_e32 v[122:123], v[2:3]
	v_mov_b64_e32 v[70:71], v[2:3]
	v_mov_b64_e32 v[78:79], v[2:3]
	v_mov_b64_e32 v[86:87], v[2:3]
	v_mov_b64_e32 v[94:95], v[2:3]
	v_mov_b64_e32 v[102:103], v[2:3]
	v_mov_b64_e32 v[110:111], v[2:3]
	v_mov_b64_e32 v[118:119], v[2:3]
	v_mov_b64_e32 v[126:127], v[2:3]
	s_addc_u32 s29, s65, 0
	s_mov_b32 s38, -2
	v_mov_b64_e32 v[8:9], v[0:1]
	v_mov_b64_e32 v[16:17], v[0:1]
	v_mov_b64_e32 v[24:25], v[0:1]
	v_mov_b64_e32 v[32:33], v[0:1]
	v_mov_b64_e32 v[40:41], v[0:1]
	v_mov_b64_e32 v[48:49], v[0:1]
	v_mov_b64_e32 v[56:57], v[0:1]
	v_mov_b64_e32 v[4:5], v[0:1]
	v_mov_b64_e32 v[12:13], v[0:1]
	v_mov_b64_e32 v[20:21], v[0:1]
	v_mov_b64_e32 v[28:29], v[0:1]
	v_mov_b64_e32 v[36:37], v[0:1]
	v_mov_b64_e32 v[44:45], v[0:1]
	v_mov_b64_e32 v[52:53], v[0:1]
	v_mov_b64_e32 v[60:61], v[0:1]
	v_mov_b64_e32 v[64:65], v[0:1]
	v_mov_b64_e32 v[72:73], v[0:1]
	v_mov_b64_e32 v[80:81], v[0:1]
	v_mov_b64_e32 v[88:89], v[0:1]
	v_mov_b64_e32 v[96:97], v[0:1]
	v_mov_b64_e32 v[104:105], v[0:1]
	v_mov_b64_e32 v[112:113], v[0:1]
	v_mov_b64_e32 v[120:121], v[0:1]
	v_mov_b64_e32 v[68:69], v[0:1]
	v_mov_b64_e32 v[76:77], v[0:1]
	v_mov_b64_e32 v[84:85], v[0:1]
	v_mov_b64_e32 v[92:93], v[0:1]
	v_mov_b64_e32 v[100:101], v[0:1]
	v_mov_b64_e32 v[108:109], v[0:1]
	v_mov_b64_e32 v[116:117], v[0:1]
	v_mov_b64_e32 v[124:125], v[0:1]
	v_readlane_b32 vcc_lo, v253, 14
	s_nop 3
	s_cmp_eq_u32 vcc_lo, 0
	s_cbranch_scc1 .Lgprio_1
	s_setprio 1
.Lgprio_1:
.LBB0_82:
	s_add_u32 s3, s62, 0xfff80080
	s_addc_u32 s26, s63, -1
	s_add_i32 s36, 0, 0x10000
	s_cmp_eq_u32 s38, 28
	s_cselect_b32 s67, s19, s26
	s_cselect_b32 s66, s22, s3
	v_add_u32_e32 v146, s36, v139
	s_cselect_b32 s65, s5, s29
	s_cselect_b32 s64, s23, s28
	s_add_i32 s3, 0, 0x14000
	ds_read_b128 v[142:145], v146
	ds_read_b128 v[150:153], v146 offset:1024
	ds_read_b128 v[156:159], v146 offset:2048
	ds_read_b128 v[160:163], v146 offset:3072
	v_add_u32_e32 v146, s3, v139
	ds_read_b128 v[164:167], v146
	ds_read_b128 v[168:171], v146 offset:1024
	ds_read_b128 v[172:175], v146 offset:2048
	ds_read_b128 v[176:179], v146 offset:3072
	v_lshl_add_u64 v[146:147], s[62:63], 0, v[134:135]
	s_add_i32 m0, s61, 0xc000
	ds_read_b128 v[180:183], v141
	ds_read_b128 v[184:187], v141 offset:1024
	ds_read_b128 v[188:191], v141 offset:2048
	ds_read_b128 v[206:209], v141 offset:3072
	ds_read_b128 v[210:213], v141 offset:4096
	ds_read_b128 v[214:217], v141 offset:5120
	ds_read_b128 v[218:221], v141 offset:6144
	ds_read_b128 v[222:225], v141 offset:7168
	global_load_lds_dwordx4 v[146:147], off
	v_lshl_add_u64 v[146:147], s[62:63], 0, v[136:137]
	s_add_i32 m0, s61, 0xe000
	s_nop 0
	global_load_lds_dwordx4 v[146:147], off
	s_waitcnt vmcnt(8)
	s_waitcnt lgkmcnt(0)
	s_barrier
	s_waitcnt lgkmcnt(0)
	v_mfma_f32_16x16x32_bf16 v[124:127], v[142:145], v[180:183], v[124:127]
	v_mfma_f32_16x16x32_bf16 v[116:119], v[156:159], v[180:183], v[116:119]
	v_mfma_f32_16x16x32_bf16 v[108:111], v[142:145], v[188:191], v[108:111]
	v_mfma_f32_16x16x32_bf16 v[100:103], v[156:159], v[188:191], v[100:103]
	v_mfma_f32_16x16x32_bf16 v[92:95], v[142:145], v[210:213], v[92:95]
	v_mfma_f32_16x16x32_bf16 v[84:87], v[156:159], v[210:213], v[84:87]
	v_mfma_f32_16x16x32_bf16 v[76:79], v[142:145], v[218:221], v[76:79]
	v_mfma_f32_16x16x32_bf16 v[68:71], v[156:159], v[218:221], v[68:71]
	v_mfma_f32_16x16x32_bf16 v[124:127], v[150:153], v[184:187], v[124:127]
	v_mfma_f32_16x16x32_bf16 v[116:119], v[160:163], v[184:187], v[116:119]
	v_mfma_f32_16x16x32_bf16 v[108:111], v[150:153], v[206:209], v[108:111]
	v_mfma_f32_16x16x32_bf16 v[100:103], v[160:163], v[206:209], v[100:103]
	v_mfma_f32_16x16x32_bf16 v[92:95], v[150:153], v[214:217], v[92:95]
	v_mfma_f32_16x16x32_bf16 v[84:87], v[160:163], v[214:217], v[84:87]
	v_mfma_f32_16x16x32_bf16 v[76:79], v[150:153], v[222:225], v[76:79]
	v_mfma_f32_16x16x32_bf16 v[68:71], v[160:163], v[222:225], v[68:71]
	v_mfma_f32_16x16x32_bf16 v[120:123], v[164:167], v[180:183], v[120:123]
	v_mfma_f32_16x16x32_bf16 v[112:115], v[172:175], v[180:183], v[112:115]
	v_mfma_f32_16x16x32_bf16 v[104:107], v[164:167], v[188:191], v[104:107]
	v_mfma_f32_16x16x32_bf16 v[96:99], v[172:175], v[188:191], v[96:99]
	v_mfma_f32_16x16x32_bf16 v[88:91], v[164:167], v[210:213], v[88:91]
	v_mfma_f32_16x16x32_bf16 v[80:83], v[172:175], v[210:213], v[80:83]
	v_mfma_f32_16x16x32_bf16 v[72:75], v[164:167], v[218:221], v[72:75]
	v_mfma_f32_16x16x32_bf16 v[64:67], v[172:175], v[218:221], v[64:67]
	v_mfma_f32_16x16x32_bf16 v[120:123], v[168:171], v[184:187], v[120:123]
	v_mfma_f32_16x16x32_bf16 v[112:115], v[176:179], v[184:187], v[112:115]
	v_mfma_f32_16x16x32_bf16 v[104:107], v[168:171], v[206:209], v[104:107]
	v_mfma_f32_16x16x32_bf16 v[96:99], v[176:179], v[206:209], v[96:99]
	v_mfma_f32_16x16x32_bf16 v[88:91], v[168:171], v[214:217], v[88:91]
	v_mfma_f32_16x16x32_bf16 v[80:83], v[176:179], v[214:217], v[80:83]
	v_mfma_f32_16x16x32_bf16 v[72:75], v[168:171], v[222:225], v[72:75]
	v_mfma_f32_16x16x32_bf16 v[64:67], v[176:179], v[222:225], v[64:67]
	s_barrier
; #define PG8_STAGE(bufoff, gbase, voff) do { _Pragma("unroll") for (int _i = 0; _i < 2; ++_i) \
;         __builtin_amdgcn_global_load_lds((const unsigned*)((const char*)(gbase) + (voff)[_i]), (PG8_LAS unsigned*)(lds + (bufoff) + ldsw + _i * 8192), 16, 0, 0); } while (0)
; #define PG8_LDA(dst, b, h) do { _Pragma("unroll") for (int m = 0; m < 4; ++m) _Pragma("unroll") for (int k = 0; k < 2; ++k) dst[m][k] = *(const PG8_LAS bf16x8*)(lds + PG8_SA(b, h) + aoff + m * 2048 + k * 1024); } while (0)
; #define PG8_LDB(dst, b, h) do { _Pragma("unroll") for (int n = 0; n < 2; ++n) _Pragma("unroll") for (int k = 0; k < 2; ++k) dst[n][k] = *(const PG8_LAS bf16x8*)(lds + PG8_SB(b, h) + boff + n * 2048 + k * 1024); } while (0)
; #define PG8_MMA(ai, bj, At, Bt) do { __builtin_amdgcn_s_setprio(1); _Pragma("unroll") for (int m = 0; m < 4; ++m) _Pragma("unroll") for (int n = 0; n < 2; ++n) _Pragma("unroll") for (int k = 0; k < 2; ++k) \
;         acc[ai][bj][m][n] = __builtin_amdgcn_mfma_f32_16x16x32_bf16(Bt[n][k], At[m][k], acc[ai][bj][m][n], 0, 0, 0); __builtin_amdgcn_s_setprio(0); } while (0)
; #define PG8_WAIT_V(n) asm volatile("s_waitcnt vmcnt(" #n ")" ::: "memory")
; #define PG8_WAIT_L(n) asm volatile("s_waitcnt lgkmcnt(" #n ")" ::: "memory")
; #define PG8_BAR __builtin_amdgcn_s_barrier()
; #define PG8_SCHED __builtin_amdgcn_sched_barrier(0)
; template <class Epi, class Sched, bool ALIGN_EPI = false, bool SP2 = false>
; __device__ __forceinline__ void gemm_phase(PG8_LAS unsigned char* lds, const Gemm g, const Sched& S, const Epi& E, int wave_s) {
;     ...
;             PG8_LDA(At, 0, 1); PG8_STAGE(PG8_SB(0, 0), b2, voffB); PG8_STAGE(PG8_SB(0, 1), b2 + hstep, voffB); PG8_STAGE(PG8_SA(0, 0), a2, voffA);
;             PG8_WAIT_V(8); PG8_WAIT_L(0); PG8_BAR; PG8_MMA(1, 0, At, B0); PG8_MMA(1, 1, At, B1); PG8_BAR; PG8_SCHED;
;             PG8_LDB(B0, 1, 0); PG8_LDB(B1, 1, 1); PG8_SCHED; PG8_LDA(At, 1, 0); PG8_STAGE(PG8_SA(0, 1), a2 + hstep, voffA);
;             PG8_WAIT_V(8); PG8_WAIT_L(0); PG8_BAR; PG8_MMA(0, 0, At, B0); PG8_MMA(0, 1, At, B1); PG8_BAR; PG8_SCHED;
	s_add_i32 s26, s36, s25
	v_lshl_add_u64 v[146:147], s[64:65], 0, v[148:149]
	s_mov_b32 m0, s26
	ds_read_b128 v[180:183], v141 offset:16384
	ds_read_b128 v[184:187], v141 offset:17408
	ds_read_b128 v[188:191], v141 offset:18432
	ds_read_b128 v[206:209], v141 offset:19456
	ds_read_b128 v[210:213], v141 offset:20480
	ds_read_b128 v[214:217], v141 offset:21504
	ds_read_b128 v[218:221], v141 offset:22528
	ds_read_b128 v[222:225], v141 offset:23552
	global_load_lds_dwordx4 v[146:147], off
	s_add_i32 m0, s26, 0x2000
	s_add_u32 s36, s64, 0x80000
	v_lshl_add_u64 v[226:227], s[64:65], 0, v[128:129]
	s_addc_u32 s37, s65, 0
	s_add_i32 s3, s3, s25
	global_load_lds_dwordx4 v[226:227], off
	v_lshl_add_u64 v[228:229], s[36:37], 0, v[148:149]
	s_mov_b32 m0, s3
	v_lshl_add_u64 v[230:231], s[66:67], 0, v[130:131]
	global_load_lds_dwordx4 v[228:229], off
	v_lshl_add_u64 v[228:229], s[36:37], 0, v[128:129]
	s_add_i32 m0, s3, 0x2000
	s_nop 0
	global_load_lds_dwordx4 v[228:229], off
	v_lshl_add_u64 v[228:229], s[66:67], 0, v[132:133]
	s_mov_b32 m0, s61
	s_nop 0
	global_load_lds_dwordx4 v[228:229], off
	s_mov_b32 m0, s73
	s_nop 0
	global_load_lds_dwordx4 v[230:231], off
	s_waitcnt vmcnt(8)
	s_waitcnt lgkmcnt(0)
	s_barrier
	s_waitcnt lgkmcnt(0)
	v_mfma_f32_16x16x32_bf16 v[60:63], v[142:145], v[180:183], v[60:63]
	v_mfma_f32_16x16x32_bf16 v[52:55], v[156:159], v[180:183], v[52:55]
	v_mfma_f32_16x16x32_bf16 v[44:47], v[142:145], v[188:191], v[44:47]
	v_mfma_f32_16x16x32_bf16 v[36:39], v[156:159], v[188:191], v[36:39]
	v_mfma_f32_16x16x32_bf16 v[28:31], v[142:145], v[210:213], v[28:31]
	v_mfma_f32_16x16x32_bf16 v[20:23], v[156:159], v[210:213], v[20:23]
	v_mfma_f32_16x16x32_bf16 v[12:15], v[142:145], v[218:221], v[12:15]
	v_mfma_f32_16x16x32_bf16 v[4:7], v[156:159], v[218:221], v[4:7]
	v_mfma_f32_16x16x32_bf16 v[60:63], v[150:153], v[184:187], v[60:63]
	v_mfma_f32_16x16x32_bf16 v[52:55], v[160:163], v[184:187], v[52:55]
	v_mfma_f32_16x16x32_bf16 v[44:47], v[150:153], v[206:209], v[44:47]
	v_mfma_f32_16x16x32_bf16 v[36:39], v[160:163], v[206:209], v[36:39]
	v_mfma_f32_16x16x32_bf16 v[28:31], v[150:153], v[214:217], v[28:31]
	v_mfma_f32_16x16x32_bf16 v[20:23], v[160:163], v[214:217], v[20:23]
	v_mfma_f32_16x16x32_bf16 v[12:15], v[150:153], v[222:225], v[12:15]
	v_mfma_f32_16x16x32_bf16 v[4:7], v[160:163], v[222:225], v[4:7]
	v_mfma_f32_16x16x32_bf16 v[56:59], v[164:167], v[180:183], v[56:59]
	v_mfma_f32_16x16x32_bf16 v[48:51], v[172:175], v[180:183], v[48:51]
	v_mfma_f32_16x16x32_bf16 v[40:43], v[164:167], v[188:191], v[40:43]
	v_mfma_f32_16x16x32_bf16 v[32:35], v[172:175], v[188:191], v[32:35]
	v_mfma_f32_16x16x32_bf16 v[24:27], v[164:167], v[210:213], v[24:27]
	v_mfma_f32_16x16x32_bf16 v[16:19], v[172:175], v[210:213], v[16:19]
	v_mfma_f32_16x16x32_bf16 v[8:11], v[164:167], v[218:221], v[8:11]
	v_mfma_f32_16x16x32_bf16 v[0:3], v[172:175], v[218:221], v[0:3]
	v_mfma_f32_16x16x32_bf16 v[56:59], v[168:171], v[184:187], v[56:59]
	v_mfma_f32_16x16x32_bf16 v[48:51], v[176:179], v[184:187], v[48:51]
	v_mfma_f32_16x16x32_bf16 v[40:43], v[168:171], v[206:209], v[40:43]
	v_mfma_f32_16x16x32_bf16 v[32:35], v[176:179], v[206:209], v[32:35]
	v_mfma_f32_16x16x32_bf16 v[24:27], v[168:171], v[214:217], v[24:27]
	v_mfma_f32_16x16x32_bf16 v[16:19], v[176:179], v[214:217], v[16:19]
	v_mfma_f32_16x16x32_bf16 v[8:11], v[168:171], v[222:225], v[8:11]
	v_mfma_f32_16x16x32_bf16 v[0:3], v[176:179], v[222:225], v[0:3]
	s_barrier
	s_add_i32 s3, 0, 0x18000
	s_add_i32 s26, 0, 0x1c000
	v_add_u32_e32 v160, s3, v139
	v_add_u32_e32 v176, s26, v139
	ds_read_b128 v[142:145], v160
	ds_read_b128 v[150:153], v160 offset:1024
	ds_read_b128 v[156:159], v160 offset:2048
	ds_read_b128 v[160:163], v160 offset:3072
	ds_read_b128 v[164:167], v176
	ds_read_b128 v[168:171], v176 offset:1024
	ds_read_b128 v[172:175], v176 offset:2048
	ds_read_b128 v[176:179], v176 offset:3072
	s_add_u32 s36, s66, 0x80000
	s_addc_u32 s37, s67, 0
	s_mov_b32 m0, s74
	v_lshl_add_u64 v[232:233], s[36:37], 0, v[132:133]
	ds_read_b128 v[180:183], v141 offset:32768
	ds_read_b128 v[184:187], v141 offset:33792
	ds_read_b128 v[188:191], v141 offset:34816
	ds_read_b128 v[206:209], v141 offset:35840
	ds_read_b128 v[210:213], v141 offset:36864
	ds_read_b128 v[214:217], v141 offset:37888
	ds_read_b128 v[218:221], v141 offset:38912
	ds_read_b128 v[222:225], v141 offset:39936
	global_load_lds_dwordx4 v[232:233], off
	v_lshl_add_u64 v[232:233], s[36:37], 0, v[130:131]
	s_mov_b32 m0, s75
	s_nop 0
	global_load_lds_dwordx4 v[232:233], off
	s_waitcnt vmcnt(8)
	s_waitcnt lgkmcnt(0)
	s_barrier
; #define PG8_STAGE(bufoff, gbase, voff) do { _Pragma("unroll") for (int _i = 0; _i < 2; ++_i) \
;         __builtin_amdgcn_global_load_lds((const unsigned*)((const char*)(gbase) + (voff)[_i]), (PG8_LAS unsigned*)(lds + (bufoff) + ldsw + _i * 8192), 16, 0, 0); } while (0)
; #define PG8_LDA(dst, b, h) do { _Pragma("unroll") for (int m = 0; m < 4; ++m) _Pragma("unroll") for (int k = 0; k < 2; ++k) dst[m][k] = *(const PG8_LAS bf16x8*)(lds + PG8_SA(b, h) + aoff + m * 2048 + k * 1024); } while (0)
; #define PG8_MMA(ai, bj, At, Bt) do { __builtin_amdgcn_s_setprio(1); _Pragma("unroll") for (int m = 0; m < 4; ++m) _Pragma("unroll") for (int n = 0; n < 2; ++n) _Pragma("unroll") for (int k = 0; k < 2; ++k) \
;         acc[ai][bj][m][n] = __builtin_amdgcn_mfma_f32_16x16x32_bf16(Bt[n][k], At[m][k], acc[ai][bj][m][n], 0, 0, 0); __builtin_amdgcn_s_setprio(0); } while (0)
; #define PG8_WAIT_V(n) asm volatile("s_waitcnt vmcnt(" #n ")" ::: "memory")
; #define PG8_WAIT_L(n) asm volatile("s_waitcnt lgkmcnt(" #n ")" ::: "memory")
; #define PG8_BAR __builtin_amdgcn_s_barrier()
; #define PG8_SCHED __builtin_amdgcn_sched_barrier(0)
; template <class Epi, class Sched, bool ALIGN_EPI = false, bool SP2 = false>
; __device__ __forceinline__ void gemm_phase(PG8_LAS unsigned char* lds, const Gemm g, const Sched& S, const Epi& E, int wave_s) {
;     ...
;             PG8_WAIT_V(8); PG8_WAIT_L(0); PG8_BAR; PG8_MMA(0, 0, At, B0); PG8_MMA(0, 1, At, B1); PG8_BAR; PG8_SCHED;
;             PG8_LDA(At, 1, 1); PG8_STAGE(PG8_SB(1, 0), b3, voffB); PG8_STAGE(PG8_SB(1, 1), b3 + hstep, voffB); PG8_STAGE(PG8_SA(1, 0), a3, voffA);
;             PG8_WAIT_V(8); PG8_WAIT_L(0); PG8_BAR; PG8_MMA(1, 0, At, B0); PG8_MMA(1, 1, At, B1); PG8_BAR; PG8_SCHED;
	s_waitcnt lgkmcnt(0)
	v_mfma_f32_16x16x32_bf16 v[124:127], v[142:145], v[180:183], v[124:127]
	v_mfma_f32_16x16x32_bf16 v[116:119], v[156:159], v[180:183], v[116:119]
	v_mfma_f32_16x16x32_bf16 v[108:111], v[142:145], v[188:191], v[108:111]
	v_mfma_f32_16x16x32_bf16 v[100:103], v[156:159], v[188:191], v[100:103]
	v_mfma_f32_16x16x32_bf16 v[92:95], v[142:145], v[210:213], v[92:95]
	v_mfma_f32_16x16x32_bf16 v[84:87], v[156:159], v[210:213], v[84:87]
	v_mfma_f32_16x16x32_bf16 v[76:79], v[142:145], v[218:221], v[76:79]
	v_mfma_f32_16x16x32_bf16 v[68:71], v[156:159], v[218:221], v[68:71]
	v_mfma_f32_16x16x32_bf16 v[124:127], v[150:153], v[184:187], v[124:127]
	v_mfma_f32_16x16x32_bf16 v[116:119], v[160:163], v[184:187], v[116:119]
	v_mfma_f32_16x16x32_bf16 v[108:111], v[150:153], v[206:209], v[108:111]
	v_mfma_f32_16x16x32_bf16 v[100:103], v[160:163], v[206:209], v[100:103]
	v_mfma_f32_16x16x32_bf16 v[92:95], v[150:153], v[214:217], v[92:95]
	v_mfma_f32_16x16x32_bf16 v[84:87], v[160:163], v[214:217], v[84:87]
	v_mfma_f32_16x16x32_bf16 v[76:79], v[150:153], v[222:225], v[76:79]
	v_mfma_f32_16x16x32_bf16 v[68:71], v[160:163], v[222:225], v[68:71]
	v_mfma_f32_16x16x32_bf16 v[120:123], v[164:167], v[180:183], v[120:123]
	v_mfma_f32_16x16x32_bf16 v[112:115], v[172:175], v[180:183], v[112:115]
	v_mfma_f32_16x16x32_bf16 v[104:107], v[164:167], v[188:191], v[104:107]
	v_mfma_f32_16x16x32_bf16 v[96:99], v[172:175], v[188:191], v[96:99]
	v_mfma_f32_16x16x32_bf16 v[88:91], v[164:167], v[210:213], v[88:91]
	v_mfma_f32_16x16x32_bf16 v[80:83], v[172:175], v[210:213], v[80:83]
	v_mfma_f32_16x16x32_bf16 v[72:75], v[164:167], v[218:221], v[72:75]
	v_mfma_f32_16x16x32_bf16 v[64:67], v[172:175], v[218:221], v[64:67]
	v_mfma_f32_16x16x32_bf16 v[120:123], v[168:171], v[184:187], v[120:123]
	v_mfma_f32_16x16x32_bf16 v[112:115], v[176:179], v[184:187], v[112:115]
	v_mfma_f32_16x16x32_bf16 v[104:107], v[168:171], v[206:209], v[104:107]
	v_mfma_f32_16x16x32_bf16 v[96:99], v[176:179], v[206:209], v[96:99]
	v_mfma_f32_16x16x32_bf16 v[88:91], v[168:171], v[214:217], v[88:91]
	v_mfma_f32_16x16x32_bf16 v[80:83], v[176:179], v[214:217], v[80:83]
	v_mfma_f32_16x16x32_bf16 v[72:75], v[168:171], v[222:225], v[72:75]
	v_mfma_f32_16x16x32_bf16 v[64:67], v[176:179], v[222:225], v[64:67]
	s_barrier
	s_add_i32 s3, s3, s25
	v_lshl_add_u64 v[146:147], v[146:147], 0, s[34:35]
	s_mov_b32 m0, s3
	ds_read_b128 v[180:183], v141 offset:49152
	ds_read_b128 v[184:187], v141 offset:50176
	ds_read_b128 v[188:191], v141 offset:51200
	ds_read_b128 v[206:209], v141 offset:52224
	ds_read_b128 v[210:213], v141 offset:53248
	ds_read_b128 v[214:217], v141 offset:54272
	ds_read_b128 v[218:221], v141 offset:55296
	ds_read_b128 v[222:225], v141 offset:56320
	global_load_lds_dwordx4 v[146:147], off
	s_add_i32 m0, s3, 0x2000
	s_add_u32 s36, s64, 0x80080
	v_lshl_add_u64 v[146:147], v[226:227], 0, s[34:35]
	s_addc_u32 s37, s65, 0
	s_add_i32 s3, s26, s25
	global_load_lds_dwordx4 v[146:147], off
	v_lshl_add_u64 v[146:147], s[36:37], 0, v[148:149]
	s_mov_b32 m0, s3
	s_nop 0
	global_load_lds_dwordx4 v[146:147], off
	v_lshl_add_u64 v[146:147], s[36:37], 0, v[128:129]
	s_add_i32 m0, s3, 0x2000
	s_nop 0
	global_load_lds_dwordx4 v[146:147], off
	v_lshl_add_u64 v[146:147], v[228:229], 0, s[34:35]
	s_mov_b32 m0, s77
	s_nop 0
	global_load_lds_dwordx4 v[146:147], off
	v_lshl_add_u64 v[146:147], v[230:231], 0, s[34:35]
	s_mov_b32 m0, s78
	s_nop 0
	global_load_lds_dwordx4 v[146:147], off
	s_waitcnt vmcnt(8)
	s_waitcnt lgkmcnt(0)
	s_barrier
	s_waitcnt lgkmcnt(0)
	v_mfma_f32_16x16x32_bf16 v[60:63], v[142:145], v[180:183], v[60:63]
	v_mfma_f32_16x16x32_bf16 v[52:55], v[156:159], v[180:183], v[52:55]
	v_mfma_f32_16x16x32_bf16 v[44:47], v[142:145], v[188:191], v[44:47]
	v_mfma_f32_16x16x32_bf16 v[36:39], v[156:159], v[188:191], v[36:39]
	v_mfma_f32_16x16x32_bf16 v[28:31], v[142:145], v[210:213], v[28:31]
	v_mfma_f32_16x16x32_bf16 v[20:23], v[156:159], v[210:213], v[20:23]
	v_mfma_f32_16x16x32_bf16 v[12:15], v[142:145], v[218:221], v[12:15]
	v_mfma_f32_16x16x32_bf16 v[4:7], v[156:159], v[218:221], v[4:7]
	v_mfma_f32_16x16x32_bf16 v[60:63], v[150:153], v[184:187], v[60:63]
	v_mfma_f32_16x16x32_bf16 v[52:55], v[160:163], v[184:187], v[52:55]
	v_mfma_f32_16x16x32_bf16 v[44:47], v[150:153], v[206:209], v[44:47]
	v_mfma_f32_16x16x32_bf16 v[36:39], v[160:163], v[206:209], v[36:39]
	v_mfma_f32_16x16x32_bf16 v[28:31], v[150:153], v[214:217], v[28:31]
	v_mfma_f32_16x16x32_bf16 v[20:23], v[160:163], v[214:217], v[20:23]
	v_mfma_f32_16x16x32_bf16 v[12:15], v[150:153], v[222:225], v[12:15]
	v_mfma_f32_16x16x32_bf16 v[4:7], v[160:163], v[222:225], v[4:7]
	v_mfma_f32_16x16x32_bf16 v[56:59], v[164:167], v[180:183], v[56:59]
	v_mfma_f32_16x16x32_bf16 v[48:51], v[172:175], v[180:183], v[48:51]
	v_mfma_f32_16x16x32_bf16 v[40:43], v[164:167], v[188:191], v[40:43]
	v_mfma_f32_16x16x32_bf16 v[32:35], v[172:175], v[188:191], v[32:35]
	v_mfma_f32_16x16x32_bf16 v[24:27], v[164:167], v[210:213], v[24:27]
	v_mfma_f32_16x16x32_bf16 v[16:19], v[172:175], v[210:213], v[16:19]
	v_mfma_f32_16x16x32_bf16 v[8:11], v[164:167], v[218:221], v[8:11]
	v_mfma_f32_16x16x32_bf16 v[0:3], v[172:175], v[218:221], v[0:3]
	v_mfma_f32_16x16x32_bf16 v[56:59], v[168:171], v[184:187], v[56:59]
	v_mfma_f32_16x16x32_bf16 v[48:51], v[176:179], v[184:187], v[48:51]
	v_mfma_f32_16x16x32_bf16 v[40:43], v[168:171], v[206:209], v[40:43]
	v_mfma_f32_16x16x32_bf16 v[32:35], v[176:179], v[206:209], v[32:35]
	v_mfma_f32_16x16x32_bf16 v[24:27], v[168:171], v[214:217], v[24:27]
	v_mfma_f32_16x16x32_bf16 v[16:19], v[176:179], v[214:217], v[16:19]
	v_mfma_f32_16x16x32_bf16 v[8:11], v[168:171], v[222:225], v[8:11]
	v_mfma_f32_16x16x32_bf16 v[0:3], v[176:179], v[222:225], v[0:3]
	s_barrier
	s_add_i32 s38, s38, 2
	s_add_u32 s62, s62, 0x100
	s_addc_u32 s63, s63, 0
	s_add_u32 s28, s28, 0x100
	s_addc_u32 s29, s29, 0
	s_cmp_gt_u32 s38, 29
	s_cbranch_scc0 .LBB0_82
	s_setprio 0
	s_and_b64 vcc, exec, s[48:49]
	s_cbranch_vccz .LBB0_85
	s_barrier

; #define PG8_STAGE(bufoff, gbase, voff) do { _Pragma("unroll") for (int _i = 0; _i < 2; ++_i) \
;         __builtin_amdgcn_global_load_lds((const unsigned*)((const char*)(gbase) + (voff)[_i]), (PG8_LAS unsigned*)(lds + (bufoff) + ldsw + _i * 8192), 16, 0, 0); } while (0)
; #define PG8_LDA(dst, b, h) do { _Pragma("unroll") for (int m = 0; m < 4; ++m) _Pragma("unroll") for (int k = 0; k < 2; ++k) dst[m][k] = *(const PG8_LAS bf16x8*)(lds + PG8_SA(b, h) + aoff + m * 2048 + k * 1024); } while (0)
; #define PG8_WAIT_V(n) asm volatile("s_waitcnt vmcnt(" #n ")" ::: "memory")
; #define PG8_BAR __builtin_amdgcn_s_barrier()
; template <class Epi, class Sched, bool ALIGN_EPI = false, bool SP2 = false>
; __device__ __forceinline__ void gemm_phase(PG8_LAS unsigned char* lds, const Gemm g, const Sched& S, const Epi& E, int wave_s) {
;     ...
;         const bool has_next = S.next(ui + 1, nxt);
;         const char* nA = has_next ? (const char*)g.A + (size_t)nxt.pm * tstep : cA; const char* nB = has_next ? (const char*)g.Bt + (size_t)nxt.pn * tstep : cB;
;         for (int t = 0; t < nt; t += 2) {
;             const bool last = (t == nt - 2);
;             const char* a1 = cA + (size_t)(t + 1) * kstep;
;             const char* a2 = last ? nA : cA + (size_t)(t + 2) * kstep; const char* b2 = last ? nB : cB + (size_t)(t + 2) * kstep;
;             const char* a3 = a2 + kstep; const char* b3 = b2 + kstep;
;             if (last && has_next) S.a_ready(nxt);
;             if constexpr (SP2) {
;             PG8_LDB(B0, 0, 0); PG8_LDB(B1, 0, 1); PG8_SCHED; PG8_LDA(At, 0, 0); PG8_STAGE(PG8_SA(1, 1), a1 + hstep, voffA);
;             PG8_WAIT_V(8); PG8_WAIT_L(0); PG8_BAR; PG8_MMA(0, 0, At, B0); PG8_MMA(0, 1, At, B1); PG8_BAR; PG8_SCHED;
;             PG8_LDA(At, 0, 1); PG8_STAGE(PG8_SB(0, 0), b2, voffB); PG8_STAGE(PG8_SB(0, 1), b2 + hstep, voffB); PG8_STAGE(PG8_SA(0, 0), a2, voffA);
;             PG8_WAIT_V(8); PG8_WAIT_L(0); PG8_BAR; PG8_MMA(1, 0, At, B0); PG8_MMA(1, 1, At, B1); PG8_BAR; PG8_SCHED;
;     ...
;         { float zf_ = 0.f; asm volatile("" : "+v"(zf_)); const f32x4 zero4_ = {zf_, zf_, zf_, zf_};
; #pragma unroll
;         for (int a = 0; a < 2; ++a)
; #pragma unroll
;             for (int b = 0; b < 2; ++b)
; #pragma unroll
;                 for (int m = 0; m < 4; ++m)
; #pragma unroll
;                     for (int n = 0; n < 2; ++n) acc[a][b][m][n] = zero4_; }
.LBB0_114:
	s_ashr_i32 s55, s54, 31
	s_lshl_b64 s[22:23], s[54:55], 20
	s_add_u32 s56, s9, s22
	s_addc_u32 s57, s11, s23
	s_and_b64 s[22:23], s[40:41], exec
	s_cselect_b32 s22, s57, s63
	s_cselect_b32 s23, s56, s62
	s_ashr_i32 s53, s52, 31
	s_lshl_b64 s[28:29], s[52:53], 20
	s_add_u32 s58, s20, s28
	s_addc_u32 s59, s21, s29
	s_and_b64 s[28:29], s[40:41], exec
	s_cselect_b32 s5, s59, s65
	s_cselect_b32 s28, s58, s64
	s_add_u32 s29, s64, 0x100
	v_mov_b64_e32 v[6:7], v[2:3]
	v_mov_b64_e32 v[18:19], v[2:3]
	v_mov_b64_e32 v[22:23], v[2:3]
	v_mov_b64_e32 v[34:35], v[2:3]
	v_mov_b64_e32 v[38:39], v[2:3]
	v_mov_b64_e32 v[50:51], v[2:3]
	v_mov_b64_e32 v[54:55], v[2:3]
	v_mov_b64_e32 v[10:11], v[2:3]
	v_mov_b64_e32 v[14:15], v[2:3]
	v_mov_b64_e32 v[26:27], v[2:3]
	v_mov_b64_e32 v[30:31], v[2:3]
	v_mov_b64_e32 v[42:43], v[2:3]
	v_mov_b64_e32 v[46:47], v[2:3]
	v_mov_b64_e32 v[58:59], v[2:3]
	v_mov_b64_e32 v[62:63], v[2:3]
	v_mov_b64_e32 v[66:67], v[2:3]
	v_mov_b64_e32 v[70:71], v[2:3]
	v_mov_b64_e32 v[82:83], v[2:3]
	v_mov_b64_e32 v[86:87], v[2:3]
	v_mov_b64_e32 v[98:99], v[2:3]
	v_mov_b64_e32 v[102:103], v[2:3]
	v_mov_b64_e32 v[114:115], v[2:3]
	v_mov_b64_e32 v[118:119], v[2:3]
	v_mov_b64_e32 v[74:75], v[2:3]
	v_mov_b64_e32 v[78:79], v[2:3]
	v_mov_b64_e32 v[90:91], v[2:3]
	v_mov_b64_e32 v[94:95], v[2:3]
	v_mov_b64_e32 v[106:107], v[2:3]
	v_mov_b64_e32 v[110:111], v[2:3]
	v_mov_b64_e32 v[122:123], v[2:3]
	v_mov_b64_e32 v[126:127], v[2:3]
	s_addc_u32 s39, s65, 0
	s_mov_b32 s53, -2
	v_mov_b64_e32 v[4:5], v[0:1]
	v_mov_b64_e32 v[16:17], v[0:1]
	v_mov_b64_e32 v[20:21], v[0:1]
	v_mov_b64_e32 v[32:33], v[0:1]
	v_mov_b64_e32 v[36:37], v[0:1]
	v_mov_b64_e32 v[48:49], v[0:1]
	v_mov_b64_e32 v[52:53], v[0:1]
	v_mov_b64_e32 v[8:9], v[0:1]
	v_mov_b64_e32 v[12:13], v[0:1]
	v_mov_b64_e32 v[24:25], v[0:1]
	v_mov_b64_e32 v[28:29], v[0:1]
	v_mov_b64_e32 v[40:41], v[0:1]
	v_mov_b64_e32 v[44:45], v[0:1]
	v_mov_b64_e32 v[56:57], v[0:1]
	v_mov_b64_e32 v[60:61], v[0:1]
	v_mov_b64_e32 v[64:65], v[0:1]
	v_mov_b64_e32 v[68:69], v[0:1]
	v_mov_b64_e32 v[80:81], v[0:1]
	v_mov_b64_e32 v[84:85], v[0:1]
	v_mov_b64_e32 v[96:97], v[0:1]
	v_mov_b64_e32 v[100:101], v[0:1]
	v_mov_b64_e32 v[112:113], v[0:1]
	v_mov_b64_e32 v[116:117], v[0:1]
	v_mov_b64_e32 v[72:73], v[0:1]
	v_mov_b64_e32 v[76:77], v[0:1]
	v_mov_b64_e32 v[88:89], v[0:1]
	v_mov_b64_e32 v[92:93], v[0:1]
	v_mov_b64_e32 v[104:105], v[0:1]
	v_mov_b64_e32 v[108:109], v[0:1]
	v_mov_b64_e32 v[120:121], v[0:1]
	v_mov_b64_e32 v[124:125], v[0:1]
	v_readlane_b32 vcc_lo, v253, 14
	s_nop 3
	s_cmp_eq_u32 vcc_lo, 0
	s_cbranch_scc1 .Lgprio_2
	s_setprio 1
.Lgprio_2:
.LBB0_115:
	s_add_u32 s64, s62, 0x100
	s_addc_u32 s65, s63, 0
	s_add_i32 s3, 0, 0x10000
	s_cmp_eq_u32 s53, 28
	s_cselect_b32 s75, s22, s65
	s_cselect_b32 s74, s23, s64
	v_add_u32_e32 v134, s3, v137
	s_cselect_b32 s67, s5, s39
	s_cselect_b32 s66, s28, s29
	s_add_i32 s26, 0, 0x14000
	ds_read_b128 v[140:143], v134
	ds_read_b128 v[144:147], v134 offset:1024
	ds_read_b128 v[150:153], v134 offset:2048
	ds_read_b128 v[156:159], v134 offset:3072
	v_add_u32_e32 v134, s26, v137
	ds_read_b128 v[160:163], v134
	ds_read_b128 v[164:167], v134 offset:1024
	ds_read_b128 v[168:171], v134 offset:2048
	ds_read_b128 v[172:175], v134 offset:3072
	v_lshl_add_u64 v[134:135], s[62:63], 0, v[130:131]
	s_add_i32 m0, s61, 0xc000
	ds_read_b128 v[176:179], v139
	ds_read_b128 v[180:183], v139 offset:1024
	ds_read_b128 v[184:187], v139 offset:2048
	ds_read_b128 v[188:191], v139 offset:3072
	ds_read_b128 v[206:209], v139 offset:4096
	ds_read_b128 v[210:213], v139 offset:5120
	ds_read_b128 v[214:217], v139 offset:6144
	ds_read_b128 v[218:221], v139 offset:7168
	global_load_lds_dwordx4 v[134:135], off
	v_lshl_add_u64 v[134:135], s[62:63], 0, v[132:133]
	s_add_i32 m0, s61, 0xe000
	s_nop 0
	global_load_lds_dwordx4 v[134:135], off
	s_waitcnt vmcnt(8)
	s_waitcnt lgkmcnt(0)
	s_barrier
	s_waitcnt lgkmcnt(0)
	v_mfma_f32_16x16x32_bf16 v[124:127], v[140:143], v[176:179], v[124:127]
	v_mfma_f32_16x16x32_bf16 v[120:123], v[150:153], v[176:179], v[120:123]
	v_mfma_f32_16x16x32_bf16 v[108:111], v[140:143], v[184:187], v[108:111]
	v_mfma_f32_16x16x32_bf16 v[104:107], v[150:153], v[184:187], v[104:107]
	v_mfma_f32_16x16x32_bf16 v[92:95], v[140:143], v[206:209], v[92:95]
	v_mfma_f32_16x16x32_bf16 v[88:91], v[150:153], v[206:209], v[88:91]
	v_mfma_f32_16x16x32_bf16 v[76:79], v[140:143], v[214:217], v[76:79]
	v_mfma_f32_16x16x32_bf16 v[72:75], v[150:153], v[214:217], v[72:75]
	v_mfma_f32_16x16x32_bf16 v[124:127], v[144:147], v[180:183], v[124:127]
	v_mfma_f32_16x16x32_bf16 v[120:123], v[156:159], v[180:183], v[120:123]
	v_mfma_f32_16x16x32_bf16 v[108:111], v[144:147], v[188:191], v[108:111]
	v_mfma_f32_16x16x32_bf16 v[104:107], v[156:159], v[188:191], v[104:107]
	v_mfma_f32_16x16x32_bf16 v[92:95], v[144:147], v[210:213], v[92:95]
	v_mfma_f32_16x16x32_bf16 v[88:91], v[156:159], v[210:213], v[88:91]
	v_mfma_f32_16x16x32_bf16 v[76:79], v[144:147], v[218:221], v[76:79]
	v_mfma_f32_16x16x32_bf16 v[72:75], v[156:159], v[218:221], v[72:75]
	v_mfma_f32_16x16x32_bf16 v[116:119], v[160:163], v[176:179], v[116:119]
	v_mfma_f32_16x16x32_bf16 v[112:115], v[168:171], v[176:179], v[112:115]
	v_mfma_f32_16x16x32_bf16 v[100:103], v[160:163], v[184:187], v[100:103]
	v_mfma_f32_16x16x32_bf16 v[96:99], v[168:171], v[184:187], v[96:99]
	v_mfma_f32_16x16x32_bf16 v[84:87], v[160:163], v[206:209], v[84:87]
	v_mfma_f32_16x16x32_bf16 v[80:83], v[168:171], v[206:209], v[80:83]
	v_mfma_f32_16x16x32_bf16 v[68:71], v[160:163], v[214:217], v[68:71]
	v_mfma_f32_16x16x32_bf16 v[64:67], v[168:171], v[214:217], v[64:67]
	v_mfma_f32_16x16x32_bf16 v[116:119], v[164:167], v[180:183], v[116:119]
	v_mfma_f32_16x16x32_bf16 v[112:115], v[172:175], v[180:183], v[112:115]
	v_mfma_f32_16x16x32_bf16 v[100:103], v[164:167], v[188:191], v[100:103]
	v_mfma_f32_16x16x32_bf16 v[96:99], v[172:175], v[188:191], v[96:99]
	v_mfma_f32_16x16x32_bf16 v[84:87], v[164:167], v[210:213], v[84:87]
	v_mfma_f32_16x16x32_bf16 v[80:83], v[172:175], v[210:213], v[80:83]
	v_mfma_f32_16x16x32_bf16 v[68:71], v[164:167], v[218:221], v[68:71]
	v_mfma_f32_16x16x32_bf16 v[64:67], v[172:175], v[218:221], v[64:67]
	s_barrier
; #define PG8_STAGE(bufoff, gbase, voff) do { _Pragma("unroll") for (int _i = 0; _i < 2; ++_i) \
;         __builtin_amdgcn_global_load_lds((const unsigned*)((const char*)(gbase) + (voff)[_i]), (PG8_LAS unsigned*)(lds + (bufoff) + ldsw + _i * 8192), 16, 0, 0); } while (0)
; #define PG8_LDA(dst, b, h) do { _Pragma("unroll") for (int m = 0; m < 4; ++m) _Pragma("unroll") for (int k = 0; k < 2; ++k) dst[m][k] = *(const PG8_LAS bf16x8*)(lds + PG8_SA(b, h) + aoff + m * 2048 + k * 1024); } while (0)
; #define PG8_LDB(dst, b, h) do { _Pragma("unroll") for (int n = 0; n < 2; ++n) _Pragma("unroll") for (int k = 0; k < 2; ++k) dst[n][k] = *(const PG8_LAS bf16x8*)(lds + PG8_SB(b, h) + boff + n * 2048 + k * 1024); } while (0)
; #define PG8_MMA(ai, bj, At, Bt) do { __builtin_amdgcn_s_setprio(1); _Pragma("unroll") for (int m = 0; m < 4; ++m) _Pragma("unroll") for (int n = 0; n < 2; ++n) _Pragma("unroll") for (int k = 0; k < 2; ++k) \
;         acc[ai][bj][m][n] = __builtin_amdgcn_mfma_f32_16x16x32_bf16(Bt[n][k], At[m][k], acc[ai][bj][m][n], 0, 0, 0); __builtin_amdgcn_s_setprio(0); } while (0)
; #define PG8_WAIT_V(n) asm volatile("s_waitcnt vmcnt(" #n ")" ::: "memory")
; #define PG8_WAIT_L(n) asm volatile("s_waitcnt lgkmcnt(" #n ")" ::: "memory")
; #define PG8_BAR __builtin_amdgcn_s_barrier()
; #define PG8_SCHED __builtin_amdgcn_sched_barrier(0)
; template <class Epi, class Sched, bool ALIGN_EPI = false, bool SP2 = false>
; __device__ __forceinline__ void gemm_phase(PG8_LAS unsigned char* lds, const Gemm g, const Sched& S, const Epi& E, int wave_s) {
;     ...
;             PG8_LDA(At, 0, 1); PG8_STAGE(PG8_SB(0, 0), b2, voffB); PG8_STAGE(PG8_SB(0, 1), b2 + hstep, voffB); PG8_STAGE(PG8_SA(0, 0), a2, voffA);
;             PG8_WAIT_V(8); PG8_WAIT_L(0); PG8_BAR; PG8_MMA(1, 0, At, B0); PG8_MMA(1, 1, At, B1); PG8_BAR; PG8_SCHED;
;             PG8_LDB(B0, 1, 0); PG8_LDB(B1, 1, 1); PG8_SCHED; PG8_LDA(At, 1, 0); PG8_STAGE(PG8_SA(0, 1), a2 + hstep, voffA);
;             PG8_WAIT_V(8); PG8_WAIT_L(0); PG8_BAR; PG8_MMA(0, 0, At, B0); PG8_MMA(0, 1, At, B1); PG8_BAR; PG8_SCHED;
	s_add_i32 s3, s3, s25
	v_lshl_add_u64 v[134:135], s[66:67], 0, v[148:149]
	s_mov_b32 m0, s3
	ds_read_b128 v[176:179], v139 offset:16384
	ds_read_b128 v[180:183], v139 offset:17408
	ds_read_b128 v[184:187], v139 offset:18432
	ds_read_b128 v[188:191], v139 offset:19456
	ds_read_b128 v[206:209], v139 offset:20480
	ds_read_b128 v[210:213], v139 offset:21504
	ds_read_b128 v[214:217], v139 offset:22528
	ds_read_b128 v[218:221], v139 offset:23552
	global_load_lds_dwordx4 v[134:135], off
	s_add_i32 m0, s3, 0x2000
	s_add_u32 s36, s66, 0x80000
	v_lshl_add_u64 v[222:223], s[66:67], 0, v[128:129]
	s_addc_u32 s37, s67, 0
	s_add_i32 s3, s26, s25
	global_load_lds_dwordx4 v[222:223], off
	v_lshl_add_u64 v[224:225], s[36:37], 0, v[148:149]
	s_mov_b32 m0, s3
	v_lshl_add_u64 v[226:227], s[74:75], 0, v[128:129]
	global_load_lds_dwordx4 v[224:225], off
	v_lshl_add_u64 v[224:225], s[36:37], 0, v[128:129]
	s_add_i32 m0, s3, 0x2000
	s_nop 0
	global_load_lds_dwordx4 v[224:225], off
	v_lshl_add_u64 v[224:225], s[74:75], 0, v[148:149]
	s_mov_b32 m0, s61
	s_nop 0
	global_load_lds_dwordx4 v[224:225], off
	s_mov_b32 m0, s73
	s_nop 0
	global_load_lds_dwordx4 v[226:227], off
	s_waitcnt vmcnt(8)
	s_waitcnt lgkmcnt(0)
	s_barrier
	s_waitcnt lgkmcnt(0)
	v_mfma_f32_16x16x32_bf16 v[60:63], v[140:143], v[176:179], v[60:63]
	v_mfma_f32_16x16x32_bf16 v[56:59], v[150:153], v[176:179], v[56:59]
	v_mfma_f32_16x16x32_bf16 v[44:47], v[140:143], v[184:187], v[44:47]
	v_mfma_f32_16x16x32_bf16 v[40:43], v[150:153], v[184:187], v[40:43]
	v_mfma_f32_16x16x32_bf16 v[28:31], v[140:143], v[206:209], v[28:31]
	v_mfma_f32_16x16x32_bf16 v[24:27], v[150:153], v[206:209], v[24:27]
	v_mfma_f32_16x16x32_bf16 v[12:15], v[140:143], v[214:217], v[12:15]
	v_mfma_f32_16x16x32_bf16 v[8:11], v[150:153], v[214:217], v[8:11]
	v_mfma_f32_16x16x32_bf16 v[60:63], v[144:147], v[180:183], v[60:63]
	v_mfma_f32_16x16x32_bf16 v[56:59], v[156:159], v[180:183], v[56:59]
	v_mfma_f32_16x16x32_bf16 v[44:47], v[144:147], v[188:191], v[44:47]
	v_mfma_f32_16x16x32_bf16 v[40:43], v[156:159], v[188:191], v[40:43]
	v_mfma_f32_16x16x32_bf16 v[28:31], v[144:147], v[210:213], v[28:31]
	v_mfma_f32_16x16x32_bf16 v[24:27], v[156:159], v[210:213], v[24:27]
	v_mfma_f32_16x16x32_bf16 v[12:15], v[144:147], v[218:221], v[12:15]
	v_mfma_f32_16x16x32_bf16 v[8:11], v[156:159], v[218:221], v[8:11]
	v_mfma_f32_16x16x32_bf16 v[52:55], v[160:163], v[176:179], v[52:55]
	v_mfma_f32_16x16x32_bf16 v[48:51], v[168:171], v[176:179], v[48:51]
	v_mfma_f32_16x16x32_bf16 v[36:39], v[160:163], v[184:187], v[36:39]
	v_mfma_f32_16x16x32_bf16 v[32:35], v[168:171], v[184:187], v[32:35]
	v_mfma_f32_16x16x32_bf16 v[20:23], v[160:163], v[206:209], v[20:23]
	v_mfma_f32_16x16x32_bf16 v[16:19], v[168:171], v[206:209], v[16:19]
	v_mfma_f32_16x16x32_bf16 v[4:7], v[160:163], v[214:217], v[4:7]
	v_mfma_f32_16x16x32_bf16 v[0:3], v[168:171], v[214:217], v[0:3]
	v_mfma_f32_16x16x32_bf16 v[52:55], v[164:167], v[180:183], v[52:55]
	v_mfma_f32_16x16x32_bf16 v[48:51], v[172:175], v[180:183], v[48:51]
	v_mfma_f32_16x16x32_bf16 v[36:39], v[164:167], v[188:191], v[36:39]
	v_mfma_f32_16x16x32_bf16 v[32:35], v[172:175], v[188:191], v[32:35]
	v_mfma_f32_16x16x32_bf16 v[20:23], v[164:167], v[210:213], v[20:23]
	v_mfma_f32_16x16x32_bf16 v[16:19], v[172:175], v[210:213], v[16:19]
	v_mfma_f32_16x16x32_bf16 v[4:7], v[164:167], v[218:221], v[4:7]
	v_mfma_f32_16x16x32_bf16 v[0:3], v[172:175], v[218:221], v[0:3]
	s_barrier
	s_add_i32 s3, 0, 0x18000
	s_add_i32 s26, 0, 0x1c000
	v_add_u32_e32 v156, s3, v137
	v_add_u32_e32 v172, s26, v137
	ds_read_b128 v[140:143], v156
	ds_read_b128 v[144:147], v156 offset:1024
	ds_read_b128 v[150:153], v156 offset:2048
	ds_read_b128 v[156:159], v156 offset:3072
	ds_read_b128 v[160:163], v172
	ds_read_b128 v[164:167], v172 offset:1024
	ds_read_b128 v[168:171], v172 offset:2048
	ds_read_b128 v[172:175], v172 offset:3072
	s_add_u32 s36, s74, 0x80000
	s_addc_u32 s37, s75, 0
	s_mov_b32 m0, s76
	v_lshl_add_u64 v[228:229], s[36:37], 0, v[148:149]
	ds_read_b128 v[176:179], v139 offset:32768
	ds_read_b128 v[180:183], v139 offset:33792
	ds_read_b128 v[184:187], v139 offset:34816
	ds_read_b128 v[188:191], v139 offset:35840
	ds_read_b128 v[206:209], v139 offset:36864
	ds_read_b128 v[210:213], v139 offset:37888
	ds_read_b128 v[214:217], v139 offset:38912
	ds_read_b128 v[218:221], v139 offset:39936
	global_load_lds_dwordx4 v[228:229], off
	v_lshl_add_u64 v[228:229], s[36:37], 0, v[128:129]
	s_mov_b32 m0, s77
	s_nop 0
	global_load_lds_dwordx4 v[228:229], off
	s_waitcnt vmcnt(8)
	s_waitcnt lgkmcnt(0)
	s_barrier
; #define PG8_STAGE(bufoff, gbase, voff) do { _Pragma("unroll") for (int _i = 0; _i < 2; ++_i) \
;         __builtin_amdgcn_global_load_lds((const unsigned*)((const char*)(gbase) + (voff)[_i]), (PG8_LAS unsigned*)(lds + (bufoff) + ldsw + _i * 8192), 16, 0, 0); } while (0)
; #define PG8_LDA(dst, b, h) do { _Pragma("unroll") for (int m = 0; m < 4; ++m) _Pragma("unroll") for (int k = 0; k < 2; ++k) dst[m][k] = *(const PG8_LAS bf16x8*)(lds + PG8_SA(b, h) + aoff + m * 2048 + k * 1024); } while (0)
; #define PG8_MMA(ai, bj, At, Bt) do { __builtin_amdgcn_s_setprio(1); _Pragma("unroll") for (int m = 0; m < 4; ++m) _Pragma("unroll") for (int n = 0; n < 2; ++n) _Pragma("unroll") for (int k = 0; k < 2; ++k) \
;         acc[ai][bj][m][n] = __builtin_amdgcn_mfma_f32_16x16x32_bf16(Bt[n][k], At[m][k], acc[ai][bj][m][n], 0, 0, 0); __builtin_amdgcn_s_setprio(0); } while (0)
; #define PG8_WAIT_V(n) asm volatile("s_waitcnt vmcnt(" #n ")" ::: "memory")
; #define PG8_WAIT_L(n) asm volatile("s_waitcnt lgkmcnt(" #n ")" ::: "memory")
; #define PG8_BAR __builtin_amdgcn_s_barrier()
; #define PG8_SCHED __builtin_amdgcn_sched_barrier(0)
; template <class Epi, class Sched, bool ALIGN_EPI = false, bool SP2 = false>
; __device__ __forceinline__ void gemm_phase(PG8_LAS unsigned char* lds, const Gemm g, const Sched& S, const Epi& E, int wave_s) {
;     ...
;             PG8_WAIT_V(8); PG8_WAIT_L(0); PG8_BAR; PG8_MMA(0, 0, At, B0); PG8_MMA(0, 1, At, B1); PG8_BAR; PG8_SCHED;
;             PG8_LDA(At, 1, 1); PG8_STAGE(PG8_SB(1, 0), b3, voffB); PG8_STAGE(PG8_SB(1, 1), b3 + hstep, voffB); PG8_STAGE(PG8_SA(1, 0), a3, voffA);
;             PG8_WAIT_V(8); PG8_WAIT_L(0); PG8_BAR; PG8_MMA(1, 0, At, B0); PG8_MMA(1, 1, At, B1); PG8_BAR; PG8_SCHED;
	s_waitcnt lgkmcnt(0)
	v_mfma_f32_16x16x32_bf16 v[124:127], v[140:143], v[176:179], v[124:127]
	v_mfma_f32_16x16x32_bf16 v[120:123], v[150:153], v[176:179], v[120:123]
	v_mfma_f32_16x16x32_bf16 v[108:111], v[140:143], v[184:187], v[108:111]
	v_mfma_f32_16x16x32_bf16 v[104:107], v[150:153], v[184:187], v[104:107]
	v_mfma_f32_16x16x32_bf16 v[92:95], v[140:143], v[206:209], v[92:95]
	v_mfma_f32_16x16x32_bf16 v[88:91], v[150:153], v[206:209], v[88:91]
	v_mfma_f32_16x16x32_bf16 v[76:79], v[140:143], v[214:217], v[76:79]
	v_mfma_f32_16x16x32_bf16 v[72:75], v[150:153], v[214:217], v[72:75]
	v_mfma_f32_16x16x32_bf16 v[124:127], v[144:147], v[180:183], v[124:127]
	v_mfma_f32_16x16x32_bf16 v[120:123], v[156:159], v[180:183], v[120:123]
	v_mfma_f32_16x16x32_bf16 v[108:111], v[144:147], v[188:191], v[108:111]
	v_mfma_f32_16x16x32_bf16 v[104:107], v[156:159], v[188:191], v[104:107]
	v_mfma_f32_16x16x32_bf16 v[92:95], v[144:147], v[210:213], v[92:95]
	v_mfma_f32_16x16x32_bf16 v[88:91], v[156:159], v[210:213], v[88:91]
	v_mfma_f32_16x16x32_bf16 v[76:79], v[144:147], v[218:221], v[76:79]
	v_mfma_f32_16x16x32_bf16 v[72:75], v[156:159], v[218:221], v[72:75]
	v_mfma_f32_16x16x32_bf16 v[116:119], v[160:163], v[176:179], v[116:119]
	v_mfma_f32_16x16x32_bf16 v[112:115], v[168:171], v[176:179], v[112:115]
	v_mfma_f32_16x16x32_bf16 v[100:103], v[160:163], v[184:187], v[100:103]
	v_mfma_f32_16x16x32_bf16 v[96:99], v[168:171], v[184:187], v[96:99]
	v_mfma_f32_16x16x32_bf16 v[84:87], v[160:163], v[206:209], v[84:87]
	v_mfma_f32_16x16x32_bf16 v[80:83], v[168:171], v[206:209], v[80:83]
	v_mfma_f32_16x16x32_bf16 v[68:71], v[160:163], v[214:217], v[68:71]
	v_mfma_f32_16x16x32_bf16 v[64:67], v[168:171], v[214:217], v[64:67]
	v_mfma_f32_16x16x32_bf16 v[116:119], v[164:167], v[180:183], v[116:119]
	v_mfma_f32_16x16x32_bf16 v[112:115], v[172:175], v[180:183], v[112:115]
	v_mfma_f32_16x16x32_bf16 v[100:103], v[164:167], v[188:191], v[100:103]
	v_mfma_f32_16x16x32_bf16 v[96:99], v[172:175], v[188:191], v[96:99]
	v_mfma_f32_16x16x32_bf16 v[84:87], v[164:167], v[210:213], v[84:87]
	v_mfma_f32_16x16x32_bf16 v[80:83], v[172:175], v[210:213], v[80:83]
	v_mfma_f32_16x16x32_bf16 v[68:71], v[164:167], v[218:221], v[68:71]
	v_mfma_f32_16x16x32_bf16 v[64:67], v[172:175], v[218:221], v[64:67]
	s_barrier
	s_add_i32 s3, s3, s25
	v_lshl_add_u64 v[134:135], v[134:135], 0, s[34:35]
	s_mov_b32 m0, s3
	ds_read_b128 v[176:179], v139 offset:49152
	ds_read_b128 v[180:183], v139 offset:50176
	ds_read_b128 v[184:187], v139 offset:51200
	ds_read_b128 v[188:191], v139 offset:52224
	ds_read_b128 v[206:209], v139 offset:53248
	ds_read_b128 v[210:213], v139 offset:54272
	ds_read_b128 v[214:217], v139 offset:55296
	ds_read_b128 v[218:221], v139 offset:56320
	global_load_lds_dwordx4 v[134:135], off
	s_add_i32 m0, s3, 0x2000
	s_add_u32 s36, s66, 0x80080
	v_lshl_add_u64 v[134:135], v[222:223], 0, s[34:35]
	s_addc_u32 s37, s67, 0
	s_add_i32 s3, s26, s25
	global_load_lds_dwordx4 v[134:135], off
	v_lshl_add_u64 v[134:135], s[36:37], 0, v[148:149]
	s_mov_b32 m0, s3
	s_nop 0
	global_load_lds_dwordx4 v[134:135], off
	v_lshl_add_u64 v[134:135], s[36:37], 0, v[128:129]
	s_add_i32 m0, s3, 0x2000
	s_nop 0
	global_load_lds_dwordx4 v[134:135], off
	v_lshl_add_u64 v[134:135], v[224:225], 0, s[34:35]
	s_mov_b32 m0, s79
	s_nop 0
	global_load_lds_dwordx4 v[134:135], off
	v_lshl_add_u64 v[134:135], v[226:227], 0, s[34:35]
	s_mov_b32 m0, s18
	s_nop 0
	global_load_lds_dwordx4 v[134:135], off
	s_waitcnt vmcnt(8)
	s_waitcnt lgkmcnt(0)
	s_barrier
	s_waitcnt lgkmcnt(0)
	v_mfma_f32_16x16x32_bf16 v[60:63], v[140:143], v[176:179], v[60:63]
	v_mfma_f32_16x16x32_bf16 v[56:59], v[150:153], v[176:179], v[56:59]
	v_mfma_f32_16x16x32_bf16 v[44:47], v[140:143], v[184:187], v[44:47]
	v_mfma_f32_16x16x32_bf16 v[40:43], v[150:153], v[184:187], v[40:43]
	v_mfma_f32_16x16x32_bf16 v[28:31], v[140:143], v[206:209], v[28:31]
	v_mfma_f32_16x16x32_bf16 v[24:27], v[150:153], v[206:209], v[24:27]
	v_mfma_f32_16x16x32_bf16 v[12:15], v[140:143], v[214:217], v[12:15]
	v_mfma_f32_16x16x32_bf16 v[8:11], v[150:153], v[214:217], v[8:11]
	v_mfma_f32_16x16x32_bf16 v[60:63], v[144:147], v[180:183], v[60:63]
	v_mfma_f32_16x16x32_bf16 v[56:59], v[156:159], v[180:183], v[56:59]
	v_mfma_f32_16x16x32_bf16 v[44:47], v[144:147], v[188:191], v[44:47]
	v_mfma_f32_16x16x32_bf16 v[40:43], v[156:159], v[188:191], v[40:43]
	v_mfma_f32_16x16x32_bf16 v[28:31], v[144:147], v[210:213], v[28:31]
	v_mfma_f32_16x16x32_bf16 v[24:27], v[156:159], v[210:213], v[24:27]
	v_mfma_f32_16x16x32_bf16 v[12:15], v[144:147], v[218:221], v[12:15]
	v_mfma_f32_16x16x32_bf16 v[8:11], v[156:159], v[218:221], v[8:11]
	v_mfma_f32_16x16x32_bf16 v[52:55], v[160:163], v[176:179], v[52:55]
	v_mfma_f32_16x16x32_bf16 v[48:51], v[168:171], v[176:179], v[48:51]
	v_mfma_f32_16x16x32_bf16 v[36:39], v[160:163], v[184:187], v[36:39]
	v_mfma_f32_16x16x32_bf16 v[32:35], v[168:171], v[184:187], v[32:35]
	v_mfma_f32_16x16x32_bf16 v[20:23], v[160:163], v[206:209], v[20:23]
	v_mfma_f32_16x16x32_bf16 v[16:19], v[168:171], v[206:209], v[16:19]
	v_mfma_f32_16x16x32_bf16 v[4:7], v[160:163], v[214:217], v[4:7]
	v_mfma_f32_16x16x32_bf16 v[0:3], v[168:171], v[214:217], v[0:3]
	v_mfma_f32_16x16x32_bf16 v[52:55], v[164:167], v[180:183], v[52:55]
	v_mfma_f32_16x16x32_bf16 v[48:51], v[172:175], v[180:183], v[48:51]
	v_mfma_f32_16x16x32_bf16 v[36:39], v[164:167], v[188:191], v[36:39]
	v_mfma_f32_16x16x32_bf16 v[32:35], v[172:175], v[188:191], v[32:35]
	v_mfma_f32_16x16x32_bf16 v[20:23], v[164:167], v[210:213], v[20:23]
	v_mfma_f32_16x16x32_bf16 v[16:19], v[172:175], v[210:213], v[16:19]
	v_mfma_f32_16x16x32_bf16 v[4:7], v[164:167], v[218:221], v[4:7]
	v_mfma_f32_16x16x32_bf16 v[0:3], v[172:175], v[218:221], v[0:3]
	s_barrier
	s_add_i32 s53, s53, 2
	s_add_u32 s29, s29, 0x100
	s_addc_u32 s39, s39, 0
	s_cmp_gt_u32 s53, 29
	s_mov_b64 s[62:63], s[64:65]
	s_cbranch_scc0 .LBB0_115
	s_setprio 0
	s_and_b64 vcc, exec, s[48:49]
	s_cbranch_vccz .LBB0_118
	s_barrier

; #define PG8_STAGE(bufoff, gbase, voff) do { _Pragma("unroll") for (int _i = 0; _i < 2; ++_i) \
;         __builtin_amdgcn_global_load_lds((const unsigned*)((const char*)(gbase) + (voff)[_i]), (PG8_LAS unsigned*)(lds + (bufoff) + ldsw + _i * 8192), 16, 0, 0); } while (0)
; #define PG8_LDA(dst, b, h) do { _Pragma("unroll") for (int m = 0; m < 4; ++m) _Pragma("unroll") for (int k = 0; k < 2; ++k) dst[m][k] = *(const PG8_LAS bf16x8*)(lds + PG8_SA(b, h) + aoff + m * 2048 + k * 1024); } while (0)
; #define PG8_LDB(dst, b, h) do { _Pragma("unroll") for (int n = 0; n < 2; ++n) _Pragma("unroll") for (int k = 0; k < 2; ++k) dst[n][k] = *(const PG8_LAS bf16x8*)(lds + PG8_SB(b, h) + boff + n * 2048 + k * 1024); } while (0)
; #define PG8_WAIT_V(n) asm volatile("s_waitcnt vmcnt(" #n ")" ::: "memory")
; #define PG8_WAIT_L(n) asm volatile("s_waitcnt lgkmcnt(" #n ")" ::: "memory")
; template <class Epi, class Sched, bool ALIGN_EPI = false, bool SP2 = false>
; __device__ __forceinline__ void gemm_phase(PG8_LAS unsigned char* lds, const Gemm g, const Sched& S, const Epi& E, int wave_s) {
;     ...
;         const bool has_next = S.next(ui + 1, nxt);
;         const char* nA = has_next ? (const char*)g.A + (size_t)nxt.pm * tstep : cA; const char* nB = has_next ? (const char*)g.Bt + (size_t)nxt.pn * tstep : cB;
;         for (int t = 0; t < nt; t += 2) {
;             const bool last = (t == nt - 2);
;             const char* a1 = cA + (size_t)(t + 1) * kstep;
;             const char* a2 = last ? nA : cA + (size_t)(t + 2) * kstep; const char* b2 = last ? nB : cB + (size_t)(t + 2) * kstep;
;             const char* a3 = a2 + kstep; const char* b3 = b2 + kstep;
;             if (last && has_next) S.a_ready(nxt);
;             if constexpr (SP2) {
;             PG8_LDB(B0, 0, 0); PG8_LDB(B1, 0, 1); PG8_SCHED; PG8_LDA(At, 0, 0); PG8_STAGE(PG8_SA(1, 1), a1 + hstep, voffA);
;             PG8_WAIT_V(8); PG8_WAIT_L(0); PG8_BAR; PG8_MMA(0, 0, At, B0); PG8_MMA(0, 1, At, B1); PG8_BAR; PG8_SCHED;
;     ...
;         { float zf_ = 0.f; asm volatile("" : "+v"(zf_)); const f32x4 zero4_ = {zf_, zf_, zf_, zf_};
; #pragma unroll
;         for (int a = 0; a < 2; ++a)
; #pragma unroll
;             for (int b = 0; b < 2; ++b)
; #pragma unroll
;                 for (int m = 0; m < 4; ++m)
; #pragma unroll
;                     for (int n = 0; n < 2; ++n) acc[a][b][m][n] = zero4_; }
.LBB0_386:
	s_ashr_i32 s53, s52, 31
	s_lshl_b64 s[22:23], s[52:53], 18
	s_add_u32 s54, s19, s22
	s_addc_u32 s55, s20, s23
	s_and_b64 s[22:23], s[40:41], exec
	s_cselect_b32 s22, s55, s61
	s_cselect_b32 s23, s54, s60
	s_ashr_i32 s49, s48, 31
	s_lshl_b64 s[56:57], s[48:49], 18
	s_add_u32 s56, s43, s56
	s_addc_u32 s57, s1, s57
	s_and_b64 s[64:65], s[40:41], exec
	s_cselect_b32 s5, s57, s63
	s_cselect_b32 s29, s56, s62
	s_add_u32 s60, s60, 0x20080
	s_addc_u32 s61, s61, 0
	s_add_u32 s49, s62, 0x100
	v_mov_b64_e32 v[6:7], v[2:3]
	v_mov_b64_e32 v[18:19], v[2:3]
	v_mov_b64_e32 v[22:23], v[2:3]
	v_mov_b64_e32 v[34:35], v[2:3]
	v_mov_b64_e32 v[38:39], v[2:3]
	v_mov_b64_e32 v[50:51], v[2:3]
	v_mov_b64_e32 v[54:55], v[2:3]
	v_mov_b64_e32 v[10:11], v[2:3]
	v_mov_b64_e32 v[14:15], v[2:3]
	v_mov_b64_e32 v[26:27], v[2:3]
	v_mov_b64_e32 v[30:31], v[2:3]
	v_mov_b64_e32 v[42:43], v[2:3]
	v_mov_b64_e32 v[46:47], v[2:3]
	v_mov_b64_e32 v[58:59], v[2:3]
	v_mov_b64_e32 v[62:63], v[2:3]
	v_mov_b64_e32 v[66:67], v[2:3]
	v_mov_b64_e32 v[70:71], v[2:3]
	v_mov_b64_e32 v[82:83], v[2:3]
	v_mov_b64_e32 v[86:87], v[2:3]
	v_mov_b64_e32 v[98:99], v[2:3]
	v_mov_b64_e32 v[102:103], v[2:3]
	v_mov_b64_e32 v[114:115], v[2:3]
	v_mov_b64_e32 v[118:119], v[2:3]
	v_mov_b64_e32 v[74:75], v[2:3]
	v_mov_b64_e32 v[78:79], v[2:3]
	v_mov_b64_e32 v[90:91], v[2:3]
	v_mov_b64_e32 v[94:95], v[2:3]
	v_mov_b64_e32 v[106:107], v[2:3]
	v_mov_b64_e32 v[110:111], v[2:3]
	v_mov_b64_e32 v[122:123], v[2:3]
	v_mov_b64_e32 v[126:127], v[2:3]
	s_addc_u32 s53, s63, 0
	s_mov_b32 s74, -2
	v_mov_b64_e32 v[4:5], v[0:1]
	v_mov_b64_e32 v[16:17], v[0:1]
	v_mov_b64_e32 v[20:21], v[0:1]
	v_mov_b64_e32 v[32:33], v[0:1]
	v_mov_b64_e32 v[36:37], v[0:1]
	v_mov_b64_e32 v[48:49], v[0:1]
	v_mov_b64_e32 v[52:53], v[0:1]
	v_mov_b64_e32 v[8:9], v[0:1]
	v_mov_b64_e32 v[12:13], v[0:1]
	v_mov_b64_e32 v[24:25], v[0:1]
	v_mov_b64_e32 v[28:29], v[0:1]
	v_mov_b64_e32 v[40:41], v[0:1]
	v_mov_b64_e32 v[44:45], v[0:1]
	v_mov_b64_e32 v[56:57], v[0:1]
	v_mov_b64_e32 v[60:61], v[0:1]
	v_mov_b64_e32 v[64:65], v[0:1]
	v_mov_b64_e32 v[68:69], v[0:1]
	v_mov_b64_e32 v[80:81], v[0:1]
	v_mov_b64_e32 v[84:85], v[0:1]
	v_mov_b64_e32 v[96:97], v[0:1]
	v_mov_b64_e32 v[100:101], v[0:1]
	v_mov_b64_e32 v[112:113], v[0:1]
	v_mov_b64_e32 v[116:117], v[0:1]
	v_mov_b64_e32 v[72:73], v[0:1]
	v_mov_b64_e32 v[76:77], v[0:1]
	v_mov_b64_e32 v[88:89], v[0:1]
	v_mov_b64_e32 v[92:93], v[0:1]
	v_mov_b64_e32 v[104:105], v[0:1]
	v_mov_b64_e32 v[108:109], v[0:1]
	v_mov_b64_e32 v[120:121], v[0:1]
	v_mov_b64_e32 v[124:125], v[0:1]
	v_readlane_b32 vcc_lo, v253, 14
	s_nop 3
	s_cmp_eq_u32 vcc_lo, 0
	s_cbranch_scc1 .Lgprio_5
	s_setprio 1
.Lgprio_5:
.LBB0_387:
	s_add_u32 s36, s60, 0xfffe0080
	s_addc_u32 s37, s61, -1
	s_add_i32 s75, 0, 0x10000
	s_cmp_eq_u32 s74, 4
	s_cselect_b32 s65, s22, s37
	s_cselect_b32 s64, s23, s36
	v_add_u32_e32 v138, s75, v141
	s_cselect_b32 s63, s5, s53
	s_cselect_b32 s62, s29, s49
	s_add_i32 s36, 0, 0x14000
	ds_read_b128 v[144:147], v138
	ds_read_b128 v[156:159], v138 offset:1024
	ds_read_b128 v[160:163], v138 offset:2048
	ds_read_b128 v[164:167], v138 offset:3072
	v_add_u32_e32 v138, s36, v141
	ds_read_b128 v[168:171], v138
	ds_read_b128 v[172:175], v138 offset:1024
	ds_read_b128 v[176:179], v138 offset:2048
	ds_read_b128 v[180:183], v138 offset:3072
	v_lshl_add_u64 v[138:139], s[60:61], 0, v[134:135]
	s_add_i32 m0, s25, 0xc000
	ds_read_b128 v[184:187], v143
	ds_read_b128 v[188:191], v143 offset:1024
	ds_read_b128 v[206:209], v143 offset:2048
	ds_read_b128 v[210:213], v143 offset:3072
	ds_read_b128 v[214:217], v143 offset:4096
	ds_read_b128 v[218:221], v143 offset:5120
	ds_read_b128 v[222:225], v143 offset:6144
	ds_read_b128 v[226:229], v143 offset:7168
	global_load_lds_dwordx4 v[138:139], off
	v_lshl_add_u64 v[138:139], s[60:61], 0, v[136:137]
	s_add_i32 m0, s25, 0xe000
	s_nop 0
	global_load_lds_dwordx4 v[138:139], off
	s_waitcnt vmcnt(8)
	s_waitcnt lgkmcnt(0)
	s_barrier
	s_waitcnt lgkmcnt(0)
	v_mfma_f32_16x16x32_bf16 v[124:127], v[144:147], v[184:187], v[124:127]
	v_mfma_f32_16x16x32_bf16 v[120:123], v[160:163], v[184:187], v[120:123]
	v_mfma_f32_16x16x32_bf16 v[108:111], v[144:147], v[206:209], v[108:111]
	v_mfma_f32_16x16x32_bf16 v[104:107], v[160:163], v[206:209], v[104:107]
	v_mfma_f32_16x16x32_bf16 v[92:95], v[144:147], v[214:217], v[92:95]
	v_mfma_f32_16x16x32_bf16 v[88:91], v[160:163], v[214:217], v[88:91]
	v_mfma_f32_16x16x32_bf16 v[76:79], v[144:147], v[222:225], v[76:79]
	v_mfma_f32_16x16x32_bf16 v[72:75], v[160:163], v[222:225], v[72:75]
	v_mfma_f32_16x16x32_bf16 v[124:127], v[156:159], v[188:191], v[124:127]
	v_mfma_f32_16x16x32_bf16 v[120:123], v[164:167], v[188:191], v[120:123]
	v_mfma_f32_16x16x32_bf16 v[108:111], v[156:159], v[210:213], v[108:111]
	v_mfma_f32_16x16x32_bf16 v[104:107], v[164:167], v[210:213], v[104:107]
	v_mfma_f32_16x16x32_bf16 v[92:95], v[156:159], v[218:221], v[92:95]
	v_mfma_f32_16x16x32_bf16 v[88:91], v[164:167], v[218:221], v[88:91]
	v_mfma_f32_16x16x32_bf16 v[76:79], v[156:159], v[226:229], v[76:79]
	v_mfma_f32_16x16x32_bf16 v[72:75], v[164:167], v[226:229], v[72:75]
	v_mfma_f32_16x16x32_bf16 v[116:119], v[168:171], v[184:187], v[116:119]
	v_mfma_f32_16x16x32_bf16 v[112:115], v[176:179], v[184:187], v[112:115]
	v_mfma_f32_16x16x32_bf16 v[100:103], v[168:171], v[206:209], v[100:103]
	v_mfma_f32_16x16x32_bf16 v[96:99], v[176:179], v[206:209], v[96:99]
	v_mfma_f32_16x16x32_bf16 v[84:87], v[168:171], v[214:217], v[84:87]
	v_mfma_f32_16x16x32_bf16 v[80:83], v[176:179], v[214:217], v[80:83]
	v_mfma_f32_16x16x32_bf16 v[68:71], v[168:171], v[222:225], v[68:71]
	v_mfma_f32_16x16x32_bf16 v[64:67], v[176:179], v[222:225], v[64:67]
	v_mfma_f32_16x16x32_bf16 v[116:119], v[172:175], v[188:191], v[116:119]
	v_mfma_f32_16x16x32_bf16 v[112:115], v[180:183], v[188:191], v[112:115]
	v_mfma_f32_16x16x32_bf16 v[100:103], v[172:175], v[210:213], v[100:103]
	v_mfma_f32_16x16x32_bf16 v[96:99], v[180:183], v[210:213], v[96:99]
	v_mfma_f32_16x16x32_bf16 v[84:87], v[172:175], v[218:221], v[84:87]
	v_mfma_f32_16x16x32_bf16 v[80:83], v[180:183], v[218:221], v[80:83]
	v_mfma_f32_16x16x32_bf16 v[68:71], v[172:175], v[226:229], v[68:71]
	v_mfma_f32_16x16x32_bf16 v[64:67], v[180:183], v[226:229], v[64:67]
	s_barrier
; #define PG8_STAGE(bufoff, gbase, voff) do { _Pragma("unroll") for (int _i = 0; _i < 2; ++_i) \
;         __builtin_amdgcn_global_load_lds((const unsigned*)((const char*)(gbase) + (voff)[_i]), (PG8_LAS unsigned*)(lds + (bufoff) + ldsw + _i * 8192), 16, 0, 0); } while (0)
; #define PG8_LDA(dst, b, h) do { _Pragma("unroll") for (int m = 0; m < 4; ++m) _Pragma("unroll") for (int k = 0; k < 2; ++k) dst[m][k] = *(const PG8_LAS bf16x8*)(lds + PG8_SA(b, h) + aoff + m * 2048 + k * 1024); } while (0)
; #define PG8_LDB(dst, b, h) do { _Pragma("unroll") for (int n = 0; n < 2; ++n) _Pragma("unroll") for (int k = 0; k < 2; ++k) dst[n][k] = *(const PG8_LAS bf16x8*)(lds + PG8_SB(b, h) + boff + n * 2048 + k * 1024); } while (0)
; #define PG8_MMA(ai, bj, At, Bt) do { __builtin_amdgcn_s_setprio(1); _Pragma("unroll") for (int m = 0; m < 4; ++m) _Pragma("unroll") for (int n = 0; n < 2; ++n) _Pragma("unroll") for (int k = 0; k < 2; ++k) \
;         acc[ai][bj][m][n] = __builtin_amdgcn_mfma_f32_16x16x32_bf16(Bt[n][k], At[m][k], acc[ai][bj][m][n], 0, 0, 0); __builtin_amdgcn_s_setprio(0); } while (0)
; #define PG8_WAIT_V(n) asm volatile("s_waitcnt vmcnt(" #n ")" ::: "memory")
; #define PG8_WAIT_L(n) asm volatile("s_waitcnt lgkmcnt(" #n ")" ::: "memory")
; #define PG8_BAR __builtin_amdgcn_s_barrier()
; #define PG8_SCHED __builtin_amdgcn_sched_barrier(0)
; template <class Epi, class Sched, bool ALIGN_EPI = false, bool SP2 = false>
; __device__ __forceinline__ void gemm_phase(PG8_LAS unsigned char* lds, const Gemm g, const Sched& S, const Epi& E, int wave_s) {
;     ...
;             PG8_LDA(At, 0, 1); PG8_STAGE(PG8_SB(0, 0), b2, voffB); PG8_STAGE(PG8_SB(0, 1), b2 + hstep, voffB); PG8_STAGE(PG8_SA(0, 0), a2, voffA);
;             PG8_WAIT_V(8); PG8_WAIT_L(0); PG8_BAR; PG8_MMA(1, 0, At, B0); PG8_MMA(1, 1, At, B1); PG8_BAR; PG8_SCHED;
;             PG8_LDB(B0, 1, 0); PG8_LDB(B1, 1, 1); PG8_SCHED; PG8_LDA(At, 1, 0); PG8_STAGE(PG8_SA(0, 1), a2 + hstep, voffA);
;             PG8_WAIT_V(8); PG8_WAIT_L(0); PG8_BAR; PG8_MMA(0, 0, At, B0); PG8_MMA(0, 1, At, B1); PG8_BAR; PG8_SCHED;
	s_add_i32 s37, s75, s21
	v_lshl_add_u64 v[138:139], s[62:63], 0, v[148:149]
	s_mov_b32 m0, s37
	ds_read_b128 v[184:187], v143 offset:16384
	ds_read_b128 v[188:191], v143 offset:17408
	ds_read_b128 v[206:209], v143 offset:18432
	ds_read_b128 v[210:213], v143 offset:19456
	ds_read_b128 v[214:217], v143 offset:20480
	ds_read_b128 v[218:221], v143 offset:21504
	ds_read_b128 v[222:225], v143 offset:22528
	ds_read_b128 v[226:229], v143 offset:23552
	global_load_lds_dwordx4 v[138:139], off
	s_add_i32 m0, s37, 0x2000
	s_add_u32 s76, s62, 0x20000
	v_lshl_add_u64 v[150:151], s[62:63], 0, v[128:129]
	s_addc_u32 s77, s63, 0
	s_add_i32 s36, s36, s21
	global_load_lds_dwordx4 v[150:151], off
	v_lshl_add_u64 v[152:153], s[76:77], 0, v[148:149]
	s_mov_b32 m0, s36
	v_lshl_add_u64 v[230:231], s[64:65], 0, v[130:131]
	global_load_lds_dwordx4 v[152:153], off
	v_lshl_add_u64 v[152:153], s[76:77], 0, v[128:129]
	s_add_i32 m0, s36, 0x2000
	s_nop 0
	global_load_lds_dwordx4 v[152:153], off
	v_lshl_add_u64 v[152:153], s[64:65], 0, v[132:133]
	s_mov_b32 m0, s25
	s_nop 0
	global_load_lds_dwordx4 v[152:153], off
	s_mov_b32 m0, s38
	s_nop 0
	global_load_lds_dwordx4 v[230:231], off
	s_waitcnt vmcnt(8)
	s_waitcnt lgkmcnt(0)
	s_barrier
	s_waitcnt lgkmcnt(0)
	v_mfma_f32_16x16x32_bf16 v[60:63], v[144:147], v[184:187], v[60:63]
	v_mfma_f32_16x16x32_bf16 v[56:59], v[160:163], v[184:187], v[56:59]
	v_mfma_f32_16x16x32_bf16 v[44:47], v[144:147], v[206:209], v[44:47]
	v_mfma_f32_16x16x32_bf16 v[40:43], v[160:163], v[206:209], v[40:43]
	v_mfma_f32_16x16x32_bf16 v[28:31], v[144:147], v[214:217], v[28:31]
	v_mfma_f32_16x16x32_bf16 v[24:27], v[160:163], v[214:217], v[24:27]
	v_mfma_f32_16x16x32_bf16 v[12:15], v[144:147], v[222:225], v[12:15]
	v_mfma_f32_16x16x32_bf16 v[8:11], v[160:163], v[222:225], v[8:11]
	v_mfma_f32_16x16x32_bf16 v[60:63], v[156:159], v[188:191], v[60:63]
	v_mfma_f32_16x16x32_bf16 v[56:59], v[164:167], v[188:191], v[56:59]
	v_mfma_f32_16x16x32_bf16 v[44:47], v[156:159], v[210:213], v[44:47]
	v_mfma_f32_16x16x32_bf16 v[40:43], v[164:167], v[210:213], v[40:43]
	v_mfma_f32_16x16x32_bf16 v[28:31], v[156:159], v[218:221], v[28:31]
	v_mfma_f32_16x16x32_bf16 v[24:27], v[164:167], v[218:221], v[24:27]
	v_mfma_f32_16x16x32_bf16 v[12:15], v[156:159], v[226:229], v[12:15]
	v_mfma_f32_16x16x32_bf16 v[8:11], v[164:167], v[226:229], v[8:11]
	v_mfma_f32_16x16x32_bf16 v[52:55], v[168:171], v[184:187], v[52:55]
	v_mfma_f32_16x16x32_bf16 v[48:51], v[176:179], v[184:187], v[48:51]
	v_mfma_f32_16x16x32_bf16 v[36:39], v[168:171], v[206:209], v[36:39]
	v_mfma_f32_16x16x32_bf16 v[32:35], v[176:179], v[206:209], v[32:35]
	v_mfma_f32_16x16x32_bf16 v[20:23], v[168:171], v[214:217], v[20:23]
	v_mfma_f32_16x16x32_bf16 v[16:19], v[176:179], v[214:217], v[16:19]
	v_mfma_f32_16x16x32_bf16 v[4:7], v[168:171], v[222:225], v[4:7]
	v_mfma_f32_16x16x32_bf16 v[0:3], v[176:179], v[222:225], v[0:3]
	v_mfma_f32_16x16x32_bf16 v[52:55], v[172:175], v[188:191], v[52:55]
	v_mfma_f32_16x16x32_bf16 v[48:51], v[180:183], v[188:191], v[48:51]
	v_mfma_f32_16x16x32_bf16 v[36:39], v[172:175], v[210:213], v[36:39]
	v_mfma_f32_16x16x32_bf16 v[32:35], v[180:183], v[210:213], v[32:35]
	v_mfma_f32_16x16x32_bf16 v[20:23], v[172:175], v[218:221], v[20:23]
	v_mfma_f32_16x16x32_bf16 v[16:19], v[180:183], v[218:221], v[16:19]
	v_mfma_f32_16x16x32_bf16 v[4:7], v[172:175], v[226:229], v[4:7]
	v_mfma_f32_16x16x32_bf16 v[0:3], v[180:183], v[226:229], v[0:3]
	s_barrier
	s_add_i32 s36, 0, 0x18000
	s_add_i32 s37, 0, 0x1c000
	v_add_u32_e32 v164, s36, v141
	v_add_u32_e32 v180, s37, v141
	ds_read_b128 v[144:147], v164
	ds_read_b128 v[156:159], v164 offset:1024
	ds_read_b128 v[160:163], v164 offset:2048
	ds_read_b128 v[164:167], v164 offset:3072
	ds_read_b128 v[168:171], v180
	ds_read_b128 v[172:175], v180 offset:1024
	ds_read_b128 v[176:179], v180 offset:2048
	ds_read_b128 v[180:183], v180 offset:3072
	s_add_u32 s64, s64, 0x20000
	s_addc_u32 s65, s65, 0
	s_mov_b32 m0, s39
	v_lshl_add_u64 v[232:233], s[64:65], 0, v[132:133]
	ds_read_b128 v[184:187], v143 offset:32768
	ds_read_b128 v[188:191], v143 offset:33792
	ds_read_b128 v[206:209], v143 offset:34816
	ds_read_b128 v[210:213], v143 offset:35840
	ds_read_b128 v[214:217], v143 offset:36864
	ds_read_b128 v[218:221], v143 offset:37888
	ds_read_b128 v[222:225], v143 offset:38912
	ds_read_b128 v[226:229], v143 offset:39936
	global_load_lds_dwordx4 v[232:233], off
	v_lshl_add_u64 v[232:233], s[64:65], 0, v[130:131]
	s_mov_b32 m0, s59
	s_nop 0
	global_load_lds_dwordx4 v[232:233], off
	s_waitcnt vmcnt(8)
	s_waitcnt lgkmcnt(0)
	s_barrier
; #define PG8_STAGE(bufoff, gbase, voff) do { _Pragma("unroll") for (int _i = 0; _i < 2; ++_i) \
;         __builtin_amdgcn_global_load_lds((const unsigned*)((const char*)(gbase) + (voff)[_i]), (PG8_LAS unsigned*)(lds + (bufoff) + ldsw + _i * 8192), 16, 0, 0); } while (0)
; #define PG8_LDA(dst, b, h) do { _Pragma("unroll") for (int m = 0; m < 4; ++m) _Pragma("unroll") for (int k = 0; k < 2; ++k) dst[m][k] = *(const PG8_LAS bf16x8*)(lds + PG8_SA(b, h) + aoff + m * 2048 + k * 1024); } while (0)
; #define PG8_MMA(ai, bj, At, Bt) do { __builtin_amdgcn_s_setprio(1); _Pragma("unroll") for (int m = 0; m < 4; ++m) _Pragma("unroll") for (int n = 0; n < 2; ++n) _Pragma("unroll") for (int k = 0; k < 2; ++k) \
;         acc[ai][bj][m][n] = __builtin_amdgcn_mfma_f32_16x16x32_bf16(Bt[n][k], At[m][k], acc[ai][bj][m][n], 0, 0, 0); __builtin_amdgcn_s_setprio(0); } while (0)
; #define PG8_WAIT_V(n) asm volatile("s_waitcnt vmcnt(" #n ")" ::: "memory")
; #define PG8_WAIT_L(n) asm volatile("s_waitcnt lgkmcnt(" #n ")" ::: "memory")
; #define PG8_BAR __builtin_amdgcn_s_barrier()
; #define PG8_SCHED __builtin_amdgcn_sched_barrier(0)
; template <class Epi, class Sched, bool ALIGN_EPI = false, bool SP2 = false>
; __device__ __forceinline__ void gemm_phase(PG8_LAS unsigned char* lds, const Gemm g, const Sched& S, const Epi& E, int wave_s) {
;     ...
;             PG8_WAIT_V(8); PG8_WAIT_L(0); PG8_BAR; PG8_MMA(0, 0, At, B0); PG8_MMA(0, 1, At, B1); PG8_BAR; PG8_SCHED;
;             PG8_LDA(At, 1, 1); PG8_STAGE(PG8_SB(1, 0), b3, voffB); PG8_STAGE(PG8_SB(1, 1), b3 + hstep, voffB); PG8_STAGE(PG8_SA(1, 0), a3, voffA);
;             PG8_WAIT_V(8); PG8_WAIT_L(0); PG8_BAR; PG8_MMA(1, 0, At, B0); PG8_MMA(1, 1, At, B1); PG8_BAR; PG8_SCHED;
	s_waitcnt lgkmcnt(0)
	v_mfma_f32_16x16x32_bf16 v[124:127], v[144:147], v[184:187], v[124:127]
	v_mfma_f32_16x16x32_bf16 v[120:123], v[160:163], v[184:187], v[120:123]
	v_mfma_f32_16x16x32_bf16 v[108:111], v[144:147], v[206:209], v[108:111]
	v_mfma_f32_16x16x32_bf16 v[104:107], v[160:163], v[206:209], v[104:107]
	v_mfma_f32_16x16x32_bf16 v[92:95], v[144:147], v[214:217], v[92:95]
	v_mfma_f32_16x16x32_bf16 v[88:91], v[160:163], v[214:217], v[88:91]
	v_mfma_f32_16x16x32_bf16 v[76:79], v[144:147], v[222:225], v[76:79]
	v_mfma_f32_16x16x32_bf16 v[72:75], v[160:163], v[222:225], v[72:75]
	v_mfma_f32_16x16x32_bf16 v[124:127], v[156:159], v[188:191], v[124:127]
	v_mfma_f32_16x16x32_bf16 v[120:123], v[164:167], v[188:191], v[120:123]
	v_mfma_f32_16x16x32_bf16 v[108:111], v[156:159], v[210:213], v[108:111]
	v_mfma_f32_16x16x32_bf16 v[104:107], v[164:167], v[210:213], v[104:107]
	v_mfma_f32_16x16x32_bf16 v[92:95], v[156:159], v[218:221], v[92:95]
	v_mfma_f32_16x16x32_bf16 v[88:91], v[164:167], v[218:221], v[88:91]
	v_mfma_f32_16x16x32_bf16 v[76:79], v[156:159], v[226:229], v[76:79]
	v_mfma_f32_16x16x32_bf16 v[72:75], v[164:167], v[226:229], v[72:75]
	v_mfma_f32_16x16x32_bf16 v[116:119], v[168:171], v[184:187], v[116:119]
	v_mfma_f32_16x16x32_bf16 v[112:115], v[176:179], v[184:187], v[112:115]
	v_mfma_f32_16x16x32_bf16 v[100:103], v[168:171], v[206:209], v[100:103]
	v_mfma_f32_16x16x32_bf16 v[96:99], v[176:179], v[206:209], v[96:99]
	v_mfma_f32_16x16x32_bf16 v[84:87], v[168:171], v[214:217], v[84:87]
	v_mfma_f32_16x16x32_bf16 v[80:83], v[176:179], v[214:217], v[80:83]
	v_mfma_f32_16x16x32_bf16 v[68:71], v[168:171], v[222:225], v[68:71]
	v_mfma_f32_16x16x32_bf16 v[64:67], v[176:179], v[222:225], v[64:67]
	v_mfma_f32_16x16x32_bf16 v[116:119], v[172:175], v[188:191], v[116:119]
	v_mfma_f32_16x16x32_bf16 v[112:115], v[180:183], v[188:191], v[112:115]
	v_mfma_f32_16x16x32_bf16 v[100:103], v[172:175], v[210:213], v[100:103]
	v_mfma_f32_16x16x32_bf16 v[96:99], v[180:183], v[210:213], v[96:99]
	v_mfma_f32_16x16x32_bf16 v[84:87], v[172:175], v[218:221], v[84:87]
	v_mfma_f32_16x16x32_bf16 v[80:83], v[180:183], v[218:221], v[80:83]
	v_mfma_f32_16x16x32_bf16 v[68:71], v[172:175], v[226:229], v[68:71]
	v_mfma_f32_16x16x32_bf16 v[64:67], v[180:183], v[226:229], v[64:67]
	s_barrier
	s_add_i32 s36, s36, s21
	v_lshl_add_u64 v[138:139], v[138:139], 0, s[34:35]
	s_mov_b32 m0, s36
	ds_read_b128 v[184:187], v143 offset:49152
	ds_read_b128 v[188:191], v143 offset:50176
	ds_read_b128 v[206:209], v143 offset:51200
	ds_read_b128 v[210:213], v143 offset:52224
	ds_read_b128 v[214:217], v143 offset:53248
	ds_read_b128 v[218:221], v143 offset:54272
	ds_read_b128 v[222:225], v143 offset:55296
	ds_read_b128 v[226:229], v143 offset:56320
	global_load_lds_dwordx4 v[138:139], off
	s_add_i32 m0, s36, 0x2000
	s_add_u32 s62, s62, 0x20080
	v_lshl_add_u64 v[138:139], v[150:151], 0, s[34:35]
	s_addc_u32 s63, s63, 0
	s_add_i32 s36, s37, s21
	global_load_lds_dwordx4 v[138:139], off
	v_lshl_add_u64 v[138:139], s[62:63], 0, v[148:149]
	s_mov_b32 m0, s36
	s_nop 0
	global_load_lds_dwordx4 v[138:139], off
	v_lshl_add_u64 v[138:139], s[62:63], 0, v[128:129]
	s_add_i32 m0, s36, 0x2000
	s_nop 0
	global_load_lds_dwordx4 v[138:139], off
	v_lshl_add_u64 v[138:139], v[152:153], 0, s[34:35]
	s_mov_b32 m0, s66
	s_nop 0
	global_load_lds_dwordx4 v[138:139], off
	v_lshl_add_u64 v[138:139], v[230:231], 0, s[34:35]
	s_mov_b32 m0, s67
	s_nop 0
	global_load_lds_dwordx4 v[138:139], off
	s_waitcnt vmcnt(8)
	s_waitcnt lgkmcnt(0)
	s_barrier
	s_waitcnt lgkmcnt(0)
	v_mfma_f32_16x16x32_bf16 v[60:63], v[144:147], v[184:187], v[60:63]
	v_mfma_f32_16x16x32_bf16 v[56:59], v[160:163], v[184:187], v[56:59]
	v_mfma_f32_16x16x32_bf16 v[44:47], v[144:147], v[206:209], v[44:47]
	v_mfma_f32_16x16x32_bf16 v[40:43], v[160:163], v[206:209], v[40:43]
	v_mfma_f32_16x16x32_bf16 v[28:31], v[144:147], v[214:217], v[28:31]
	v_mfma_f32_16x16x32_bf16 v[24:27], v[160:163], v[214:217], v[24:27]
	v_mfma_f32_16x16x32_bf16 v[12:15], v[144:147], v[222:225], v[12:15]
	v_mfma_f32_16x16x32_bf16 v[8:11], v[160:163], v[222:225], v[8:11]
	v_mfma_f32_16x16x32_bf16 v[60:63], v[156:159], v[188:191], v[60:63]
	v_mfma_f32_16x16x32_bf16 v[56:59], v[164:167], v[188:191], v[56:59]
	v_mfma_f32_16x16x32_bf16 v[44:47], v[156:159], v[210:213], v[44:47]
	v_mfma_f32_16x16x32_bf16 v[40:43], v[164:167], v[210:213], v[40:43]
	v_mfma_f32_16x16x32_bf16 v[28:31], v[156:159], v[218:221], v[28:31]
	v_mfma_f32_16x16x32_bf16 v[24:27], v[164:167], v[218:221], v[24:27]
	v_mfma_f32_16x16x32_bf16 v[12:15], v[156:159], v[226:229], v[12:15]
	v_mfma_f32_16x16x32_bf16 v[8:11], v[164:167], v[226:229], v[8:11]
	v_mfma_f32_16x16x32_bf16 v[52:55], v[168:171], v[184:187], v[52:55]
	v_mfma_f32_16x16x32_bf16 v[48:51], v[176:179], v[184:187], v[48:51]
	v_mfma_f32_16x16x32_bf16 v[36:39], v[168:171], v[206:209], v[36:39]
	v_mfma_f32_16x16x32_bf16 v[32:35], v[176:179], v[206:209], v[32:35]
	v_mfma_f32_16x16x32_bf16 v[20:23], v[168:171], v[214:217], v[20:23]
	v_mfma_f32_16x16x32_bf16 v[16:19], v[176:179], v[214:217], v[16:19]
	v_mfma_f32_16x16x32_bf16 v[4:7], v[168:171], v[222:225], v[4:7]
	v_mfma_f32_16x16x32_bf16 v[0:3], v[176:179], v[222:225], v[0:3]
	v_mfma_f32_16x16x32_bf16 v[52:55], v[172:175], v[188:191], v[52:55]
	v_mfma_f32_16x16x32_bf16 v[48:51], v[180:183], v[188:191], v[48:51]
	v_mfma_f32_16x16x32_bf16 v[36:39], v[172:175], v[210:213], v[36:39]
	v_mfma_f32_16x16x32_bf16 v[32:35], v[180:183], v[210:213], v[32:35]
	v_mfma_f32_16x16x32_bf16 v[20:23], v[172:175], v[218:221], v[20:23]
	v_mfma_f32_16x16x32_bf16 v[16:19], v[180:183], v[218:221], v[16:19]
	v_mfma_f32_16x16x32_bf16 v[4:7], v[172:175], v[226:229], v[4:7]
	v_mfma_f32_16x16x32_bf16 v[0:3], v[180:183], v[226:229], v[0:3]
	s_barrier
	s_add_i32 s74, s74, 2
	s_add_u32 s60, s60, 0x100
	s_addc_u32 s61, s61, 0
	s_add_u32 s49, s49, 0x100
	s_addc_u32 s53, s53, 0
	s_cmp_gt_u32 s74, 5
	s_cbranch_scc0 .LBB0_387
	s_setprio 0
	s_and_b64 vcc, exec, s[46:47]
	s_cbranch_vccz .LBB0_390
	s_barrier

; #define PG8_STAGE(bufoff, gbase, voff) do { _Pragma("unroll") for (int _i = 0; _i < 2; ++_i) \
;         __builtin_amdgcn_global_load_lds((const unsigned*)((const char*)(gbase) + (voff)[_i]), (PG8_LAS unsigned*)(lds + (bufoff) + ldsw + _i * 8192), 16, 0, 0); } while (0)
; #define PG8_LDA(dst, b, h) do { _Pragma("unroll") for (int m = 0; m < 4; ++m) _Pragma("unroll") for (int k = 0; k < 2; ++k) dst[m][k] = *(const PG8_LAS bf16x8*)(lds + PG8_SA(b, h) + aoff + m * 2048 + k * 1024); } while (0)
; #define PG8_WAIT_V(n) asm volatile("s_waitcnt vmcnt(" #n ")" ::: "memory")
; #define PG8_BAR __builtin_amdgcn_s_barrier()
; template <class Epi, class Sched, bool ALIGN_EPI = false, bool SP2 = false>
; __device__ __forceinline__ void gemm_phase(PG8_LAS unsigned char* lds, const Gemm g, const Sched& S, const Epi& E, int wave_s) {
;     ...
;         const bool has_next = S.next(ui + 1, nxt);
;         const char* nA = has_next ? (const char*)g.A + (size_t)nxt.pm * tstep : cA; const char* nB = has_next ? (const char*)g.Bt + (size_t)nxt.pn * tstep : cB;
;         for (int t = 0; t < nt; t += 2) {
;             const bool last = (t == nt - 2);
;             const char* a1 = cA + (size_t)(t + 1) * kstep;
;             const char* a2 = last ? nA : cA + (size_t)(t + 2) * kstep; const char* b2 = last ? nB : cB + (size_t)(t + 2) * kstep;
;             const char* a3 = a2 + kstep; const char* b3 = b2 + kstep;
;             if (last && has_next) S.a_ready(nxt);
;             if constexpr (SP2) {
;             PG8_LDB(B0, 0, 0); PG8_LDB(B1, 0, 1); PG8_SCHED; PG8_LDA(At, 0, 0); PG8_STAGE(PG8_SA(1, 1), a1 + hstep, voffA);
;             PG8_WAIT_V(8); PG8_WAIT_L(0); PG8_BAR; PG8_MMA(0, 0, At, B0); PG8_MMA(0, 1, At, B1); PG8_BAR; PG8_SCHED;
;             PG8_LDA(At, 0, 1); PG8_STAGE(PG8_SB(0, 0), b2, voffB); PG8_STAGE(PG8_SB(0, 1), b2 + hstep, voffB); PG8_STAGE(PG8_SA(0, 0), a2, voffA);
;             PG8_WAIT_V(8); PG8_WAIT_L(0); PG8_BAR; PG8_MMA(1, 0, At, B0); PG8_MMA(1, 1, At, B1); PG8_BAR; PG8_SCHED;
;     ...
;         { float zf_ = 0.f; asm volatile("" : "+v"(zf_)); const f32x4 zero4_ = {zf_, zf_, zf_, zf_};
; #pragma unroll
;         for (int a = 0; a < 2; ++a)
; #pragma unroll
;             for (int b = 0; b < 2; ++b)
; #pragma unroll
;                 for (int m = 0; m < 4; ++m)
; #pragma unroll
;                     for (int n = 0; n < 2; ++n) acc[a][b][m][n] = zero4_; }
.LBB0_406:
	s_ashr_i32 s55, s54, 31
	s_lshl_b64 s[22:23], s[54:55], 17
	s_add_u32 s56, s21, s22
	s_addc_u32 s57, s73, s23
	s_and_b64 s[22:23], s[40:41], exec
	s_cselect_b32 s29, s57, s65
	s_cselect_b32 s55, s56, s64
	s_ashr_i32 s53, s52, 31
	s_lshl_b64 s[22:23], s[52:53], 17
	s_add_u32 s58, s18, s22
	s_addc_u32 s59, s19, s23
	s_and_b64 s[22:23], s[40:41], exec
	v_mov_b64_e32 v[6:7], v[2:3]
	v_mov_b64_e32 v[18:19], v[2:3]
	v_mov_b64_e32 v[22:23], v[2:3]
	v_mov_b64_e32 v[34:35], v[2:3]
	v_mov_b64_e32 v[38:39], v[2:3]
	v_mov_b64_e32 v[50:51], v[2:3]
	v_mov_b64_e32 v[54:55], v[2:3]
	v_mov_b64_e32 v[10:11], v[2:3]
	v_mov_b64_e32 v[14:15], v[2:3]
	v_mov_b64_e32 v[26:27], v[2:3]
	v_mov_b64_e32 v[30:31], v[2:3]
	v_mov_b64_e32 v[42:43], v[2:3]
	v_mov_b64_e32 v[46:47], v[2:3]
	v_mov_b64_e32 v[58:59], v[2:3]
	v_mov_b64_e32 v[62:63], v[2:3]
	v_mov_b64_e32 v[66:67], v[2:3]
	v_mov_b64_e32 v[70:71], v[2:3]
	v_mov_b64_e32 v[82:83], v[2:3]
	v_mov_b64_e32 v[86:87], v[2:3]
	v_mov_b64_e32 v[98:99], v[2:3]
	v_mov_b64_e32 v[102:103], v[2:3]
	v_mov_b64_e32 v[114:115], v[2:3]
	v_mov_b64_e32 v[118:119], v[2:3]
	v_mov_b64_e32 v[74:75], v[2:3]
	v_mov_b64_e32 v[78:79], v[2:3]
	v_mov_b64_e32 v[90:91], v[2:3]
	v_mov_b64_e32 v[94:95], v[2:3]
	v_mov_b64_e32 v[106:107], v[2:3]
	v_mov_b64_e32 v[110:111], v[2:3]
	v_mov_b64_e32 v[122:123], v[2:3]
	v_mov_b64_e32 v[126:127], v[2:3]
	s_mov_b32 s42, s97
	s_mov_b32 s1, s89
	s_mov_b32 s0, s87
	s_cselect_b32 s53, s59, s63
	s_cselect_b32 s5, s58, s62
	s_mov_b32 s74, 0
	s_mov_b64 s[66:67], -1
	s_mov_b64 s[24:25], 0
	v_mov_b64_e32 v[4:5], v[0:1]
	v_mov_b64_e32 v[16:17], v[0:1]
	v_mov_b64_e32 v[20:21], v[0:1]
	v_mov_b64_e32 v[32:33], v[0:1]
	v_mov_b64_e32 v[36:37], v[0:1]
	v_mov_b64_e32 v[48:49], v[0:1]
	v_mov_b64_e32 v[52:53], v[0:1]
	v_mov_b64_e32 v[8:9], v[0:1]
	v_mov_b64_e32 v[12:13], v[0:1]
	v_mov_b64_e32 v[24:25], v[0:1]
	v_mov_b64_e32 v[28:29], v[0:1]
	v_mov_b64_e32 v[40:41], v[0:1]
	v_mov_b64_e32 v[44:45], v[0:1]
	v_mov_b64_e32 v[56:57], v[0:1]
	v_mov_b64_e32 v[60:61], v[0:1]
	v_mov_b64_e32 v[64:65], v[0:1]
	v_mov_b64_e32 v[68:69], v[0:1]
	v_mov_b64_e32 v[80:81], v[0:1]
	v_mov_b64_e32 v[84:85], v[0:1]
	v_mov_b64_e32 v[96:97], v[0:1]
	v_mov_b64_e32 v[100:101], v[0:1]
	v_mov_b64_e32 v[112:113], v[0:1]
	v_mov_b64_e32 v[116:117], v[0:1]
	v_mov_b64_e32 v[72:73], v[0:1]
	v_mov_b64_e32 v[76:77], v[0:1]
	v_mov_b64_e32 v[88:89], v[0:1]
	v_mov_b64_e32 v[92:93], v[0:1]
	v_mov_b64_e32 v[104:105], v[0:1]
	v_mov_b64_e32 v[108:109], v[0:1]
	v_mov_b64_e32 v[120:121], v[0:1]
	v_mov_b64_e32 v[124:125], v[0:1]
	v_readlane_b32 vcc_lo, v253, 14
	s_nop 3
	s_cmp_eq_u32 vcc_lo, 0
	s_cbranch_scc1 .Lgprio_6
	s_setprio 1
.Lgprio_6:
.LBB0_407:
	s_add_u32 s36, s64, s74
	s_addc_u32 s37, s65, 0
	s_add_u32 s75, s36, 0x100
	s_addc_u32 s78, s37, 0
	s_and_b64 s[22:23], s[24:25], exec
	s_cselect_b32 s23, s29, s78
	s_cselect_b32 s22, s55, s75
	s_add_u32 s74, s62, s74
	s_addc_u32 s75, s63, 0
	s_add_u32 s74, s74, 0x100
	s_addc_u32 s75, s75, 0
	s_add_i32 s81, 0, 0x10000
	s_and_b64 s[24:25], s[24:25], exec
	s_cselect_b32 s25, s53, s75
	s_cselect_b32 s24, s5, s74
	s_add_i32 s75, 0, 0x14000
	s_add_u32 s36, s36, 0x10080
	s_addc_u32 s37, s37, 0
	s_add_i32 s51, s81, s76
	s_add_i32 m0, s26, 0xc000
	s_add_i32 s61, s26, 0xe000
	s_add_i32 s3, s51, 0x2000
	v_add_u32_e32 v134, s81, v137
	s_add_u32 s78, s24, 0x10000
	ds_read_b128 v[140:143], v134
	ds_read_b128 v[144:147], v134 offset:1024
	ds_read_b128 v[156:159], v134 offset:2048
	ds_read_b128 v[160:163], v134 offset:3072
	v_add_u32_e32 v134, s75, v137
	s_addc_u32 s79, s25, 0
	s_add_i32 s7, s75, s76
	ds_read_b128 v[164:167], v134
	ds_read_b128 v[168:171], v134 offset:1024
	ds_read_b128 v[172:175], v134 offset:2048
	ds_read_b128 v[176:179], v134 offset:3072
	s_add_i32 s9, s7, 0x2000
	s_add_i32 s87, 0, 0x18000
	s_add_i32 s47, 0, 0x1c000
	s_add_u32 vcc_lo, s22, 0x10000
	s_addc_u32 vcc_hi, s23, 0
	s_add_i32 s97, s87, s76
	s_add_i32 s46, s97, 0x2000
	s_add_u32 s74, s24, 0x10080
	s_addc_u32 s75, s25, 0
	s_add_i32 s89, s47, s76
	s_add_i32 s81, s89, 0x2000
	v_lshl_add_u64 v[134:135], s[36:37], 0, v[132:133]
	ds_read_b128 v[180:183], v139
	ds_read_b128 v[184:187], v139 offset:1024
	ds_read_b128 v[188:191], v139 offset:2048
	ds_read_b128 v[206:209], v139 offset:3072
	ds_read_b128 v[210:213], v139 offset:4096
	ds_read_b128 v[214:217], v139 offset:5120
	ds_read_b128 v[218:221], v139 offset:6144
	ds_read_b128 v[222:225], v139 offset:7168
	global_load_lds_dwordx4 v[134:135], off
	v_lshl_add_u64 v[134:135], s[36:37], 0, v[130:131]
	s_mov_b32 m0, s61
	s_nop 0
	global_load_lds_dwordx4 v[134:135], off
	s_waitcnt vmcnt(8)
	s_waitcnt lgkmcnt(0)
	s_barrier
; #define PG8_STAGE(bufoff, gbase, voff) do { _Pragma("unroll") for (int _i = 0; _i < 2; ++_i) \
;         __builtin_amdgcn_global_load_lds((const unsigned*)((const char*)(gbase) + (voff)[_i]), (PG8_LAS unsigned*)(lds + (bufoff) + ldsw + _i * 8192), 16, 0, 0); } while (0)
; #define PG8_LDA(dst, b, h) do { _Pragma("unroll") for (int m = 0; m < 4; ++m) _Pragma("unroll") for (int k = 0; k < 2; ++k) dst[m][k] = *(const PG8_LAS bf16x8*)(lds + PG8_SA(b, h) + aoff + m * 2048 + k * 1024); } while (0)
; #define PG8_LDB(dst, b, h) do { _Pragma("unroll") for (int n = 0; n < 2; ++n) _Pragma("unroll") for (int k = 0; k < 2; ++k) dst[n][k] = *(const PG8_LAS bf16x8*)(lds + PG8_SB(b, h) + boff + n * 2048 + k * 1024); } while (0)
; #define PG8_MMA(ai, bj, At, Bt) do { __builtin_amdgcn_s_setprio(1); _Pragma("unroll") for (int m = 0; m < 4; ++m) _Pragma("unroll") for (int n = 0; n < 2; ++n) _Pragma("unroll") for (int k = 0; k < 2; ++k) \
;         acc[ai][bj][m][n] = __builtin_amdgcn_mfma_f32_16x16x32_bf16(Bt[n][k], At[m][k], acc[ai][bj][m][n], 0, 0, 0); __builtin_amdgcn_s_setprio(0); } while (0)
; #define PG8_WAIT_V(n) asm volatile("s_waitcnt vmcnt(" #n ")" ::: "memory")
; #define PG8_WAIT_L(n) asm volatile("s_waitcnt lgkmcnt(" #n ")" ::: "memory")
; #define PG8_BAR __builtin_amdgcn_s_barrier()
; #define PG8_SCHED __builtin_amdgcn_sched_barrier(0)
; template <class Epi, class Sched, bool ALIGN_EPI = false, bool SP2 = false>
; __device__ __forceinline__ void gemm_phase(PG8_LAS unsigned char* lds, const Gemm g, const Sched& S, const Epi& E, int wave_s) {
;     ...
;             PG8_WAIT_V(8); PG8_WAIT_L(0); PG8_BAR; PG8_MMA(0, 0, At, B0); PG8_MMA(0, 1, At, B1); PG8_BAR; PG8_SCHED;
;             PG8_LDA(At, 0, 1); PG8_STAGE(PG8_SB(0, 0), b2, voffB); PG8_STAGE(PG8_SB(0, 1), b2 + hstep, voffB); PG8_STAGE(PG8_SA(0, 0), a2, voffA);
;             PG8_WAIT_V(8); PG8_WAIT_L(0); PG8_BAR; PG8_MMA(1, 0, At, B0); PG8_MMA(1, 1, At, B1); PG8_BAR; PG8_SCHED;
;             PG8_LDB(B0, 1, 0); PG8_LDB(B1, 1, 1); PG8_SCHED; PG8_LDA(At, 1, 0); PG8_STAGE(PG8_SA(0, 1), a2 + hstep, voffA);
	s_waitcnt lgkmcnt(0)
	v_mfma_f32_16x16x32_bf16 v[124:127], v[140:143], v[180:183], v[124:127]
	v_mfma_f32_16x16x32_bf16 v[120:123], v[156:159], v[180:183], v[120:123]
	v_mfma_f32_16x16x32_bf16 v[108:111], v[140:143], v[188:191], v[108:111]
	v_mfma_f32_16x16x32_bf16 v[104:107], v[156:159], v[188:191], v[104:107]
	v_mfma_f32_16x16x32_bf16 v[92:95], v[140:143], v[210:213], v[92:95]
	v_mfma_f32_16x16x32_bf16 v[88:91], v[156:159], v[210:213], v[88:91]
	v_mfma_f32_16x16x32_bf16 v[76:79], v[140:143], v[218:221], v[76:79]
	v_mfma_f32_16x16x32_bf16 v[72:75], v[156:159], v[218:221], v[72:75]
	v_mfma_f32_16x16x32_bf16 v[124:127], v[144:147], v[184:187], v[124:127]
	v_mfma_f32_16x16x32_bf16 v[120:123], v[160:163], v[184:187], v[120:123]
	v_mfma_f32_16x16x32_bf16 v[108:111], v[144:147], v[206:209], v[108:111]
	v_mfma_f32_16x16x32_bf16 v[104:107], v[160:163], v[206:209], v[104:107]
	v_mfma_f32_16x16x32_bf16 v[92:95], v[144:147], v[214:217], v[92:95]
	v_mfma_f32_16x16x32_bf16 v[88:91], v[160:163], v[214:217], v[88:91]
	v_mfma_f32_16x16x32_bf16 v[76:79], v[144:147], v[222:225], v[76:79]
	v_mfma_f32_16x16x32_bf16 v[72:75], v[160:163], v[222:225], v[72:75]
	v_mfma_f32_16x16x32_bf16 v[116:119], v[164:167], v[180:183], v[116:119]
	v_mfma_f32_16x16x32_bf16 v[112:115], v[172:175], v[180:183], v[112:115]
	v_mfma_f32_16x16x32_bf16 v[100:103], v[164:167], v[188:191], v[100:103]
	v_mfma_f32_16x16x32_bf16 v[96:99], v[172:175], v[188:191], v[96:99]
	v_mfma_f32_16x16x32_bf16 v[84:87], v[164:167], v[210:213], v[84:87]
	v_mfma_f32_16x16x32_bf16 v[80:83], v[172:175], v[210:213], v[80:83]
	v_mfma_f32_16x16x32_bf16 v[68:71], v[164:167], v[218:221], v[68:71]
	v_mfma_f32_16x16x32_bf16 v[64:67], v[172:175], v[218:221], v[64:67]
	v_mfma_f32_16x16x32_bf16 v[116:119], v[168:171], v[184:187], v[116:119]
	v_mfma_f32_16x16x32_bf16 v[112:115], v[176:179], v[184:187], v[112:115]
	v_mfma_f32_16x16x32_bf16 v[100:103], v[168:171], v[206:209], v[100:103]
	v_mfma_f32_16x16x32_bf16 v[96:99], v[176:179], v[206:209], v[96:99]
	v_mfma_f32_16x16x32_bf16 v[84:87], v[168:171], v[214:217], v[84:87]
	v_mfma_f32_16x16x32_bf16 v[80:83], v[176:179], v[214:217], v[80:83]
	v_mfma_f32_16x16x32_bf16 v[68:71], v[168:171], v[222:225], v[68:71]
	v_mfma_f32_16x16x32_bf16 v[64:67], v[176:179], v[222:225], v[64:67]
	s_barrier
	s_mov_b32 m0, s51
	v_lshl_add_u64 v[134:135], s[24:25], 0, v[148:149]
	ds_read_b128 v[180:183], v139 offset:16384
	ds_read_b128 v[184:187], v139 offset:17408
	ds_read_b128 v[188:191], v139 offset:18432
	ds_read_b128 v[206:209], v139 offset:19456
	ds_read_b128 v[210:213], v139 offset:20480
	ds_read_b128 v[214:217], v139 offset:21504
	ds_read_b128 v[218:221], v139 offset:22528
	ds_read_b128 v[222:225], v139 offset:23552
	global_load_lds_dwordx4 v[134:135], off
	v_lshl_add_u64 v[150:151], s[24:25], 0, v[128:129]
	s_mov_b32 m0, s3
	v_lshl_add_u64 v[152:153], s[78:79], 0, v[148:149]
	global_load_lds_dwordx4 v[150:151], off
	s_mov_b32 m0, s7
	v_lshl_add_u64 v[226:227], s[22:23], 0, v[130:131]
	global_load_lds_dwordx4 v[152:153], off
	v_lshl_add_u64 v[152:153], s[78:79], 0, v[128:129]
	s_mov_b32 m0, s9
	s_nop 0
	global_load_lds_dwordx4 v[152:153], off
	v_lshl_add_u64 v[152:153], s[22:23], 0, v[132:133]
	s_mov_b32 m0, s26
	s_nop 0
	global_load_lds_dwordx4 v[152:153], off
	s_mov_b32 m0, s38
	s_nop 0
	global_load_lds_dwordx4 v[226:227], off
	s_waitcnt vmcnt(8)
	s_waitcnt lgkmcnt(0)
	s_barrier
	s_waitcnt lgkmcnt(0)
	v_mfma_f32_16x16x32_bf16 v[60:63], v[140:143], v[180:183], v[60:63]
	v_mfma_f32_16x16x32_bf16 v[56:59], v[156:159], v[180:183], v[56:59]
	v_mfma_f32_16x16x32_bf16 v[44:47], v[140:143], v[188:191], v[44:47]
	v_mfma_f32_16x16x32_bf16 v[40:43], v[156:159], v[188:191], v[40:43]
	v_mfma_f32_16x16x32_bf16 v[28:31], v[140:143], v[210:213], v[28:31]
	v_mfma_f32_16x16x32_bf16 v[24:27], v[156:159], v[210:213], v[24:27]
	v_mfma_f32_16x16x32_bf16 v[12:15], v[140:143], v[218:221], v[12:15]
	v_mfma_f32_16x16x32_bf16 v[8:11], v[156:159], v[218:221], v[8:11]
	v_mfma_f32_16x16x32_bf16 v[60:63], v[144:147], v[184:187], v[60:63]
	v_mfma_f32_16x16x32_bf16 v[56:59], v[160:163], v[184:187], v[56:59]
	v_mfma_f32_16x16x32_bf16 v[44:47], v[144:147], v[206:209], v[44:47]
	v_mfma_f32_16x16x32_bf16 v[40:43], v[160:163], v[206:209], v[40:43]
	v_mfma_f32_16x16x32_bf16 v[28:31], v[144:147], v[214:217], v[28:31]
	v_mfma_f32_16x16x32_bf16 v[24:27], v[160:163], v[214:217], v[24:27]
	v_mfma_f32_16x16x32_bf16 v[12:15], v[144:147], v[222:225], v[12:15]
	v_mfma_f32_16x16x32_bf16 v[8:11], v[160:163], v[222:225], v[8:11]
	v_mfma_f32_16x16x32_bf16 v[52:55], v[164:167], v[180:183], v[52:55]
	v_mfma_f32_16x16x32_bf16 v[48:51], v[172:175], v[180:183], v[48:51]
	v_mfma_f32_16x16x32_bf16 v[36:39], v[164:167], v[188:191], v[36:39]
	v_mfma_f32_16x16x32_bf16 v[32:35], v[172:175], v[188:191], v[32:35]
	v_mfma_f32_16x16x32_bf16 v[20:23], v[164:167], v[210:213], v[20:23]
	v_mfma_f32_16x16x32_bf16 v[16:19], v[172:175], v[210:213], v[16:19]
	v_mfma_f32_16x16x32_bf16 v[4:7], v[164:167], v[218:221], v[4:7]
	v_mfma_f32_16x16x32_bf16 v[0:3], v[172:175], v[218:221], v[0:3]
	v_mfma_f32_16x16x32_bf16 v[52:55], v[168:171], v[184:187], v[52:55]
	v_mfma_f32_16x16x32_bf16 v[48:51], v[176:179], v[184:187], v[48:51]
	v_mfma_f32_16x16x32_bf16 v[36:39], v[168:171], v[206:209], v[36:39]
	v_mfma_f32_16x16x32_bf16 v[32:35], v[176:179], v[206:209], v[32:35]
	v_mfma_f32_16x16x32_bf16 v[20:23], v[168:171], v[214:217], v[20:23]
	v_mfma_f32_16x16x32_bf16 v[16:19], v[176:179], v[214:217], v[16:19]
	v_mfma_f32_16x16x32_bf16 v[4:7], v[168:171], v[222:225], v[4:7]
	v_mfma_f32_16x16x32_bf16 v[0:3], v[176:179], v[222:225], v[0:3]
	s_barrier
; #define PG8_STAGE(bufoff, gbase, voff) do { _Pragma("unroll") for (int _i = 0; _i < 2; ++_i) \
;         __builtin_amdgcn_global_load_lds((const unsigned*)((const char*)(gbase) + (voff)[_i]), (PG8_LAS unsigned*)(lds + (bufoff) + ldsw + _i * 8192), 16, 0, 0); } while (0)
; #define PG8_LDA(dst, b, h) do { _Pragma("unroll") for (int m = 0; m < 4; ++m) _Pragma("unroll") for (int k = 0; k < 2; ++k) dst[m][k] = *(const PG8_LAS bf16x8*)(lds + PG8_SA(b, h) + aoff + m * 2048 + k * 1024); } while (0)
; #define PG8_LDB(dst, b, h) do { _Pragma("unroll") for (int n = 0; n < 2; ++n) _Pragma("unroll") for (int k = 0; k < 2; ++k) dst[n][k] = *(const PG8_LAS bf16x8*)(lds + PG8_SB(b, h) + boff + n * 2048 + k * 1024); } while (0)
; #define PG8_MMA(ai, bj, At, Bt) do { __builtin_amdgcn_s_setprio(1); _Pragma("unroll") for (int m = 0; m < 4; ++m) _Pragma("unroll") for (int n = 0; n < 2; ++n) _Pragma("unroll") for (int k = 0; k < 2; ++k) \
;         acc[ai][bj][m][n] = __builtin_amdgcn_mfma_f32_16x16x32_bf16(Bt[n][k], At[m][k], acc[ai][bj][m][n], 0, 0, 0); __builtin_amdgcn_s_setprio(0); } while (0)
; #define PG8_WAIT_V(n) asm volatile("s_waitcnt vmcnt(" #n ")" ::: "memory")
; #define PG8_WAIT_L(n) asm volatile("s_waitcnt lgkmcnt(" #n ")" ::: "memory")
; #define PG8_BAR __builtin_amdgcn_s_barrier()
; #define PG8_SCHED __builtin_amdgcn_sched_barrier(0)
; template <class Epi, class Sched, bool ALIGN_EPI = false, bool SP2 = false>
; __device__ __forceinline__ void gemm_phase(PG8_LAS unsigned char* lds, const Gemm g, const Sched& S, const Epi& E, int wave_s) {
;     ...
;             PG8_LDB(B0, 1, 0); PG8_LDB(B1, 1, 1); PG8_SCHED; PG8_LDA(At, 1, 0); PG8_STAGE(PG8_SA(0, 1), a2 + hstep, voffA);
;             PG8_WAIT_V(8); PG8_WAIT_L(0); PG8_BAR; PG8_MMA(0, 0, At, B0); PG8_MMA(0, 1, At, B1); PG8_BAR; PG8_SCHED;
;             PG8_LDA(At, 1, 1); PG8_STAGE(PG8_SB(1, 0), b3, voffB); PG8_STAGE(PG8_SB(1, 1), b3 + hstep, voffB); PG8_STAGE(PG8_SA(1, 0), a3, voffA);
;             PG8_WAIT_V(8); PG8_WAIT_L(0); PG8_BAR; PG8_MMA(1, 0, At, B0); PG8_MMA(1, 1, At, B1); PG8_BAR; PG8_SCHED;
	v_add_u32_e32 v160, s87, v137
	v_add_u32_e32 v176, s47, v137
	ds_read_b128 v[140:143], v160
	ds_read_b128 v[144:147], v160 offset:1024
	ds_read_b128 v[156:159], v160 offset:2048
	ds_read_b128 v[160:163], v160 offset:3072
	ds_read_b128 v[164:167], v176
	ds_read_b128 v[168:171], v176 offset:1024
	ds_read_b128 v[172:175], v176 offset:2048
	ds_read_b128 v[176:179], v176 offset:3072
	s_mov_b32 m0, s39
	v_lshl_add_u64 v[228:229], vcc, 0, v[132:133]
	ds_read_b128 v[180:183], v139 offset:32768
	ds_read_b128 v[184:187], v139 offset:33792
	ds_read_b128 v[188:191], v139 offset:34816
	ds_read_b128 v[206:209], v139 offset:35840
	ds_read_b128 v[210:213], v139 offset:36864
	ds_read_b128 v[214:217], v139 offset:37888
	ds_read_b128 v[218:221], v139 offset:38912
	ds_read_b128 v[222:225], v139 offset:39936
	global_load_lds_dwordx4 v[228:229], off
	v_lshl_add_u64 v[228:229], vcc, 0, v[130:131]
	s_mov_b32 m0, s84
	s_nop 0
	global_load_lds_dwordx4 v[228:229], off
	s_waitcnt vmcnt(8)
	s_waitcnt lgkmcnt(0)
	s_barrier
	s_waitcnt lgkmcnt(0)
	v_mfma_f32_16x16x32_bf16 v[124:127], v[140:143], v[180:183], v[124:127]
	v_mfma_f32_16x16x32_bf16 v[120:123], v[156:159], v[180:183], v[120:123]
	v_mfma_f32_16x16x32_bf16 v[108:111], v[140:143], v[188:191], v[108:111]
	v_mfma_f32_16x16x32_bf16 v[104:107], v[156:159], v[188:191], v[104:107]
	v_mfma_f32_16x16x32_bf16 v[92:95], v[140:143], v[210:213], v[92:95]
	v_mfma_f32_16x16x32_bf16 v[88:91], v[156:159], v[210:213], v[88:91]
	v_mfma_f32_16x16x32_bf16 v[76:79], v[140:143], v[218:221], v[76:79]
	v_mfma_f32_16x16x32_bf16 v[72:75], v[156:159], v[218:221], v[72:75]
	v_mfma_f32_16x16x32_bf16 v[124:127], v[144:147], v[184:187], v[124:127]
	v_mfma_f32_16x16x32_bf16 v[120:123], v[160:163], v[184:187], v[120:123]
	v_mfma_f32_16x16x32_bf16 v[108:111], v[144:147], v[206:209], v[108:111]
	v_mfma_f32_16x16x32_bf16 v[104:107], v[160:163], v[206:209], v[104:107]
	v_mfma_f32_16x16x32_bf16 v[92:95], v[144:147], v[214:217], v[92:95]
	v_mfma_f32_16x16x32_bf16 v[88:91], v[160:163], v[214:217], v[88:91]
	v_mfma_f32_16x16x32_bf16 v[76:79], v[144:147], v[222:225], v[76:79]
	v_mfma_f32_16x16x32_bf16 v[72:75], v[160:163], v[222:225], v[72:75]
	v_mfma_f32_16x16x32_bf16 v[116:119], v[164:167], v[180:183], v[116:119]
	v_mfma_f32_16x16x32_bf16 v[112:115], v[172:175], v[180:183], v[112:115]
	v_mfma_f32_16x16x32_bf16 v[100:103], v[164:167], v[188:191], v[100:103]
	v_mfma_f32_16x16x32_bf16 v[96:99], v[172:175], v[188:191], v[96:99]
	v_mfma_f32_16x16x32_bf16 v[84:87], v[164:167], v[210:213], v[84:87]
	v_mfma_f32_16x16x32_bf16 v[80:83], v[172:175], v[210:213], v[80:83]
	v_mfma_f32_16x16x32_bf16 v[68:71], v[164:167], v[218:221], v[68:71]
	v_mfma_f32_16x16x32_bf16 v[64:67], v[172:175], v[218:221], v[64:67]
	v_mfma_f32_16x16x32_bf16 v[116:119], v[168:171], v[184:187], v[116:119]
	v_mfma_f32_16x16x32_bf16 v[112:115], v[176:179], v[184:187], v[112:115]
	v_mfma_f32_16x16x32_bf16 v[100:103], v[168:171], v[206:209], v[100:103]
	v_mfma_f32_16x16x32_bf16 v[96:99], v[176:179], v[206:209], v[96:99]
	v_mfma_f32_16x16x32_bf16 v[84:87], v[168:171], v[214:217], v[84:87]
	v_mfma_f32_16x16x32_bf16 v[80:83], v[176:179], v[214:217], v[80:83]
	v_mfma_f32_16x16x32_bf16 v[68:71], v[168:171], v[222:225], v[68:71]
	v_mfma_f32_16x16x32_bf16 v[64:67], v[176:179], v[222:225], v[64:67]
	s_barrier
	s_mov_b32 m0, s97
	v_lshl_add_u64 v[134:135], v[134:135], 0, s[34:35]
	ds_read_b128 v[180:183], v139 offset:49152
	ds_read_b128 v[184:187], v139 offset:50176
	ds_read_b128 v[188:191], v139 offset:51200
	ds_read_b128 v[206:209], v139 offset:52224
	ds_read_b128 v[210:213], v139 offset:53248
	ds_read_b128 v[214:217], v139 offset:54272
	ds_read_b128 v[218:221], v139 offset:55296
	ds_read_b128 v[222:225], v139 offset:56320
	global_load_lds_dwordx4 v[134:135], off
	v_lshl_add_u64 v[134:135], v[150:151], 0, s[34:35]
	s_mov_b32 m0, s46
	s_nop 0
	global_load_lds_dwordx4 v[134:135], off
	v_lshl_add_u64 v[134:135], s[74:75], 0, v[148:149]
	s_mov_b32 m0, s89
	s_nop 0
	global_load_lds_dwordx4 v[134:135], off
	v_lshl_add_u64 v[134:135], s[74:75], 0, v[128:129]
	s_mov_b32 m0, s81
	s_nop 0
	global_load_lds_dwordx4 v[134:135], off
	v_lshl_add_u64 v[134:135], v[152:153], 0, s[34:35]
	s_mov_b32 m0, s85
	s_nop 0
	global_load_lds_dwordx4 v[134:135], off
	v_lshl_add_u64 v[134:135], v[226:227], 0, s[34:35]
	s_mov_b32 m0, s90
	s_nop 0
	global_load_lds_dwordx4 v[134:135], off
	s_waitcnt vmcnt(8)
	s_waitcnt lgkmcnt(0)
	s_barrier
	s_waitcnt lgkmcnt(0)
	v_mfma_f32_16x16x32_bf16 v[60:63], v[140:143], v[180:183], v[60:63]
	v_mfma_f32_16x16x32_bf16 v[56:59], v[156:159], v[180:183], v[56:59]
	v_mfma_f32_16x16x32_bf16 v[44:47], v[140:143], v[188:191], v[44:47]
	v_mfma_f32_16x16x32_bf16 v[40:43], v[156:159], v[188:191], v[40:43]
	v_mfma_f32_16x16x32_bf16 v[28:31], v[140:143], v[210:213], v[28:31]
	v_mfma_f32_16x16x32_bf16 v[24:27], v[156:159], v[210:213], v[24:27]
	v_mfma_f32_16x16x32_bf16 v[12:15], v[140:143], v[218:221], v[12:15]
	v_mfma_f32_16x16x32_bf16 v[8:11], v[156:159], v[218:221], v[8:11]
	v_mfma_f32_16x16x32_bf16 v[60:63], v[144:147], v[184:187], v[60:63]
	v_mfma_f32_16x16x32_bf16 v[56:59], v[160:163], v[184:187], v[56:59]
	v_mfma_f32_16x16x32_bf16 v[44:47], v[144:147], v[206:209], v[44:47]
	v_mfma_f32_16x16x32_bf16 v[40:43], v[160:163], v[206:209], v[40:43]
	v_mfma_f32_16x16x32_bf16 v[28:31], v[144:147], v[214:217], v[28:31]
	v_mfma_f32_16x16x32_bf16 v[24:27], v[160:163], v[214:217], v[24:27]
	v_mfma_f32_16x16x32_bf16 v[12:15], v[144:147], v[222:225], v[12:15]
	v_mfma_f32_16x16x32_bf16 v[8:11], v[160:163], v[222:225], v[8:11]
	v_mfma_f32_16x16x32_bf16 v[52:55], v[164:167], v[180:183], v[52:55]
	v_mfma_f32_16x16x32_bf16 v[48:51], v[172:175], v[180:183], v[48:51]
	v_mfma_f32_16x16x32_bf16 v[36:39], v[164:167], v[188:191], v[36:39]
	v_mfma_f32_16x16x32_bf16 v[32:35], v[172:175], v[188:191], v[32:35]
	v_mfma_f32_16x16x32_bf16 v[20:23], v[164:167], v[210:213], v[20:23]
	v_mfma_f32_16x16x32_bf16 v[16:19], v[172:175], v[210:213], v[16:19]
	v_mfma_f32_16x16x32_bf16 v[4:7], v[164:167], v[218:221], v[4:7]
	v_mfma_f32_16x16x32_bf16 v[0:3], v[172:175], v[218:221], v[0:3]
	v_mfma_f32_16x16x32_bf16 v[52:55], v[168:171], v[184:187], v[52:55]
	v_mfma_f32_16x16x32_bf16 v[48:51], v[176:179], v[184:187], v[48:51]
	v_mfma_f32_16x16x32_bf16 v[36:39], v[168:171], v[206:209], v[36:39]
	v_mfma_f32_16x16x32_bf16 v[32:35], v[176:179], v[206:209], v[32:35]
	v_mfma_f32_16x16x32_bf16 v[20:23], v[168:171], v[214:217], v[20:23]
	v_mfma_f32_16x16x32_bf16 v[16:19], v[176:179], v[214:217], v[16:19]
	v_mfma_f32_16x16x32_bf16 v[4:7], v[168:171], v[222:225], v[4:7]
	v_mfma_f32_16x16x32_bf16 v[0:3], v[176:179], v[222:225], v[0:3]
	s_barrier
	s_movk_i32 s74, 0x100
	s_andn2_b64 vcc, exec, s[66:67]
	s_mov_b64 s[24:25], -1
	s_mov_b64 s[66:67], 0
	s_cbranch_vccz .LBB0_407
	s_setprio 0
	s_and_b64 vcc, exec, s[48:49]
	v_readlane_b32 s66, v255, 8
	s_cbranch_vccz .LBB0_410
	s_barrier

; #define PG8_STAGE(bufoff, gbase, voff) do { _Pragma("unroll") for (int _i = 0; _i < 2; ++_i) \
;         __builtin_amdgcn_global_load_lds((const unsigned*)((const char*)(gbase) + (voff)[_i]), (PG8_LAS unsigned*)(lds + (bufoff) + ldsw + _i * 8192), 16, 0, 0); } while (0)
; #define PG8_LDA(dst, b, h) do { _Pragma("unroll") for (int m = 0; m < 4; ++m) _Pragma("unroll") for (int k = 0; k < 2; ++k) dst[m][k] = *(const PG8_LAS bf16x8*)(lds + PG8_SA(b, h) + aoff + m * 2048 + k * 1024); } while (0)
; #define PG8_WAIT_V(n) asm volatile("s_waitcnt vmcnt(" #n ")" ::: "memory")
; #define PG8_BAR __builtin_amdgcn_s_barrier()
; template <class Epi, class Sched, bool ALIGN_EPI = false, bool SP2 = false>
; __device__ __forceinline__ void gemm_phase(PG8_LAS unsigned char* lds, const Gemm g, const Sched& S, const Epi& E, int wave_s) {
;     ...
;         const bool has_next = S.next(ui + 1, nxt);
;         const char* nA = has_next ? (const char*)g.A + (size_t)nxt.pm * tstep : cA; const char* nB = has_next ? (const char*)g.Bt + (size_t)nxt.pn * tstep : cB;
;         for (int t = 0; t < nt; t += 2) {
;             const bool last = (t == nt - 2);
;             const char* a1 = cA + (size_t)(t + 1) * kstep;
;             const char* a2 = last ? nA : cA + (size_t)(t + 2) * kstep; const char* b2 = last ? nB : cB + (size_t)(t + 2) * kstep;
;             const char* a3 = a2 + kstep; const char* b3 = b2 + kstep;
;             if (last && has_next) S.a_ready(nxt);
;             if constexpr (SP2) {
;             PG8_LDB(B0, 0, 0); PG8_LDB(B1, 0, 1); PG8_SCHED; PG8_LDA(At, 0, 0); PG8_STAGE(PG8_SA(1, 1), a1 + hstep, voffA);
;             PG8_WAIT_V(8); PG8_WAIT_L(0); PG8_BAR; PG8_MMA(0, 0, At, B0); PG8_MMA(0, 1, At, B1); PG8_BAR; PG8_SCHED;
;             PG8_LDA(At, 0, 1); PG8_STAGE(PG8_SB(0, 0), b2, voffB); PG8_STAGE(PG8_SB(0, 1), b2 + hstep, voffB); PG8_STAGE(PG8_SA(0, 0), a2, voffA);
;             PG8_WAIT_V(8); PG8_WAIT_L(0); PG8_BAR; PG8_MMA(1, 0, At, B0); PG8_MMA(1, 1, At, B1); PG8_BAR; PG8_SCHED;
;     ...
;         { float zf_ = 0.f; asm volatile("" : "+v"(zf_)); const f32x4 zero4_ = {zf_, zf_, zf_, zf_};
; #pragma unroll
;         for (int a = 0; a < 2; ++a)
; #pragma unroll
;             for (int b = 0; b < 2; ++b)
; #pragma unroll
;                 for (int m = 0; m < 4; ++m)
; #pragma unroll
;                     for (int n = 0; n < 2; ++n) acc[a][b][m][n] = zero4_; }
.LBB0_452:
	s_ashr_i32 s49, s48, 31
	s_lshl_b64 s[22:23], s[48:49], 20
	s_add_u32 s52, s9, s22
	s_addc_u32 s53, s11, s23
	s_and_b64 s[22:23], s[40:41], exec
	s_cselect_b32 s22, s53, s59
	s_cselect_b32 s23, s52, s58
	s_ashr_i32 s47, s46, 31
	s_lshl_b64 s[28:29], s[46:47], 20
	v_readlane_b32 s0, v254, 63
	s_add_u32 s54, s0, s28
	v_readlane_b32 s0, v255, 2
	s_addc_u32 s55, s0, s29
	s_and_b64 s[28:29], s[40:41], exec
	s_cselect_b32 s5, s55, s61
	s_cselect_b32 s28, s54, s60
	s_add_u32 s58, s58, 0x80080
	s_addc_u32 s59, s59, 0
	s_add_u32 s29, s60, 0x100
	v_mov_b64_e32 v[6:7], v[2:3]
	v_mov_b64_e32 v[18:19], v[2:3]
	v_mov_b64_e32 v[22:23], v[2:3]
	v_mov_b64_e32 v[34:35], v[2:3]
	v_mov_b64_e32 v[38:39], v[2:3]
	v_mov_b64_e32 v[50:51], v[2:3]
	v_mov_b64_e32 v[54:55], v[2:3]
	v_mov_b64_e32 v[10:11], v[2:3]
	v_mov_b64_e32 v[14:15], v[2:3]
	v_mov_b64_e32 v[26:27], v[2:3]
	v_mov_b64_e32 v[30:31], v[2:3]
	v_mov_b64_e32 v[42:43], v[2:3]
	v_mov_b64_e32 v[46:47], v[2:3]
	v_mov_b64_e32 v[58:59], v[2:3]
	v_mov_b64_e32 v[62:63], v[2:3]
	v_mov_b64_e32 v[66:67], v[2:3]
	v_mov_b64_e32 v[70:71], v[2:3]
	v_mov_b64_e32 v[82:83], v[2:3]
	v_mov_b64_e32 v[86:87], v[2:3]
	v_mov_b64_e32 v[98:99], v[2:3]
	v_mov_b64_e32 v[102:103], v[2:3]
	v_mov_b64_e32 v[114:115], v[2:3]
	v_mov_b64_e32 v[118:119], v[2:3]
	v_mov_b64_e32 v[74:75], v[2:3]
	v_mov_b64_e32 v[78:79], v[2:3]
	v_mov_b64_e32 v[90:91], v[2:3]
	v_mov_b64_e32 v[94:95], v[2:3]
	v_mov_b64_e32 v[106:107], v[2:3]
	v_mov_b64_e32 v[110:111], v[2:3]
	v_mov_b64_e32 v[122:123], v[2:3]
	v_mov_b64_e32 v[126:127], v[2:3]
	s_addc_u32 s47, s61, 0
	s_mov_b32 s49, -2
	v_mov_b64_e32 v[4:5], v[0:1]
	v_mov_b64_e32 v[16:17], v[0:1]
	v_mov_b64_e32 v[20:21], v[0:1]
	v_mov_b64_e32 v[32:33], v[0:1]
	v_mov_b64_e32 v[36:37], v[0:1]
	v_mov_b64_e32 v[48:49], v[0:1]
	v_mov_b64_e32 v[52:53], v[0:1]
	v_mov_b64_e32 v[8:9], v[0:1]
	v_mov_b64_e32 v[12:13], v[0:1]
	v_mov_b64_e32 v[24:25], v[0:1]
	v_mov_b64_e32 v[28:29], v[0:1]
	v_mov_b64_e32 v[40:41], v[0:1]
	v_mov_b64_e32 v[44:45], v[0:1]
	v_mov_b64_e32 v[56:57], v[0:1]
	v_mov_b64_e32 v[60:61], v[0:1]
	v_mov_b64_e32 v[64:65], v[0:1]
	v_mov_b64_e32 v[68:69], v[0:1]
	v_mov_b64_e32 v[80:81], v[0:1]
	v_mov_b64_e32 v[84:85], v[0:1]
	v_mov_b64_e32 v[96:97], v[0:1]
	v_mov_b64_e32 v[100:101], v[0:1]
	v_mov_b64_e32 v[112:113], v[0:1]
	v_mov_b64_e32 v[116:117], v[0:1]
	v_mov_b64_e32 v[72:73], v[0:1]
	v_mov_b64_e32 v[76:77], v[0:1]
	v_mov_b64_e32 v[88:89], v[0:1]
	v_mov_b64_e32 v[92:93], v[0:1]
	v_mov_b64_e32 v[104:105], v[0:1]
	v_mov_b64_e32 v[108:109], v[0:1]
	v_mov_b64_e32 v[120:121], v[0:1]
	v_mov_b64_e32 v[124:125], v[0:1]
	v_readlane_b32 vcc_lo, v253, 14
	s_nop 3
	s_cmp_eq_u32 vcc_lo, 0
	s_cbranch_scc1 .Lgprio_3
	s_setprio 1
.Lgprio_3:
.LBB0_453:
	s_add_u32 s36, s58, 0xfff80080
	s_addc_u32 s37, s59, -1
	s_add_i32 s66, 0, 0x10000
	s_cmp_eq_u32 s49, 28
	s_cselect_b32 s63, s22, s37
	s_cselect_b32 s62, s23, s36
	v_add_u32_e32 v138, s66, v141
	s_cselect_b32 s61, s5, s47
	s_cselect_b32 s60, s28, s29
	s_add_i32 s36, 0, 0x14000
	ds_read_b128 v[144:147], v138
	ds_read_b128 v[156:159], v138 offset:1024
	ds_read_b128 v[160:163], v138 offset:2048
	ds_read_b128 v[164:167], v138 offset:3072
	v_add_u32_e32 v138, s36, v141
	ds_read_b128 v[168:171], v138
	ds_read_b128 v[172:175], v138 offset:1024
	ds_read_b128 v[176:179], v138 offset:2048
	ds_read_b128 v[180:183], v138 offset:3072
	v_lshl_add_u64 v[138:139], s[58:59], 0, v[134:135]
	s_add_i32 m0, s19, 0xc000
	ds_read_b128 v[184:187], v143
	ds_read_b128 v[188:191], v143 offset:1024
	ds_read_b128 v[206:209], v143 offset:2048
	ds_read_b128 v[210:213], v143 offset:3072
	ds_read_b128 v[214:217], v143 offset:4096
	ds_read_b128 v[218:221], v143 offset:5120
	ds_read_b128 v[222:225], v143 offset:6144
	ds_read_b128 v[226:229], v143 offset:7168
	global_load_lds_dwordx4 v[138:139], off
	v_lshl_add_u64 v[138:139], s[58:59], 0, v[136:137]
	s_add_i32 m0, s19, 0xe000
	s_nop 0
	global_load_lds_dwordx4 v[138:139], off
	s_waitcnt vmcnt(8)
	s_waitcnt lgkmcnt(0)
	s_barrier
	s_waitcnt lgkmcnt(0)
	v_mfma_f32_16x16x32_bf16 v[124:127], v[144:147], v[184:187], v[124:127]
	v_mfma_f32_16x16x32_bf16 v[120:123], v[160:163], v[184:187], v[120:123]
	v_mfma_f32_16x16x32_bf16 v[108:111], v[144:147], v[206:209], v[108:111]
	v_mfma_f32_16x16x32_bf16 v[104:107], v[160:163], v[206:209], v[104:107]
	v_mfma_f32_16x16x32_bf16 v[92:95], v[144:147], v[214:217], v[92:95]
	v_mfma_f32_16x16x32_bf16 v[88:91], v[160:163], v[214:217], v[88:91]
	v_mfma_f32_16x16x32_bf16 v[76:79], v[144:147], v[222:225], v[76:79]
	v_mfma_f32_16x16x32_bf16 v[72:75], v[160:163], v[222:225], v[72:75]
	v_mfma_f32_16x16x32_bf16 v[124:127], v[156:159], v[188:191], v[124:127]
	v_mfma_f32_16x16x32_bf16 v[120:123], v[164:167], v[188:191], v[120:123]
	v_mfma_f32_16x16x32_bf16 v[108:111], v[156:159], v[210:213], v[108:111]
	v_mfma_f32_16x16x32_bf16 v[104:107], v[164:167], v[210:213], v[104:107]
	v_mfma_f32_16x16x32_bf16 v[92:95], v[156:159], v[218:221], v[92:95]
	v_mfma_f32_16x16x32_bf16 v[88:91], v[164:167], v[218:221], v[88:91]
	v_mfma_f32_16x16x32_bf16 v[76:79], v[156:159], v[226:229], v[76:79]
	v_mfma_f32_16x16x32_bf16 v[72:75], v[164:167], v[226:229], v[72:75]
	v_mfma_f32_16x16x32_bf16 v[116:119], v[168:171], v[184:187], v[116:119]
	v_mfma_f32_16x16x32_bf16 v[112:115], v[176:179], v[184:187], v[112:115]
	v_mfma_f32_16x16x32_bf16 v[100:103], v[168:171], v[206:209], v[100:103]
	v_mfma_f32_16x16x32_bf16 v[96:99], v[176:179], v[206:209], v[96:99]
	v_mfma_f32_16x16x32_bf16 v[84:87], v[168:171], v[214:217], v[84:87]
	v_mfma_f32_16x16x32_bf16 v[80:83], v[176:179], v[214:217], v[80:83]
	v_mfma_f32_16x16x32_bf16 v[68:71], v[168:171], v[222:225], v[68:71]
	v_mfma_f32_16x16x32_bf16 v[64:67], v[176:179], v[222:225], v[64:67]
	v_mfma_f32_16x16x32_bf16 v[116:119], v[172:175], v[188:191], v[116:119]
	v_mfma_f32_16x16x32_bf16 v[112:115], v[180:183], v[188:191], v[112:115]
	v_mfma_f32_16x16x32_bf16 v[100:103], v[172:175], v[210:213], v[100:103]
	v_mfma_f32_16x16x32_bf16 v[96:99], v[180:183], v[210:213], v[96:99]
	v_mfma_f32_16x16x32_bf16 v[84:87], v[172:175], v[218:221], v[84:87]
	v_mfma_f32_16x16x32_bf16 v[80:83], v[180:183], v[218:221], v[80:83]
	v_mfma_f32_16x16x32_bf16 v[68:71], v[172:175], v[226:229], v[68:71]
	v_mfma_f32_16x16x32_bf16 v[64:67], v[180:183], v[226:229], v[64:67]
	s_barrier
; #define PG8_STAGE(bufoff, gbase, voff) do { _Pragma("unroll") for (int _i = 0; _i < 2; ++_i) \
;         __builtin_amdgcn_global_load_lds((const unsigned*)((const char*)(gbase) + (voff)[_i]), (PG8_LAS unsigned*)(lds + (bufoff) + ldsw + _i * 8192), 16, 0, 0); } while (0)
; #define PG8_LDA(dst, b, h) do { _Pragma("unroll") for (int m = 0; m < 4; ++m) _Pragma("unroll") for (int k = 0; k < 2; ++k) dst[m][k] = *(const PG8_LAS bf16x8*)(lds + PG8_SA(b, h) + aoff + m * 2048 + k * 1024); } while (0)
; #define PG8_LDB(dst, b, h) do { _Pragma("unroll") for (int n = 0; n < 2; ++n) _Pragma("unroll") for (int k = 0; k < 2; ++k) dst[n][k] = *(const PG8_LAS bf16x8*)(lds + PG8_SB(b, h) + boff + n * 2048 + k * 1024); } while (0)
; #define PG8_MMA(ai, bj, At, Bt) do { __builtin_amdgcn_s_setprio(1); _Pragma("unroll") for (int m = 0; m < 4; ++m) _Pragma("unroll") for (int n = 0; n < 2; ++n) _Pragma("unroll") for (int k = 0; k < 2; ++k) \
;         acc[ai][bj][m][n] = __builtin_amdgcn_mfma_f32_16x16x32_bf16(Bt[n][k], At[m][k], acc[ai][bj][m][n], 0, 0, 0); __builtin_amdgcn_s_setprio(0); } while (0)
; #define PG8_WAIT_V(n) asm volatile("s_waitcnt vmcnt(" #n ")" ::: "memory")
; #define PG8_WAIT_L(n) asm volatile("s_waitcnt lgkmcnt(" #n ")" ::: "memory")
; #define PG8_BAR __builtin_amdgcn_s_barrier()
; #define PG8_SCHED __builtin_amdgcn_sched_barrier(0)
; template <class Epi, class Sched, bool ALIGN_EPI = false, bool SP2 = false>
; __device__ __forceinline__ void gemm_phase(PG8_LAS unsigned char* lds, const Gemm g, const Sched& S, const Epi& E, int wave_s) {
;     ...
;             PG8_LDA(At, 0, 1); PG8_STAGE(PG8_SB(0, 0), b2, voffB); PG8_STAGE(PG8_SB(0, 1), b2 + hstep, voffB); PG8_STAGE(PG8_SA(0, 0), a2, voffA);
;             PG8_WAIT_V(8); PG8_WAIT_L(0); PG8_BAR; PG8_MMA(1, 0, At, B0); PG8_MMA(1, 1, At, B1); PG8_BAR; PG8_SCHED;
;             PG8_LDB(B0, 1, 0); PG8_LDB(B1, 1, 1); PG8_SCHED; PG8_LDA(At, 1, 0); PG8_STAGE(PG8_SA(0, 1), a2 + hstep, voffA);
;             PG8_WAIT_V(8); PG8_WAIT_L(0); PG8_BAR; PG8_MMA(0, 0, At, B0); PG8_MMA(0, 1, At, B1); PG8_BAR; PG8_SCHED;
	s_add_i32 s37, s66, s18
	v_lshl_add_u64 v[138:139], s[60:61], 0, v[148:149]
	s_mov_b32 m0, s37
	ds_read_b128 v[184:187], v143 offset:16384
	ds_read_b128 v[188:191], v143 offset:17408
	ds_read_b128 v[206:209], v143 offset:18432
	ds_read_b128 v[210:213], v143 offset:19456
	ds_read_b128 v[214:217], v143 offset:20480
	ds_read_b128 v[218:221], v143 offset:21504
	ds_read_b128 v[222:225], v143 offset:22528
	ds_read_b128 v[226:229], v143 offset:23552
	global_load_lds_dwordx4 v[138:139], off
	s_add_i32 m0, s37, 0x2000
	s_add_u32 s66, s60, 0x80000
	v_lshl_add_u64 v[150:151], s[60:61], 0, v[128:129]
	s_addc_u32 s67, s61, 0
	s_add_i32 s36, s36, s18
	global_load_lds_dwordx4 v[150:151], off
	v_lshl_add_u64 v[152:153], s[66:67], 0, v[148:149]
	s_mov_b32 m0, s36
	v_lshl_add_u64 v[230:231], s[62:63], 0, v[130:131]
	global_load_lds_dwordx4 v[152:153], off
	v_lshl_add_u64 v[152:153], s[66:67], 0, v[128:129]
	s_add_i32 m0, s36, 0x2000
	s_nop 0
	global_load_lds_dwordx4 v[152:153], off
	v_lshl_add_u64 v[152:153], s[62:63], 0, v[132:133]
	s_mov_b32 m0, s19
	s_nop 0
	global_load_lds_dwordx4 v[152:153], off
	s_mov_b32 m0, s24
	s_nop 0
	global_load_lds_dwordx4 v[230:231], off
	s_waitcnt vmcnt(8)
	s_waitcnt lgkmcnt(0)
	s_barrier
	s_waitcnt lgkmcnt(0)
	v_mfma_f32_16x16x32_bf16 v[60:63], v[144:147], v[184:187], v[60:63]
	v_mfma_f32_16x16x32_bf16 v[56:59], v[160:163], v[184:187], v[56:59]
	v_mfma_f32_16x16x32_bf16 v[44:47], v[144:147], v[206:209], v[44:47]
	v_mfma_f32_16x16x32_bf16 v[40:43], v[160:163], v[206:209], v[40:43]
	v_mfma_f32_16x16x32_bf16 v[28:31], v[144:147], v[214:217], v[28:31]
	v_mfma_f32_16x16x32_bf16 v[24:27], v[160:163], v[214:217], v[24:27]
	v_mfma_f32_16x16x32_bf16 v[12:15], v[144:147], v[222:225], v[12:15]
	v_mfma_f32_16x16x32_bf16 v[8:11], v[160:163], v[222:225], v[8:11]
	v_mfma_f32_16x16x32_bf16 v[60:63], v[156:159], v[188:191], v[60:63]
	v_mfma_f32_16x16x32_bf16 v[56:59], v[164:167], v[188:191], v[56:59]
	v_mfma_f32_16x16x32_bf16 v[44:47], v[156:159], v[210:213], v[44:47]
	v_mfma_f32_16x16x32_bf16 v[40:43], v[164:167], v[210:213], v[40:43]
	v_mfma_f32_16x16x32_bf16 v[28:31], v[156:159], v[218:221], v[28:31]
	v_mfma_f32_16x16x32_bf16 v[24:27], v[164:167], v[218:221], v[24:27]
	v_mfma_f32_16x16x32_bf16 v[12:15], v[156:159], v[226:229], v[12:15]
	v_mfma_f32_16x16x32_bf16 v[8:11], v[164:167], v[226:229], v[8:11]
	v_mfma_f32_16x16x32_bf16 v[52:55], v[168:171], v[184:187], v[52:55]
	v_mfma_f32_16x16x32_bf16 v[48:51], v[176:179], v[184:187], v[48:51]
	v_mfma_f32_16x16x32_bf16 v[36:39], v[168:171], v[206:209], v[36:39]
	v_mfma_f32_16x16x32_bf16 v[32:35], v[176:179], v[206:209], v[32:35]
	v_mfma_f32_16x16x32_bf16 v[20:23], v[168:171], v[214:217], v[20:23]
	v_mfma_f32_16x16x32_bf16 v[16:19], v[176:179], v[214:217], v[16:19]
	v_mfma_f32_16x16x32_bf16 v[4:7], v[168:171], v[222:225], v[4:7]
	v_mfma_f32_16x16x32_bf16 v[0:3], v[176:179], v[222:225], v[0:3]
	v_mfma_f32_16x16x32_bf16 v[52:55], v[172:175], v[188:191], v[52:55]
	v_mfma_f32_16x16x32_bf16 v[48:51], v[180:183], v[188:191], v[48:51]
	v_mfma_f32_16x16x32_bf16 v[36:39], v[172:175], v[210:213], v[36:39]
	v_mfma_f32_16x16x32_bf16 v[32:35], v[180:183], v[210:213], v[32:35]
	v_mfma_f32_16x16x32_bf16 v[20:23], v[172:175], v[218:221], v[20:23]
	v_mfma_f32_16x16x32_bf16 v[16:19], v[180:183], v[218:221], v[16:19]
	v_mfma_f32_16x16x32_bf16 v[4:7], v[172:175], v[226:229], v[4:7]
	v_mfma_f32_16x16x32_bf16 v[0:3], v[180:183], v[226:229], v[0:3]
	s_barrier
	s_add_i32 s36, 0, 0x18000
	s_add_i32 s37, 0, 0x1c000
	v_add_u32_e32 v164, s36, v141
	v_add_u32_e32 v180, s37, v141
	ds_read_b128 v[144:147], v164
	ds_read_b128 v[156:159], v164 offset:1024
	ds_read_b128 v[160:163], v164 offset:2048
	ds_read_b128 v[164:167], v164 offset:3072
	ds_read_b128 v[168:171], v180
	ds_read_b128 v[172:175], v180 offset:1024
	ds_read_b128 v[176:179], v180 offset:2048
	ds_read_b128 v[180:183], v180 offset:3072
	s_add_u32 s62, s62, 0x80000
	s_addc_u32 s63, s63, 0
	s_mov_b32 m0, s25
	v_lshl_add_u64 v[232:233], s[62:63], 0, v[132:133]
	ds_read_b128 v[184:187], v143 offset:32768
	ds_read_b128 v[188:191], v143 offset:33792
	ds_read_b128 v[206:209], v143 offset:34816
	ds_read_b128 v[210:213], v143 offset:35840
	ds_read_b128 v[214:217], v143 offset:36864
	ds_read_b128 v[218:221], v143 offset:37888
	ds_read_b128 v[222:225], v143 offset:38912
	ds_read_b128 v[226:229], v143 offset:39936
	global_load_lds_dwordx4 v[232:233], off
	v_lshl_add_u64 v[232:233], s[62:63], 0, v[130:131]
	s_mov_b32 m0, s57
	s_nop 0
	global_load_lds_dwordx4 v[232:233], off
	s_waitcnt vmcnt(8)
	s_waitcnt lgkmcnt(0)
	s_barrier
; #define PG8_STAGE(bufoff, gbase, voff) do { _Pragma("unroll") for (int _i = 0; _i < 2; ++_i) \
;         __builtin_amdgcn_global_load_lds((const unsigned*)((const char*)(gbase) + (voff)[_i]), (PG8_LAS unsigned*)(lds + (bufoff) + ldsw + _i * 8192), 16, 0, 0); } while (0)
; #define PG8_LDA(dst, b, h) do { _Pragma("unroll") for (int m = 0; m < 4; ++m) _Pragma("unroll") for (int k = 0; k < 2; ++k) dst[m][k] = *(const PG8_LAS bf16x8*)(lds + PG8_SA(b, h) + aoff + m * 2048 + k * 1024); } while (0)
; #define PG8_MMA(ai, bj, At, Bt) do { __builtin_amdgcn_s_setprio(1); _Pragma("unroll") for (int m = 0; m < 4; ++m) _Pragma("unroll") for (int n = 0; n < 2; ++n) _Pragma("unroll") for (int k = 0; k < 2; ++k) \
;         acc[ai][bj][m][n] = __builtin_amdgcn_mfma_f32_16x16x32_bf16(Bt[n][k], At[m][k], acc[ai][bj][m][n], 0, 0, 0); __builtin_amdgcn_s_setprio(0); } while (0)
; #define PG8_WAIT_V(n) asm volatile("s_waitcnt vmcnt(" #n ")" ::: "memory")
; #define PG8_WAIT_L(n) asm volatile("s_waitcnt lgkmcnt(" #n ")" ::: "memory")
; #define PG8_BAR __builtin_amdgcn_s_barrier()
; #define PG8_SCHED __builtin_amdgcn_sched_barrier(0)
; template <class Epi, class Sched, bool ALIGN_EPI = false, bool SP2 = false>
; __device__ __forceinline__ void gemm_phase(PG8_LAS unsigned char* lds, const Gemm g, const Sched& S, const Epi& E, int wave_s) {
;     ...
;             PG8_WAIT_V(8); PG8_WAIT_L(0); PG8_BAR; PG8_MMA(0, 0, At, B0); PG8_MMA(0, 1, At, B1); PG8_BAR; PG8_SCHED;
;             PG8_LDA(At, 1, 1); PG8_STAGE(PG8_SB(1, 0), b3, voffB); PG8_STAGE(PG8_SB(1, 1), b3 + hstep, voffB); PG8_STAGE(PG8_SA(1, 0), a3, voffA);
;             PG8_WAIT_V(8); PG8_WAIT_L(0); PG8_BAR; PG8_MMA(1, 0, At, B0); PG8_MMA(1, 1, At, B1); PG8_BAR; PG8_SCHED;
	s_waitcnt lgkmcnt(0)
	v_mfma_f32_16x16x32_bf16 v[124:127], v[144:147], v[184:187], v[124:127]
	v_mfma_f32_16x16x32_bf16 v[120:123], v[160:163], v[184:187], v[120:123]
	v_mfma_f32_16x16x32_bf16 v[108:111], v[144:147], v[206:209], v[108:111]
	v_mfma_f32_16x16x32_bf16 v[104:107], v[160:163], v[206:209], v[104:107]
	v_mfma_f32_16x16x32_bf16 v[92:95], v[144:147], v[214:217], v[92:95]
	v_mfma_f32_16x16x32_bf16 v[88:91], v[160:163], v[214:217], v[88:91]
	v_mfma_f32_16x16x32_bf16 v[76:79], v[144:147], v[222:225], v[76:79]
	v_mfma_f32_16x16x32_bf16 v[72:75], v[160:163], v[222:225], v[72:75]
	v_mfma_f32_16x16x32_bf16 v[124:127], v[156:159], v[188:191], v[124:127]
	v_mfma_f32_16x16x32_bf16 v[120:123], v[164:167], v[188:191], v[120:123]
	v_mfma_f32_16x16x32_bf16 v[108:111], v[156:159], v[210:213], v[108:111]
	v_mfma_f32_16x16x32_bf16 v[104:107], v[164:167], v[210:213], v[104:107]
	v_mfma_f32_16x16x32_bf16 v[92:95], v[156:159], v[218:221], v[92:95]
	v_mfma_f32_16x16x32_bf16 v[88:91], v[164:167], v[218:221], v[88:91]
	v_mfma_f32_16x16x32_bf16 v[76:79], v[156:159], v[226:229], v[76:79]
	v_mfma_f32_16x16x32_bf16 v[72:75], v[164:167], v[226:229], v[72:75]
	v_mfma_f32_16x16x32_bf16 v[116:119], v[168:171], v[184:187], v[116:119]
	v_mfma_f32_16x16x32_bf16 v[112:115], v[176:179], v[184:187], v[112:115]
	v_mfma_f32_16x16x32_bf16 v[100:103], v[168:171], v[206:209], v[100:103]
	v_mfma_f32_16x16x32_bf16 v[96:99], v[176:179], v[206:209], v[96:99]
	v_mfma_f32_16x16x32_bf16 v[84:87], v[168:171], v[214:217], v[84:87]
	v_mfma_f32_16x16x32_bf16 v[80:83], v[176:179], v[214:217], v[80:83]
	v_mfma_f32_16x16x32_bf16 v[68:71], v[168:171], v[222:225], v[68:71]
	v_mfma_f32_16x16x32_bf16 v[64:67], v[176:179], v[222:225], v[64:67]
	v_mfma_f32_16x16x32_bf16 v[116:119], v[172:175], v[188:191], v[116:119]
	v_mfma_f32_16x16x32_bf16 v[112:115], v[180:183], v[188:191], v[112:115]
	v_mfma_f32_16x16x32_bf16 v[100:103], v[172:175], v[210:213], v[100:103]
	v_mfma_f32_16x16x32_bf16 v[96:99], v[180:183], v[210:213], v[96:99]
	v_mfma_f32_16x16x32_bf16 v[84:87], v[172:175], v[218:221], v[84:87]
	v_mfma_f32_16x16x32_bf16 v[80:83], v[180:183], v[218:221], v[80:83]
	v_mfma_f32_16x16x32_bf16 v[68:71], v[172:175], v[226:229], v[68:71]
	v_mfma_f32_16x16x32_bf16 v[64:67], v[180:183], v[226:229], v[64:67]
	s_barrier
	s_add_i32 s36, s36, s18
	v_lshl_add_u64 v[138:139], v[138:139], 0, s[34:35]
	s_mov_b32 m0, s36
	ds_read_b128 v[184:187], v143 offset:49152
	ds_read_b128 v[188:191], v143 offset:50176
	ds_read_b128 v[206:209], v143 offset:51200
	ds_read_b128 v[210:213], v143 offset:52224
	ds_read_b128 v[214:217], v143 offset:53248
	ds_read_b128 v[218:221], v143 offset:54272
	ds_read_b128 v[222:225], v143 offset:55296
	ds_read_b128 v[226:229], v143 offset:56320
	global_load_lds_dwordx4 v[138:139], off
	s_add_i32 m0, s36, 0x2000
	s_add_u32 s60, s60, 0x80080
	v_lshl_add_u64 v[138:139], v[150:151], 0, s[34:35]
	s_addc_u32 s61, s61, 0
	s_add_i32 s36, s37, s18
	global_load_lds_dwordx4 v[138:139], off
	v_lshl_add_u64 v[138:139], s[60:61], 0, v[148:149]
	s_mov_b32 m0, s36
	s_nop 0
	global_load_lds_dwordx4 v[138:139], off
	v_lshl_add_u64 v[138:139], s[60:61], 0, v[128:129]
	s_add_i32 m0, s36, 0x2000
	s_nop 0
	global_load_lds_dwordx4 v[138:139], off
	v_lshl_add_u64 v[138:139], v[152:153], 0, s[34:35]
	s_mov_b32 m0, s38
	s_nop 0
	global_load_lds_dwordx4 v[138:139], off
	v_lshl_add_u64 v[138:139], v[230:231], 0, s[34:35]
	s_mov_b32 m0, s39
	s_nop 0
	global_load_lds_dwordx4 v[138:139], off
	s_waitcnt vmcnt(8)
	s_waitcnt lgkmcnt(0)
	s_barrier
	s_waitcnt lgkmcnt(0)
	v_mfma_f32_16x16x32_bf16 v[60:63], v[144:147], v[184:187], v[60:63]
	v_mfma_f32_16x16x32_bf16 v[56:59], v[160:163], v[184:187], v[56:59]
	v_mfma_f32_16x16x32_bf16 v[44:47], v[144:147], v[206:209], v[44:47]
	v_mfma_f32_16x16x32_bf16 v[40:43], v[160:163], v[206:209], v[40:43]
	v_mfma_f32_16x16x32_bf16 v[28:31], v[144:147], v[214:217], v[28:31]
	v_mfma_f32_16x16x32_bf16 v[24:27], v[160:163], v[214:217], v[24:27]
	v_mfma_f32_16x16x32_bf16 v[12:15], v[144:147], v[222:225], v[12:15]
	v_mfma_f32_16x16x32_bf16 v[8:11], v[160:163], v[222:225], v[8:11]
	v_mfma_f32_16x16x32_bf16 v[60:63], v[156:159], v[188:191], v[60:63]
	v_mfma_f32_16x16x32_bf16 v[56:59], v[164:167], v[188:191], v[56:59]
	v_mfma_f32_16x16x32_bf16 v[44:47], v[156:159], v[210:213], v[44:47]
	v_mfma_f32_16x16x32_bf16 v[40:43], v[164:167], v[210:213], v[40:43]
	v_mfma_f32_16x16x32_bf16 v[28:31], v[156:159], v[218:221], v[28:31]
	v_mfma_f32_16x16x32_bf16 v[24:27], v[164:167], v[218:221], v[24:27]
	v_mfma_f32_16x16x32_bf16 v[12:15], v[156:159], v[226:229], v[12:15]
	v_mfma_f32_16x16x32_bf16 v[8:11], v[164:167], v[226:229], v[8:11]
	v_mfma_f32_16x16x32_bf16 v[52:55], v[168:171], v[184:187], v[52:55]
	v_mfma_f32_16x16x32_bf16 v[48:51], v[176:179], v[184:187], v[48:51]
	v_mfma_f32_16x16x32_bf16 v[36:39], v[168:171], v[206:209], v[36:39]
	v_mfma_f32_16x16x32_bf16 v[32:35], v[176:179], v[206:209], v[32:35]
	v_mfma_f32_16x16x32_bf16 v[20:23], v[168:171], v[214:217], v[20:23]
	v_mfma_f32_16x16x32_bf16 v[16:19], v[176:179], v[214:217], v[16:19]
	v_mfma_f32_16x16x32_bf16 v[4:7], v[168:171], v[222:225], v[4:7]
	v_mfma_f32_16x16x32_bf16 v[0:3], v[176:179], v[222:225], v[0:3]
	v_mfma_f32_16x16x32_bf16 v[52:55], v[172:175], v[188:191], v[52:55]
	v_mfma_f32_16x16x32_bf16 v[48:51], v[180:183], v[188:191], v[48:51]
	v_mfma_f32_16x16x32_bf16 v[36:39], v[172:175], v[210:213], v[36:39]
	v_mfma_f32_16x16x32_bf16 v[32:35], v[180:183], v[210:213], v[32:35]
	v_mfma_f32_16x16x32_bf16 v[20:23], v[172:175], v[218:221], v[20:23]
	v_mfma_f32_16x16x32_bf16 v[16:19], v[180:183], v[218:221], v[16:19]
	v_mfma_f32_16x16x32_bf16 v[4:7], v[172:175], v[226:229], v[4:7]
	v_mfma_f32_16x16x32_bf16 v[0:3], v[180:183], v[226:229], v[0:3]
	s_barrier
	s_add_i32 s49, s49, 2
	s_add_u32 s58, s58, 0x100
	s_addc_u32 s59, s59, 0
	s_add_u32 s29, s29, 0x100
	s_addc_u32 s47, s47, 0
	s_cmp_gt_u32 s49, 29
	s_cbranch_scc0 .LBB0_453
	s_setprio 0
	s_and_b64 vcc, exec, s[44:45]
	s_cbranch_vccz .LBB0_456
	s_barrier

; #define PG8_STAGE(bufoff, gbase, voff) do { _Pragma("unroll") for (int _i = 0; _i < 2; ++_i) \
;         __builtin_amdgcn_global_load_lds((const unsigned*)((const char*)(gbase) + (voff)[_i]), (PG8_LAS unsigned*)(lds + (bufoff) + ldsw + _i * 8192), 16, 0, 0); } while (0)
; #define PG8_LDA(dst, b, h) do { _Pragma("unroll") for (int m = 0; m < 4; ++m) _Pragma("unroll") for (int k = 0; k < 2; ++k) dst[m][k] = *(const PG8_LAS bf16x8*)(lds + PG8_SA(b, h) + aoff + m * 2048 + k * 1024); } while (0)
; #define PG8_WAIT_V(n) asm volatile("s_waitcnt vmcnt(" #n ")" ::: "memory")
; #define PG8_BAR __builtin_amdgcn_s_barrier()
; template <class Epi, class Sched, bool ALIGN_EPI = false, bool SP2 = false>
; __device__ __forceinline__ void gemm_phase(PG8_LAS unsigned char* lds, const Gemm g, const Sched& S, const Epi& E, int wave_s) {
;     ...
;         const bool has_next = S.next(ui + 1, nxt);
;         const char* nA = has_next ? (const char*)g.A + (size_t)nxt.pm * tstep : cA; const char* nB = has_next ? (const char*)g.Bt + (size_t)nxt.pn * tstep : cB;
;         for (int t = 0; t < nt; t += 2) {
;             const bool last = (t == nt - 2);
;             const char* a1 = cA + (size_t)(t + 1) * kstep;
;             const char* a2 = last ? nA : cA + (size_t)(t + 2) * kstep; const char* b2 = last ? nB : cB + (size_t)(t + 2) * kstep;
;             const char* a3 = a2 + kstep; const char* b3 = b2 + kstep;
;             if (last && has_next) S.a_ready(nxt);
;             if constexpr (SP2) {
;             PG8_LDB(B0, 0, 0); PG8_LDB(B1, 0, 1); PG8_SCHED; PG8_LDA(At, 0, 0); PG8_STAGE(PG8_SA(1, 1), a1 + hstep, voffA);
;             PG8_WAIT_V(8); PG8_WAIT_L(0); PG8_BAR; PG8_MMA(0, 0, At, B0); PG8_MMA(0, 1, At, B1); PG8_BAR; PG8_SCHED;
;             PG8_LDA(At, 0, 1); PG8_STAGE(PG8_SB(0, 0), b2, voffB); PG8_STAGE(PG8_SB(0, 1), b2 + hstep, voffB); PG8_STAGE(PG8_SA(0, 0), a2, voffA);
;             PG8_WAIT_V(8); PG8_WAIT_L(0); PG8_BAR; PG8_MMA(1, 0, At, B0); PG8_MMA(1, 1, At, B1); PG8_BAR; PG8_SCHED;
;     ...
;         { float zf_ = 0.f; asm volatile("" : "+v"(zf_)); const f32x4 zero4_ = {zf_, zf_, zf_, zf_};
; #pragma unroll
;         for (int a = 0; a < 2; ++a)
; #pragma unroll
;             for (int b = 0; b < 2; ++b)
; #pragma unroll
;                 for (int m = 0; m < 4; ++m)
; #pragma unroll
;                     for (int n = 0; n < 2; ++n) acc[a][b][m][n] = zero4_; }
.LBB0_468:
	s_ashr_i32 s53, s52, 31
	s_lshl_b64 s[22:23], s[52:53], 20
	s_add_u32 s54, s19, s22
	s_addc_u32 s55, s24, s23
	s_and_b64 s[22:23], s[40:41], exec
	s_cselect_b32 s22, s55, s61
	s_cselect_b32 s23, s54, s60
	s_ashr_i32 s49, s48, 31
	s_lshl_b64 s[56:57], s[48:49], 20
	s_add_u32 s56, s9, s56
	s_addc_u32 s57, s11, s57
	s_and_b64 s[64:65], s[40:41], exec
	s_cselect_b32 s5, s57, s63
	s_cselect_b32 s29, s56, s62
	s_add_u32 s60, s60, 0x80080
	s_addc_u32 s61, s61, 0
	s_add_u32 s49, s62, 0x100
	v_mov_b64_e32 v[6:7], v[2:3]
	v_mov_b64_e32 v[18:19], v[2:3]
	v_mov_b64_e32 v[22:23], v[2:3]
	v_mov_b64_e32 v[34:35], v[2:3]
	v_mov_b64_e32 v[38:39], v[2:3]
	v_mov_b64_e32 v[50:51], v[2:3]
	v_mov_b64_e32 v[54:55], v[2:3]
	v_mov_b64_e32 v[10:11], v[2:3]
	v_mov_b64_e32 v[14:15], v[2:3]
	v_mov_b64_e32 v[26:27], v[2:3]
	v_mov_b64_e32 v[30:31], v[2:3]
	v_mov_b64_e32 v[42:43], v[2:3]
	v_mov_b64_e32 v[46:47], v[2:3]
	v_mov_b64_e32 v[58:59], v[2:3]
	v_mov_b64_e32 v[62:63], v[2:3]
	v_mov_b64_e32 v[66:67], v[2:3]
	v_mov_b64_e32 v[70:71], v[2:3]
	v_mov_b64_e32 v[82:83], v[2:3]
	v_mov_b64_e32 v[86:87], v[2:3]
	v_mov_b64_e32 v[98:99], v[2:3]
	v_mov_b64_e32 v[102:103], v[2:3]
	v_mov_b64_e32 v[114:115], v[2:3]
	v_mov_b64_e32 v[118:119], v[2:3]
	v_mov_b64_e32 v[74:75], v[2:3]
	v_mov_b64_e32 v[78:79], v[2:3]
	v_mov_b64_e32 v[90:91], v[2:3]
	v_mov_b64_e32 v[94:95], v[2:3]
	v_mov_b64_e32 v[106:107], v[2:3]
	v_mov_b64_e32 v[110:111], v[2:3]
	v_mov_b64_e32 v[122:123], v[2:3]
	v_mov_b64_e32 v[126:127], v[2:3]
	s_addc_u32 s53, s63, 0
	s_mov_b32 s78, -2
	v_mov_b64_e32 v[4:5], v[0:1]
	v_mov_b64_e32 v[16:17], v[0:1]
	v_mov_b64_e32 v[20:21], v[0:1]
	v_mov_b64_e32 v[32:33], v[0:1]
	v_mov_b64_e32 v[36:37], v[0:1]
	v_mov_b64_e32 v[48:49], v[0:1]
	v_mov_b64_e32 v[52:53], v[0:1]
	v_mov_b64_e32 v[8:9], v[0:1]
	v_mov_b64_e32 v[12:13], v[0:1]
	v_mov_b64_e32 v[24:25], v[0:1]
	v_mov_b64_e32 v[28:29], v[0:1]
	v_mov_b64_e32 v[40:41], v[0:1]
	v_mov_b64_e32 v[44:45], v[0:1]
	v_mov_b64_e32 v[56:57], v[0:1]
	v_mov_b64_e32 v[60:61], v[0:1]
	v_mov_b64_e32 v[64:65], v[0:1]
	v_mov_b64_e32 v[68:69], v[0:1]
	v_mov_b64_e32 v[80:81], v[0:1]
	v_mov_b64_e32 v[84:85], v[0:1]
	v_mov_b64_e32 v[96:97], v[0:1]
	v_mov_b64_e32 v[100:101], v[0:1]
	v_mov_b64_e32 v[112:113], v[0:1]
	v_mov_b64_e32 v[116:117], v[0:1]
	v_mov_b64_e32 v[72:73], v[0:1]
	v_mov_b64_e32 v[76:77], v[0:1]
	v_mov_b64_e32 v[88:89], v[0:1]
	v_mov_b64_e32 v[92:93], v[0:1]
	v_mov_b64_e32 v[104:105], v[0:1]
	v_mov_b64_e32 v[108:109], v[0:1]
	v_mov_b64_e32 v[120:121], v[0:1]
	v_mov_b64_e32 v[124:125], v[0:1]
	v_readlane_b32 vcc_lo, v253, 14
	s_nop 3
	s_cmp_eq_u32 vcc_lo, 0
	s_cbranch_scc1 .Lgprio_4
	s_setprio 1
.Lgprio_4:
.LBB0_469:
	s_add_u32 s36, s60, 0xfff80080
	s_addc_u32 s37, s61, -1
	s_add_i32 s79, 0, 0x10000
	s_cmp_eq_u32 s78, 28
	s_cselect_b32 s65, s22, s37
	s_cselect_b32 s64, s23, s36
	v_add_u32_e32 v138, s79, v141
	s_cselect_b32 s63, s5, s53
	s_cselect_b32 s62, s29, s49
	s_add_i32 s36, 0, 0x14000
	ds_read_b128 v[144:147], v138
	ds_read_b128 v[156:159], v138 offset:1024
	ds_read_b128 v[160:163], v138 offset:2048
	ds_read_b128 v[164:167], v138 offset:3072
	v_add_u32_e32 v138, s36, v141
	ds_read_b128 v[168:171], v138
	ds_read_b128 v[172:175], v138 offset:1024
	ds_read_b128 v[176:179], v138 offset:2048
	ds_read_b128 v[180:183], v138 offset:3072
	v_lshl_add_u64 v[138:139], s[60:61], 0, v[134:135]
	s_add_i32 m0, s38, 0xc000
	ds_read_b128 v[184:187], v143
	ds_read_b128 v[188:191], v143 offset:1024
	ds_read_b128 v[206:209], v143 offset:2048
	ds_read_b128 v[210:213], v143 offset:3072
	ds_read_b128 v[214:217], v143 offset:4096
	ds_read_b128 v[218:221], v143 offset:5120
	ds_read_b128 v[222:225], v143 offset:6144
	ds_read_b128 v[226:229], v143 offset:7168
	global_load_lds_dwordx4 v[138:139], off
	v_lshl_add_u64 v[138:139], s[60:61], 0, v[136:137]
	s_add_i32 m0, s38, 0xe000
	s_nop 0
	global_load_lds_dwordx4 v[138:139], off
	s_waitcnt vmcnt(8)
	s_waitcnt lgkmcnt(0)
	s_barrier
	s_waitcnt lgkmcnt(0)
	v_mfma_f32_16x16x32_bf16 v[124:127], v[144:147], v[184:187], v[124:127]
	v_mfma_f32_16x16x32_bf16 v[120:123], v[160:163], v[184:187], v[120:123]
	v_mfma_f32_16x16x32_bf16 v[108:111], v[144:147], v[206:209], v[108:111]
	v_mfma_f32_16x16x32_bf16 v[104:107], v[160:163], v[206:209], v[104:107]
	v_mfma_f32_16x16x32_bf16 v[92:95], v[144:147], v[214:217], v[92:95]
	v_mfma_f32_16x16x32_bf16 v[88:91], v[160:163], v[214:217], v[88:91]
	v_mfma_f32_16x16x32_bf16 v[76:79], v[144:147], v[222:225], v[76:79]
	v_mfma_f32_16x16x32_bf16 v[72:75], v[160:163], v[222:225], v[72:75]
	v_mfma_f32_16x16x32_bf16 v[124:127], v[156:159], v[188:191], v[124:127]
	v_mfma_f32_16x16x32_bf16 v[120:123], v[164:167], v[188:191], v[120:123]
	v_mfma_f32_16x16x32_bf16 v[108:111], v[156:159], v[210:213], v[108:111]
	v_mfma_f32_16x16x32_bf16 v[104:107], v[164:167], v[210:213], v[104:107]
	v_mfma_f32_16x16x32_bf16 v[92:95], v[156:159], v[218:221], v[92:95]
	v_mfma_f32_16x16x32_bf16 v[88:91], v[164:167], v[218:221], v[88:91]
	v_mfma_f32_16x16x32_bf16 v[76:79], v[156:159], v[226:229], v[76:79]
	v_mfma_f32_16x16x32_bf16 v[72:75], v[164:167], v[226:229], v[72:75]
	v_mfma_f32_16x16x32_bf16 v[116:119], v[168:171], v[184:187], v[116:119]
	v_mfma_f32_16x16x32_bf16 v[112:115], v[176:179], v[184:187], v[112:115]
	v_mfma_f32_16x16x32_bf16 v[100:103], v[168:171], v[206:209], v[100:103]
	v_mfma_f32_16x16x32_bf16 v[96:99], v[176:179], v[206:209], v[96:99]
	v_mfma_f32_16x16x32_bf16 v[84:87], v[168:171], v[214:217], v[84:87]
	v_mfma_f32_16x16x32_bf16 v[80:83], v[176:179], v[214:217], v[80:83]
	v_mfma_f32_16x16x32_bf16 v[68:71], v[168:171], v[222:225], v[68:71]
	v_mfma_f32_16x16x32_bf16 v[64:67], v[176:179], v[222:225], v[64:67]
	v_mfma_f32_16x16x32_bf16 v[116:119], v[172:175], v[188:191], v[116:119]
	v_mfma_f32_16x16x32_bf16 v[112:115], v[180:183], v[188:191], v[112:115]
	v_mfma_f32_16x16x32_bf16 v[100:103], v[172:175], v[210:213], v[100:103]
	v_mfma_f32_16x16x32_bf16 v[96:99], v[180:183], v[210:213], v[96:99]
	v_mfma_f32_16x16x32_bf16 v[84:87], v[172:175], v[218:221], v[84:87]
	v_mfma_f32_16x16x32_bf16 v[80:83], v[180:183], v[218:221], v[80:83]
	v_mfma_f32_16x16x32_bf16 v[68:71], v[172:175], v[226:229], v[68:71]
	v_mfma_f32_16x16x32_bf16 v[64:67], v[180:183], v[226:229], v[64:67]
	s_barrier
; #define PG8_STAGE(bufoff, gbase, voff) do { _Pragma("unroll") for (int _i = 0; _i < 2; ++_i) \
;         __builtin_amdgcn_global_load_lds((const unsigned*)((const char*)(gbase) + (voff)[_i]), (PG8_LAS unsigned*)(lds + (bufoff) + ldsw + _i * 8192), 16, 0, 0); } while (0)
; #define PG8_LDA(dst, b, h) do { _Pragma("unroll") for (int m = 0; m < 4; ++m) _Pragma("unroll") for (int k = 0; k < 2; ++k) dst[m][k] = *(const PG8_LAS bf16x8*)(lds + PG8_SA(b, h) + aoff + m * 2048 + k * 1024); } while (0)
; #define PG8_LDB(dst, b, h) do { _Pragma("unroll") for (int n = 0; n < 2; ++n) _Pragma("unroll") for (int k = 0; k < 2; ++k) dst[n][k] = *(const PG8_LAS bf16x8*)(lds + PG8_SB(b, h) + boff + n * 2048 + k * 1024); } while (0)
; #define PG8_MMA(ai, bj, At, Bt) do { __builtin_amdgcn_s_setprio(1); _Pragma("unroll") for (int m = 0; m < 4; ++m) _Pragma("unroll") for (int n = 0; n < 2; ++n) _Pragma("unroll") for (int k = 0; k < 2; ++k) \
;         acc[ai][bj][m][n] = __builtin_amdgcn_mfma_f32_16x16x32_bf16(Bt[n][k], At[m][k], acc[ai][bj][m][n], 0, 0, 0); __builtin_amdgcn_s_setprio(0); } while (0)
; #define PG8_WAIT_V(n) asm volatile("s_waitcnt vmcnt(" #n ")" ::: "memory")
; #define PG8_WAIT_L(n) asm volatile("s_waitcnt lgkmcnt(" #n ")" ::: "memory")
; #define PG8_BAR __builtin_amdgcn_s_barrier()
; #define PG8_SCHED __builtin_amdgcn_sched_barrier(0)
; template <class Epi, class Sched, bool ALIGN_EPI = false, bool SP2 = false>
; __device__ __forceinline__ void gemm_phase(PG8_LAS unsigned char* lds, const Gemm g, const Sched& S, const Epi& E, int wave_s) {
;     ...
;             PG8_LDA(At, 0, 1); PG8_STAGE(PG8_SB(0, 0), b2, voffB); PG8_STAGE(PG8_SB(0, 1), b2 + hstep, voffB); PG8_STAGE(PG8_SA(0, 0), a2, voffA);
;             PG8_WAIT_V(8); PG8_WAIT_L(0); PG8_BAR; PG8_MMA(1, 0, At, B0); PG8_MMA(1, 1, At, B1); PG8_BAR; PG8_SCHED;
;             PG8_LDB(B0, 1, 0); PG8_LDB(B1, 1, 1); PG8_SCHED; PG8_LDA(At, 1, 0); PG8_STAGE(PG8_SA(0, 1), a2 + hstep, voffA);
;             PG8_WAIT_V(8); PG8_WAIT_L(0); PG8_BAR; PG8_MMA(0, 0, At, B0); PG8_MMA(0, 1, At, B1); PG8_BAR; PG8_SCHED;
	s_add_i32 s37, s79, s25
	v_lshl_add_u64 v[138:139], s[62:63], 0, v[148:149]
	s_mov_b32 m0, s37
	ds_read_b128 v[184:187], v143 offset:16384
	ds_read_b128 v[188:191], v143 offset:17408
	ds_read_b128 v[206:209], v143 offset:18432
	ds_read_b128 v[210:213], v143 offset:19456
	ds_read_b128 v[214:217], v143 offset:20480
	ds_read_b128 v[218:221], v143 offset:21504
	ds_read_b128 v[222:225], v143 offset:22528
	ds_read_b128 v[226:229], v143 offset:23552
	global_load_lds_dwordx4 v[138:139], off
	s_add_i32 m0, s37, 0x2000
	s_add_u32 s84, s62, 0x80000
	v_lshl_add_u64 v[150:151], s[62:63], 0, v[128:129]
	s_addc_u32 s85, s63, 0
	s_add_i32 s36, s36, s25
	global_load_lds_dwordx4 v[150:151], off
	v_lshl_add_u64 v[152:153], s[84:85], 0, v[148:149]
	s_mov_b32 m0, s36
	v_lshl_add_u64 v[230:231], s[64:65], 0, v[130:131]
	global_load_lds_dwordx4 v[152:153], off
	v_lshl_add_u64 v[152:153], s[84:85], 0, v[128:129]
	s_add_i32 m0, s36, 0x2000
	s_nop 0
	global_load_lds_dwordx4 v[152:153], off
	v_lshl_add_u64 v[152:153], s[64:65], 0, v[132:133]
	s_mov_b32 m0, s38
	s_nop 0
	global_load_lds_dwordx4 v[152:153], off
	s_mov_b32 m0, s39
	s_nop 0
	global_load_lds_dwordx4 v[230:231], off
	s_waitcnt vmcnt(8)
	s_waitcnt lgkmcnt(0)
	s_barrier
	s_waitcnt lgkmcnt(0)
	v_mfma_f32_16x16x32_bf16 v[60:63], v[144:147], v[184:187], v[60:63]
	v_mfma_f32_16x16x32_bf16 v[56:59], v[160:163], v[184:187], v[56:59]
	v_mfma_f32_16x16x32_bf16 v[44:47], v[144:147], v[206:209], v[44:47]
	v_mfma_f32_16x16x32_bf16 v[40:43], v[160:163], v[206:209], v[40:43]
	v_mfma_f32_16x16x32_bf16 v[28:31], v[144:147], v[214:217], v[28:31]
	v_mfma_f32_16x16x32_bf16 v[24:27], v[160:163], v[214:217], v[24:27]
	v_mfma_f32_16x16x32_bf16 v[12:15], v[144:147], v[222:225], v[12:15]
	v_mfma_f32_16x16x32_bf16 v[8:11], v[160:163], v[222:225], v[8:11]
	v_mfma_f32_16x16x32_bf16 v[60:63], v[156:159], v[188:191], v[60:63]
	v_mfma_f32_16x16x32_bf16 v[56:59], v[164:167], v[188:191], v[56:59]
	v_mfma_f32_16x16x32_bf16 v[44:47], v[156:159], v[210:213], v[44:47]
	v_mfma_f32_16x16x32_bf16 v[40:43], v[164:167], v[210:213], v[40:43]
	v_mfma_f32_16x16x32_bf16 v[28:31], v[156:159], v[218:221], v[28:31]
	v_mfma_f32_16x16x32_bf16 v[24:27], v[164:167], v[218:221], v[24:27]
	v_mfma_f32_16x16x32_bf16 v[12:15], v[156:159], v[226:229], v[12:15]
	v_mfma_f32_16x16x32_bf16 v[8:11], v[164:167], v[226:229], v[8:11]
	v_mfma_f32_16x16x32_bf16 v[52:55], v[168:171], v[184:187], v[52:55]
	v_mfma_f32_16x16x32_bf16 v[48:51], v[176:179], v[184:187], v[48:51]
	v_mfma_f32_16x16x32_bf16 v[36:39], v[168:171], v[206:209], v[36:39]
	v_mfma_f32_16x16x32_bf16 v[32:35], v[176:179], v[206:209], v[32:35]
	v_mfma_f32_16x16x32_bf16 v[20:23], v[168:171], v[214:217], v[20:23]
	v_mfma_f32_16x16x32_bf16 v[16:19], v[176:179], v[214:217], v[16:19]
	v_mfma_f32_16x16x32_bf16 v[4:7], v[168:171], v[222:225], v[4:7]
	v_mfma_f32_16x16x32_bf16 v[0:3], v[176:179], v[222:225], v[0:3]
	v_mfma_f32_16x16x32_bf16 v[52:55], v[172:175], v[188:191], v[52:55]
	v_mfma_f32_16x16x32_bf16 v[48:51], v[180:183], v[188:191], v[48:51]
	v_mfma_f32_16x16x32_bf16 v[36:39], v[172:175], v[210:213], v[36:39]
	v_mfma_f32_16x16x32_bf16 v[32:35], v[180:183], v[210:213], v[32:35]
	v_mfma_f32_16x16x32_bf16 v[20:23], v[172:175], v[218:221], v[20:23]
	v_mfma_f32_16x16x32_bf16 v[16:19], v[180:183], v[218:221], v[16:19]
	v_mfma_f32_16x16x32_bf16 v[4:7], v[172:175], v[226:229], v[4:7]
	v_mfma_f32_16x16x32_bf16 v[0:3], v[180:183], v[226:229], v[0:3]
	s_barrier
	s_add_i32 s36, 0, 0x18000
	s_add_i32 s37, 0, 0x1c000
	v_add_u32_e32 v164, s36, v141
	v_add_u32_e32 v180, s37, v141
	ds_read_b128 v[144:147], v164
	ds_read_b128 v[156:159], v164 offset:1024
	ds_read_b128 v[160:163], v164 offset:2048
	ds_read_b128 v[164:167], v164 offset:3072
	ds_read_b128 v[168:171], v180
	ds_read_b128 v[172:175], v180 offset:1024
	ds_read_b128 v[176:179], v180 offset:2048
	ds_read_b128 v[180:183], v180 offset:3072
	s_add_u32 s64, s64, 0x80000
	s_addc_u32 s65, s65, 0
	s_mov_b32 m0, s59
	v_lshl_add_u64 v[232:233], s[64:65], 0, v[132:133]
	ds_read_b128 v[184:187], v143 offset:32768
	ds_read_b128 v[188:191], v143 offset:33792
	ds_read_b128 v[206:209], v143 offset:34816
	ds_read_b128 v[210:213], v143 offset:35840
	ds_read_b128 v[214:217], v143 offset:36864
	ds_read_b128 v[218:221], v143 offset:37888
	ds_read_b128 v[222:225], v143 offset:38912
	ds_read_b128 v[226:229], v143 offset:39936
	global_load_lds_dwordx4 v[232:233], off
	v_lshl_add_u64 v[232:233], s[64:65], 0, v[130:131]
	s_mov_b32 m0, s67
	s_nop 0
	global_load_lds_dwordx4 v[232:233], off
	s_waitcnt vmcnt(8)
	s_waitcnt lgkmcnt(0)
	s_barrier
; #define PG8_STAGE(bufoff, gbase, voff) do { _Pragma("unroll") for (int _i = 0; _i < 2; ++_i) \
;         __builtin_amdgcn_global_load_lds((const unsigned*)((const char*)(gbase) + (voff)[_i]), (PG8_LAS unsigned*)(lds + (bufoff) + ldsw + _i * 8192), 16, 0, 0); } while (0)
; #define PG8_LDA(dst, b, h) do { _Pragma("unroll") for (int m = 0; m < 4; ++m) _Pragma("unroll") for (int k = 0; k < 2; ++k) dst[m][k] = *(const PG8_LAS bf16x8*)(lds + PG8_SA(b, h) + aoff + m * 2048 + k * 1024); } while (0)
; #define PG8_MMA(ai, bj, At, Bt) do { __builtin_amdgcn_s_setprio(1); _Pragma("unroll") for (int m = 0; m < 4; ++m) _Pragma("unroll") for (int n = 0; n < 2; ++n) _Pragma("unroll") for (int k = 0; k < 2; ++k) \
;         acc[ai][bj][m][n] = __builtin_amdgcn_mfma_f32_16x16x32_bf16(Bt[n][k], At[m][k], acc[ai][bj][m][n], 0, 0, 0); __builtin_amdgcn_s_setprio(0); } while (0)
; #define PG8_WAIT_V(n) asm volatile("s_waitcnt vmcnt(" #n ")" ::: "memory")
; #define PG8_WAIT_L(n) asm volatile("s_waitcnt lgkmcnt(" #n ")" ::: "memory")
; #define PG8_BAR __builtin_amdgcn_s_barrier()
; #define PG8_SCHED __builtin_amdgcn_sched_barrier(0)
; template <class Epi, class Sched, bool ALIGN_EPI = false, bool SP2 = false>
; __device__ __forceinline__ void gemm_phase(PG8_LAS unsigned char* lds, const Gemm g, const Sched& S, const Epi& E, int wave_s) {
;     ...
;             PG8_WAIT_V(8); PG8_WAIT_L(0); PG8_BAR; PG8_MMA(0, 0, At, B0); PG8_MMA(0, 1, At, B1); PG8_BAR; PG8_SCHED;
;             PG8_LDA(At, 1, 1); PG8_STAGE(PG8_SB(1, 0), b3, voffB); PG8_STAGE(PG8_SB(1, 1), b3 + hstep, voffB); PG8_STAGE(PG8_SA(1, 0), a3, voffA);
;             PG8_WAIT_V(8); PG8_WAIT_L(0); PG8_BAR; PG8_MMA(1, 0, At, B0); PG8_MMA(1, 1, At, B1); PG8_BAR; PG8_SCHED;
	s_waitcnt lgkmcnt(0)
	v_mfma_f32_16x16x32_bf16 v[124:127], v[144:147], v[184:187], v[124:127]
	v_mfma_f32_16x16x32_bf16 v[120:123], v[160:163], v[184:187], v[120:123]
	v_mfma_f32_16x16x32_bf16 v[108:111], v[144:147], v[206:209], v[108:111]
	v_mfma_f32_16x16x32_bf16 v[104:107], v[160:163], v[206:209], v[104:107]
	v_mfma_f32_16x16x32_bf16 v[92:95], v[144:147], v[214:217], v[92:95]
	v_mfma_f32_16x16x32_bf16 v[88:91], v[160:163], v[214:217], v[88:91]
	v_mfma_f32_16x16x32_bf16 v[76:79], v[144:147], v[222:225], v[76:79]
	v_mfma_f32_16x16x32_bf16 v[72:75], v[160:163], v[222:225], v[72:75]
	v_mfma_f32_16x16x32_bf16 v[124:127], v[156:159], v[188:191], v[124:127]
	v_mfma_f32_16x16x32_bf16 v[120:123], v[164:167], v[188:191], v[120:123]
	v_mfma_f32_16x16x32_bf16 v[108:111], v[156:159], v[210:213], v[108:111]
	v_mfma_f32_16x16x32_bf16 v[104:107], v[164:167], v[210:213], v[104:107]
	v_mfma_f32_16x16x32_bf16 v[92:95], v[156:159], v[218:221], v[92:95]
	v_mfma_f32_16x16x32_bf16 v[88:91], v[164:167], v[218:221], v[88:91]
	v_mfma_f32_16x16x32_bf16 v[76:79], v[156:159], v[226:229], v[76:79]
	v_mfma_f32_16x16x32_bf16 v[72:75], v[164:167], v[226:229], v[72:75]
	v_mfma_f32_16x16x32_bf16 v[116:119], v[168:171], v[184:187], v[116:119]
	v_mfma_f32_16x16x32_bf16 v[112:115], v[176:179], v[184:187], v[112:115]
	v_mfma_f32_16x16x32_bf16 v[100:103], v[168:171], v[206:209], v[100:103]
	v_mfma_f32_16x16x32_bf16 v[96:99], v[176:179], v[206:209], v[96:99]
	v_mfma_f32_16x16x32_bf16 v[84:87], v[168:171], v[214:217], v[84:87]
	v_mfma_f32_16x16x32_bf16 v[80:83], v[176:179], v[214:217], v[80:83]
	v_mfma_f32_16x16x32_bf16 v[68:71], v[168:171], v[222:225], v[68:71]
	v_mfma_f32_16x16x32_bf16 v[64:67], v[176:179], v[222:225], v[64:67]
	v_mfma_f32_16x16x32_bf16 v[116:119], v[172:175], v[188:191], v[116:119]
	v_mfma_f32_16x16x32_bf16 v[112:115], v[180:183], v[188:191], v[112:115]
	v_mfma_f32_16x16x32_bf16 v[100:103], v[172:175], v[210:213], v[100:103]
	v_mfma_f32_16x16x32_bf16 v[96:99], v[180:183], v[210:213], v[96:99]
	v_mfma_f32_16x16x32_bf16 v[84:87], v[172:175], v[218:221], v[84:87]
	v_mfma_f32_16x16x32_bf16 v[80:83], v[180:183], v[218:221], v[80:83]
	v_mfma_f32_16x16x32_bf16 v[68:71], v[172:175], v[226:229], v[68:71]
	v_mfma_f32_16x16x32_bf16 v[64:67], v[180:183], v[226:229], v[64:67]
	s_barrier
	s_add_i32 s36, s36, s25
	v_lshl_add_u64 v[138:139], v[138:139], 0, s[34:35]
	s_mov_b32 m0, s36
	ds_read_b128 v[184:187], v143 offset:49152
	ds_read_b128 v[188:191], v143 offset:50176
	ds_read_b128 v[206:209], v143 offset:51200
	ds_read_b128 v[210:213], v143 offset:52224
	ds_read_b128 v[214:217], v143 offset:53248
	ds_read_b128 v[218:221], v143 offset:54272
	ds_read_b128 v[222:225], v143 offset:55296
	ds_read_b128 v[226:229], v143 offset:56320
	global_load_lds_dwordx4 v[138:139], off
	s_add_i32 m0, s36, 0x2000
	s_add_u32 s62, s62, 0x80080
	v_lshl_add_u64 v[138:139], v[150:151], 0, s[34:35]
	s_addc_u32 s63, s63, 0
	s_add_i32 s36, s37, s25
	global_load_lds_dwordx4 v[138:139], off
	v_lshl_add_u64 v[138:139], s[62:63], 0, v[148:149]
	s_mov_b32 m0, s36
	s_nop 0
	global_load_lds_dwordx4 v[138:139], off
	v_lshl_add_u64 v[138:139], s[62:63], 0, v[128:129]
	s_add_i32 m0, s36, 0x2000
	s_nop 0
	global_load_lds_dwordx4 v[138:139], off
	v_lshl_add_u64 v[138:139], v[152:153], 0, s[34:35]
	s_mov_b32 m0, s75
	s_nop 0
	global_load_lds_dwordx4 v[138:139], off
	v_lshl_add_u64 v[138:139], v[230:231], 0, s[34:35]
	s_mov_b32 m0, s76
	s_nop 0
	global_load_lds_dwordx4 v[138:139], off
	s_waitcnt vmcnt(8)
	s_waitcnt lgkmcnt(0)
	s_barrier
	s_waitcnt lgkmcnt(0)
	v_mfma_f32_16x16x32_bf16 v[60:63], v[144:147], v[184:187], v[60:63]
	v_mfma_f32_16x16x32_bf16 v[56:59], v[160:163], v[184:187], v[56:59]
	v_mfma_f32_16x16x32_bf16 v[44:47], v[144:147], v[206:209], v[44:47]
	v_mfma_f32_16x16x32_bf16 v[40:43], v[160:163], v[206:209], v[40:43]
	v_mfma_f32_16x16x32_bf16 v[28:31], v[144:147], v[214:217], v[28:31]
	v_mfma_f32_16x16x32_bf16 v[24:27], v[160:163], v[214:217], v[24:27]
	v_mfma_f32_16x16x32_bf16 v[12:15], v[144:147], v[222:225], v[12:15]
	v_mfma_f32_16x16x32_bf16 v[8:11], v[160:163], v[222:225], v[8:11]
	v_mfma_f32_16x16x32_bf16 v[60:63], v[156:159], v[188:191], v[60:63]
	v_mfma_f32_16x16x32_bf16 v[56:59], v[164:167], v[188:191], v[56:59]
	v_mfma_f32_16x16x32_bf16 v[44:47], v[156:159], v[210:213], v[44:47]
	v_mfma_f32_16x16x32_bf16 v[40:43], v[164:167], v[210:213], v[40:43]
	v_mfma_f32_16x16x32_bf16 v[28:31], v[156:159], v[218:221], v[28:31]
	v_mfma_f32_16x16x32_bf16 v[24:27], v[164:167], v[218:221], v[24:27]
	v_mfma_f32_16x16x32_bf16 v[12:15], v[156:159], v[226:229], v[12:15]
	v_mfma_f32_16x16x32_bf16 v[8:11], v[164:167], v[226:229], v[8:11]
	v_mfma_f32_16x16x32_bf16 v[52:55], v[168:171], v[184:187], v[52:55]
	v_mfma_f32_16x16x32_bf16 v[48:51], v[176:179], v[184:187], v[48:51]
	v_mfma_f32_16x16x32_bf16 v[36:39], v[168:171], v[206:209], v[36:39]
	v_mfma_f32_16x16x32_bf16 v[32:35], v[176:179], v[206:209], v[32:35]
	v_mfma_f32_16x16x32_bf16 v[20:23], v[168:171], v[214:217], v[20:23]
	v_mfma_f32_16x16x32_bf16 v[16:19], v[176:179], v[214:217], v[16:19]
	v_mfma_f32_16x16x32_bf16 v[4:7], v[168:171], v[222:225], v[4:7]
	v_mfma_f32_16x16x32_bf16 v[0:3], v[176:179], v[222:225], v[0:3]
	v_mfma_f32_16x16x32_bf16 v[52:55], v[172:175], v[188:191], v[52:55]
	v_mfma_f32_16x16x32_bf16 v[48:51], v[180:183], v[188:191], v[48:51]
	v_mfma_f32_16x16x32_bf16 v[36:39], v[172:175], v[210:213], v[36:39]
	v_mfma_f32_16x16x32_bf16 v[32:35], v[180:183], v[210:213], v[32:35]
	v_mfma_f32_16x16x32_bf16 v[20:23], v[172:175], v[218:221], v[20:23]
	v_mfma_f32_16x16x32_bf16 v[16:19], v[180:183], v[218:221], v[16:19]
	v_mfma_f32_16x16x32_bf16 v[4:7], v[172:175], v[226:229], v[4:7]
	v_mfma_f32_16x16x32_bf16 v[0:3], v[180:183], v[226:229], v[0:3]
	s_barrier
	s_add_i32 s78, s78, 2
	s_add_u32 s60, s60, 0x100
	s_addc_u32 s61, s61, 0
	s_add_u32 s49, s49, 0x100
	s_addc_u32 s53, s53, 0
	s_cmp_gt_u32 s78, 29
	s_cbranch_scc0 .LBB0_469
	s_setprio 0
	s_and_b64 vcc, exec, s[46:47]
	s_cbranch_vccz .LBB0_472
	s_barrier
